# GEMM loops: setprio moved across barriers, redundant lgkmcnt/setprio pairs removed
# baseline (speedup 1.0000x reference)
; #define PG8_STAGE(bufoff, gbase, voff) do { _Pragma("unroll") for (int _i = 0; _i < 2; ++_i) \
;         __builtin_amdgcn_global_load_lds((const unsigned*)((const char*)(gbase) + (voff)[_i]), (LAS unsigned*)(lds + (bufoff) + ldsw + _i * 8192), 16, 0, 0); } while (0)
; #define PG8_LDA(dst, b, h) do { _Pragma("unroll") for (int m = 0; m < 4; ++m) _Pragma("unroll") for (int k = 0; k < 2; ++k) dst[m][k] = *(const LAS bf16x8*)(lds + PG8_SA(b, h) + aoff + m * 2048 + k * 1024); } while (0)
; #define PG8_LDB(dst, b, h) do { _Pragma("unroll") for (int n = 0; n < 2; ++n) _Pragma("unroll") for (int k = 0; k < 2; ++k) dst[n][k] = *(const LAS bf16x8*)(lds + PG8_SB(b, h) + boff + n * 2048 + k * 1024); } while (0)
; #define PG8_MMA(ai, bj, At, Bt) do { __builtin_amdgcn_s_setprio(1); _Pragma("unroll") for (int m = 0; m < 4; ++m) _Pragma("unroll") for (int n = 0; n < 2; ++n) _Pragma("unroll") for (int k = 0; k < 2; ++k) \
;         acc[ai][bj][m][n] = __builtin_amdgcn_mfma_f32_16x16x32_bf16(Bt[n][k], At[m][k], acc[ai][bj][m][n], 0, 0, 0); __builtin_amdgcn_s_setprio(0); } while (0)
; #define PG8_WAIT_V(n) asm volatile("s_waitcnt vmcnt(" #n ")" ::: "memory")
; #define PG8_WAIT_L(n) asm volatile("s_waitcnt lgkmcnt(" #n ")" ::: "memory")
; #define PG8_BAR __builtin_amdgcn_s_barrier()
; #define PG8_SCHED __builtin_amdgcn_sched_barrier(0)
; template <class Epi, class Sched, bool ALIGN_EPI = true, bool SP2 = true>
; __device__ __forceinline__ void gemm_phase(LAS unsigned char* lds, const Gemm g, const Sched& S, const Epi& E) {
;     ...
;         for (int t = 0; t < nt; t += 2) {
;             const bool last = (t == nt - 2);
;             const char* a1 = cA + (size_t)(t + 1) * kstep;
;             const char* a2 = last ? nA : cA + (size_t)(t + 2) * kstep; const char* b2 = last ? nB : cB + (size_t)(t + 2) * kstep;
;             const char* a3 = a2 + kstep; const char* b3 = b2 + kstep;
;             if constexpr (SP2) {
;             PG8_LDB(B0, 0, 0); PG8_LDB(B1, 0, 1); PG8_SCHED; PG8_LDA(At, 0, 0); PG8_STAGE(PG8_SA(1, 1), a1 + hstep, voffA);
;             PG8_WAIT_V(8); PG8_WAIT_L(0); PG8_BAR; PG8_MMA(0, 0, At, B0); PG8_MMA(0, 1, At, B1); PG8_BAR; PG8_SCHED;
;             PG8_LDA(At, 0, 1); PG8_STAGE(PG8_SB(0, 0), b2, voffB); PG8_STAGE(PG8_SB(0, 1), b2 + hstep, voffB); PG8_STAGE(PG8_SA(0, 0), a2, voffA);
.LBB0_94:
	s_add_u32 s8, s6, 0xfff80080
	s_addc_u32 s9, s7, -1
	s_add_i32 s58, 0, 0x10000
	s_cmp_eq_u32 s72, 28
	s_cselect_b32 s23, s17, s9
	s_cselect_b32 s22, s56, s8
	v_add_u32_e32 v148, s58, v153
	s_cselect_b32 s9, s15, s71
	s_cselect_b32 s8, s57, s70
	s_add_i32 s73, 0, 0x14000
	ds_read_b128 v[140:143], v148
	ds_read_b128 v[144:147], v148 offset:1024
	ds_read_b128 v[160:163], v148 offset:2048
	ds_read_b128 v[164:167], v148 offset:3072
	v_add_u32_e32 v148, s73, v153
	ds_read_b128 v[168:171], v148
	ds_read_b128 v[172:175], v148 offset:1024
	ds_read_b128 v[176:179], v148 offset:2048
	ds_read_b128 v[194:197], v148 offset:3072
	v_lshl_add_u64 v[148:149], s[6:7], 0, v[136:137]
	s_add_i32 m0, s25, 0xc000
	ds_read_b128 v[198:201], v159
	ds_read_b128 v[202:205], v159 offset:1024
	ds_read_b128 v[206:209], v159 offset:2048
	ds_read_b128 v[210:213], v159 offset:3072
	ds_read_b128 v[234:237], v159 offset:4096
	ds_read_b128 v[238:241], v159 offset:5120
	ds_read_b128 v[242:245], v159 offset:6144
	ds_read_b128 v[246:249], v159 offset:7168
	global_load_lds_dwordx4 v[148:149], off
	v_lshl_add_u64 v[148:149], s[6:7], 0, v[138:139]
	s_add_i32 m0, s25, 0xe000
	s_nop 0
	global_load_lds_dwordx4 v[148:149], off
	s_waitcnt vmcnt(8)
	s_waitcnt lgkmcnt(0)
	s_setprio 1
	s_barrier
	v_mfma_f32_16x16x32_bf16 v[126:129], v[140:143], v[198:201], v[126:129]
	v_mfma_f32_16x16x32_bf16 v[118:121], v[160:163], v[198:201], v[118:121]
	v_mfma_f32_16x16x32_bf16 v[110:113], v[140:143], v[206:209], v[110:113]
	v_mfma_f32_16x16x32_bf16 v[102:105], v[160:163], v[206:209], v[102:105]
	v_mfma_f32_16x16x32_bf16 v[94:97], v[140:143], v[234:237], v[94:97]
	v_mfma_f32_16x16x32_bf16 v[86:89], v[160:163], v[234:237], v[86:89]
	v_mfma_f32_16x16x32_bf16 v[78:81], v[140:143], v[242:245], v[78:81]
	v_mfma_f32_16x16x32_bf16 v[70:73], v[160:163], v[242:245], v[70:73]
	v_mfma_f32_16x16x32_bf16 v[126:129], v[144:147], v[202:205], v[126:129]
	v_mfma_f32_16x16x32_bf16 v[118:121], v[164:167], v[202:205], v[118:121]
	v_mfma_f32_16x16x32_bf16 v[110:113], v[144:147], v[210:213], v[110:113]
	v_mfma_f32_16x16x32_bf16 v[102:105], v[164:167], v[210:213], v[102:105]
	v_mfma_f32_16x16x32_bf16 v[94:97], v[144:147], v[238:241], v[94:97]
	v_mfma_f32_16x16x32_bf16 v[86:89], v[164:167], v[238:241], v[86:89]
	v_mfma_f32_16x16x32_bf16 v[78:81], v[144:147], v[246:249], v[78:81]
	v_mfma_f32_16x16x32_bf16 v[70:73], v[164:167], v[246:249], v[70:73]
	v_mfma_f32_16x16x32_bf16 v[122:125], v[168:171], v[198:201], v[122:125]
	v_mfma_f32_16x16x32_bf16 v[114:117], v[176:179], v[198:201], v[114:117]
	v_mfma_f32_16x16x32_bf16 v[106:109], v[168:171], v[206:209], v[106:109]
	v_mfma_f32_16x16x32_bf16 v[98:101], v[176:179], v[206:209], v[98:101]
	v_mfma_f32_16x16x32_bf16 v[90:93], v[168:171], v[234:237], v[90:93]
	v_mfma_f32_16x16x32_bf16 v[82:85], v[176:179], v[234:237], v[82:85]
	v_mfma_f32_16x16x32_bf16 v[74:77], v[168:171], v[242:245], v[74:77]
	v_mfma_f32_16x16x32_bf16 v[66:69], v[176:179], v[242:245], v[66:69]
	v_mfma_f32_16x16x32_bf16 v[122:125], v[172:175], v[202:205], v[122:125]
	v_mfma_f32_16x16x32_bf16 v[114:117], v[194:197], v[202:205], v[114:117]
	v_mfma_f32_16x16x32_bf16 v[106:109], v[172:175], v[210:213], v[106:109]
	v_mfma_f32_16x16x32_bf16 v[98:101], v[194:197], v[210:213], v[98:101]
	v_mfma_f32_16x16x32_bf16 v[90:93], v[172:175], v[238:241], v[90:93]
	v_mfma_f32_16x16x32_bf16 v[82:85], v[194:197], v[238:241], v[82:85]
	v_mfma_f32_16x16x32_bf16 v[74:77], v[172:175], v[246:249], v[74:77]
	v_mfma_f32_16x16x32_bf16 v[66:69], v[194:197], v[246:249], v[66:69]
	s_barrier
	s_setprio 0
	s_add_i32 s58, s58, s24
	v_lshl_add_u64 v[148:149], s[8:9], 0, v[0:1]
	s_mov_b32 m0, s58
	ds_read_b128 v[198:201], v159 offset:16384
	ds_read_b128 v[202:205], v159 offset:17408
	ds_read_b128 v[206:209], v159 offset:18432
	ds_read_b128 v[210:213], v159 offset:19456
	ds_read_b128 v[234:237], v159 offset:20480
	ds_read_b128 v[238:241], v159 offset:21504
	ds_read_b128 v[242:245], v159 offset:22528
	ds_read_b128 v[246:249], v159 offset:23552
	global_load_lds_dwordx4 v[148:149], off
	s_add_i32 m0, s58, 0x2000
	s_add_u32 s58, s8, 0x80000
	v_lshl_add_u64 v[156:157], s[8:9], 0, v[130:131]
	s_addc_u32 s59, s9, 0
	s_add_i32 s73, s73, s24
	global_load_lds_dwordx4 v[156:157], off
	v_lshl_add_u64 v[214:215], s[58:59], 0, v[0:1]
	s_mov_b32 m0, s73
	v_lshl_add_u64 v[250:251], s[22:23], 0, v[132:133]
	global_load_lds_dwordx4 v[214:215], off
	v_lshl_add_u64 v[214:215], s[58:59], 0, v[130:131]
	s_add_i32 m0, s73, 0x2000
	s_nop 0
	global_load_lds_dwordx4 v[214:215], off
	v_lshl_add_u64 v[214:215], s[22:23], 0, v[134:135]
	s_mov_b32 m0, s25
	s_nop 0
	global_load_lds_dwordx4 v[214:215], off
	s_mov_b32 m0, s26
	s_nop 0
	global_load_lds_dwordx4 v[250:251], off
	s_waitcnt vmcnt(8)
	s_waitcnt lgkmcnt(0)
	s_setprio 1
	s_barrier
; #define PG8_STAGE(bufoff, gbase, voff) do { _Pragma("unroll") for (int _i = 0; _i < 2; ++_i) \
;         __builtin_amdgcn_global_load_lds((const unsigned*)((const char*)(gbase) + (voff)[_i]), (LAS unsigned*)(lds + (bufoff) + ldsw + _i * 8192), 16, 0, 0); } while (0)
; #define PG8_LDA(dst, b, h) do { _Pragma("unroll") for (int m = 0; m < 4; ++m) _Pragma("unroll") for (int k = 0; k < 2; ++k) dst[m][k] = *(const LAS bf16x8*)(lds + PG8_SA(b, h) + aoff + m * 2048 + k * 1024); } while (0)
; #define PG8_LDB(dst, b, h) do { _Pragma("unroll") for (int n = 0; n < 2; ++n) _Pragma("unroll") for (int k = 0; k < 2; ++k) dst[n][k] = *(const LAS bf16x8*)(lds + PG8_SB(b, h) + boff + n * 2048 + k * 1024); } while (0)
; #define PG8_MMA(ai, bj, At, Bt) do { __builtin_amdgcn_s_setprio(1); _Pragma("unroll") for (int m = 0; m < 4; ++m) _Pragma("unroll") for (int n = 0; n < 2; ++n) _Pragma("unroll") for (int k = 0; k < 2; ++k) \
;         acc[ai][bj][m][n] = __builtin_amdgcn_mfma_f32_16x16x32_bf16(Bt[n][k], At[m][k], acc[ai][bj][m][n], 0, 0, 0); __builtin_amdgcn_s_setprio(0); } while (0)
; #define PG8_WAIT_V(n) asm volatile("s_waitcnt vmcnt(" #n ")" ::: "memory")
; #define PG8_WAIT_L(n) asm volatile("s_waitcnt lgkmcnt(" #n ")" ::: "memory")
; #define PG8_BAR __builtin_amdgcn_s_barrier()
; #define PG8_SCHED __builtin_amdgcn_sched_barrier(0)
; template <class Epi, class Sched, bool ALIGN_EPI = true, bool SP2 = true>
; __device__ __forceinline__ void gemm_phase(LAS unsigned char* lds, const Gemm g, const Sched& S, const Epi& E) {
;     ...
;             PG8_WAIT_V(8); PG8_WAIT_L(0); PG8_BAR; PG8_MMA(1, 0, At, B0); PG8_MMA(1, 1, At, B1); PG8_BAR; PG8_SCHED;
;             PG8_LDB(B0, 1, 0); PG8_LDB(B1, 1, 1); PG8_SCHED; PG8_LDA(At, 1, 0); PG8_STAGE(PG8_SA(0, 1), a2 + hstep, voffA);
;             PG8_WAIT_V(8); PG8_WAIT_L(0); PG8_BAR; PG8_MMA(0, 0, At, B0); PG8_MMA(0, 1, At, B1); PG8_BAR; PG8_SCHED;
	v_mfma_f32_16x16x32_bf16 v[62:65], v[140:143], v[198:201], v[62:65]
	v_mfma_f32_16x16x32_bf16 v[54:57], v[160:163], v[198:201], v[54:57]
	v_mfma_f32_16x16x32_bf16 v[46:49], v[140:143], v[206:209], v[46:49]
	v_mfma_f32_16x16x32_bf16 v[38:41], v[160:163], v[206:209], v[38:41]
	v_mfma_f32_16x16x32_bf16 v[30:33], v[140:143], v[234:237], v[30:33]
	v_mfma_f32_16x16x32_bf16 v[22:25], v[160:163], v[234:237], v[22:25]
	v_mfma_f32_16x16x32_bf16 v[14:17], v[140:143], v[242:245], v[14:17]
	v_mfma_f32_16x16x32_bf16 v[6:9], v[160:163], v[242:245], v[6:9]
	v_mfma_f32_16x16x32_bf16 v[62:65], v[144:147], v[202:205], v[62:65]
	v_mfma_f32_16x16x32_bf16 v[54:57], v[164:167], v[202:205], v[54:57]
	v_mfma_f32_16x16x32_bf16 v[46:49], v[144:147], v[210:213], v[46:49]
	v_mfma_f32_16x16x32_bf16 v[38:41], v[164:167], v[210:213], v[38:41]
	v_mfma_f32_16x16x32_bf16 v[30:33], v[144:147], v[238:241], v[30:33]
	v_mfma_f32_16x16x32_bf16 v[22:25], v[164:167], v[238:241], v[22:25]
	v_mfma_f32_16x16x32_bf16 v[14:17], v[144:147], v[246:249], v[14:17]
	v_mfma_f32_16x16x32_bf16 v[6:9], v[164:167], v[246:249], v[6:9]
	v_mfma_f32_16x16x32_bf16 v[58:61], v[168:171], v[198:201], v[58:61]
	v_mfma_f32_16x16x32_bf16 v[50:53], v[176:179], v[198:201], v[50:53]
	v_mfma_f32_16x16x32_bf16 v[42:45], v[168:171], v[206:209], v[42:45]
	v_mfma_f32_16x16x32_bf16 v[34:37], v[176:179], v[206:209], v[34:37]
	v_mfma_f32_16x16x32_bf16 v[26:29], v[168:171], v[234:237], v[26:29]
	v_mfma_f32_16x16x32_bf16 v[18:21], v[176:179], v[234:237], v[18:21]
	v_mfma_f32_16x16x32_bf16 v[10:13], v[168:171], v[242:245], v[10:13]
	v_mfma_f32_16x16x32_bf16 v[2:5], v[176:179], v[242:245], v[2:5]
	v_mfma_f32_16x16x32_bf16 v[58:61], v[172:175], v[202:205], v[58:61]
	v_mfma_f32_16x16x32_bf16 v[50:53], v[194:197], v[202:205], v[50:53]
	v_mfma_f32_16x16x32_bf16 v[42:45], v[172:175], v[210:213], v[42:45]
	v_mfma_f32_16x16x32_bf16 v[34:37], v[194:197], v[210:213], v[34:37]
	v_mfma_f32_16x16x32_bf16 v[26:29], v[172:175], v[238:241], v[26:29]
	v_mfma_f32_16x16x32_bf16 v[18:21], v[194:197], v[238:241], v[18:21]
	v_mfma_f32_16x16x32_bf16 v[10:13], v[172:175], v[246:249], v[10:13]
	v_mfma_f32_16x16x32_bf16 v[2:5], v[194:197], v[246:249], v[2:5]
	s_barrier
	s_setprio 0
	s_add_i32 s58, 0, 0x18000
	v_add_u32_e32 v150, s58, v153
	s_add_i32 s59, 0, 0x1c000
	ds_read_b128 v[140:143], v150
	ds_read_b128 v[144:147], v150 offset:1024
	ds_read_b128 v[160:163], v150 offset:2048
	ds_read_b128 v[164:167], v150 offset:3072
	v_add_u32_e32 v150, s59, v153
	ds_read_b128 v[168:171], v150
	ds_read_b128 v[172:175], v150 offset:1024
	ds_read_b128 v[176:179], v150 offset:2048
	ds_read_b128 v[194:197], v150 offset:3072
	s_add_u32 s22, s22, 0x80000
	s_addc_u32 s23, s23, 0
	s_mov_b32 m0, s27
	v_lshl_add_u64 v[224:225], s[22:23], 0, v[134:135]
	ds_read_b128 v[198:201], v159 offset:32768
	ds_read_b128 v[202:205], v159 offset:33792
	ds_read_b128 v[206:209], v159 offset:34816
	ds_read_b128 v[210:213], v159 offset:35840
	ds_read_b128 v[234:237], v159 offset:36864
	ds_read_b128 v[238:241], v159 offset:37888
	ds_read_b128 v[242:245], v159 offset:38912
	ds_read_b128 v[246:249], v159 offset:39936
	global_load_lds_dwordx4 v[224:225], off
	v_lshl_add_u64 v[224:225], s[22:23], 0, v[132:133]
	s_mov_b32 m0, s28
	s_nop 0
	global_load_lds_dwordx4 v[224:225], off
	s_waitcnt vmcnt(8)
	s_waitcnt lgkmcnt(0)
	s_setprio 1
	s_barrier
	v_mfma_f32_16x16x32_bf16 v[126:129], v[140:143], v[198:201], v[126:129]
	v_mfma_f32_16x16x32_bf16 v[118:121], v[160:163], v[198:201], v[118:121]
	v_mfma_f32_16x16x32_bf16 v[110:113], v[140:143], v[206:209], v[110:113]
	v_mfma_f32_16x16x32_bf16 v[102:105], v[160:163], v[206:209], v[102:105]
	v_mfma_f32_16x16x32_bf16 v[94:97], v[140:143], v[234:237], v[94:97]
	v_mfma_f32_16x16x32_bf16 v[86:89], v[160:163], v[234:237], v[86:89]
	v_mfma_f32_16x16x32_bf16 v[78:81], v[140:143], v[242:245], v[78:81]
	v_mfma_f32_16x16x32_bf16 v[70:73], v[160:163], v[242:245], v[70:73]
	v_mfma_f32_16x16x32_bf16 v[126:129], v[144:147], v[202:205], v[126:129]
	v_mfma_f32_16x16x32_bf16 v[118:121], v[164:167], v[202:205], v[118:121]
	v_mfma_f32_16x16x32_bf16 v[110:113], v[144:147], v[210:213], v[110:113]
	v_mfma_f32_16x16x32_bf16 v[102:105], v[164:167], v[210:213], v[102:105]
	v_mfma_f32_16x16x32_bf16 v[94:97], v[144:147], v[238:241], v[94:97]
	v_mfma_f32_16x16x32_bf16 v[86:89], v[164:167], v[238:241], v[86:89]
	v_mfma_f32_16x16x32_bf16 v[78:81], v[144:147], v[246:249], v[78:81]
	v_mfma_f32_16x16x32_bf16 v[70:73], v[164:167], v[246:249], v[70:73]
	v_mfma_f32_16x16x32_bf16 v[122:125], v[168:171], v[198:201], v[122:125]
	v_mfma_f32_16x16x32_bf16 v[114:117], v[176:179], v[198:201], v[114:117]
	v_mfma_f32_16x16x32_bf16 v[106:109], v[168:171], v[206:209], v[106:109]
	v_mfma_f32_16x16x32_bf16 v[98:101], v[176:179], v[206:209], v[98:101]
	v_mfma_f32_16x16x32_bf16 v[90:93], v[168:171], v[234:237], v[90:93]
	v_mfma_f32_16x16x32_bf16 v[82:85], v[176:179], v[234:237], v[82:85]
	v_mfma_f32_16x16x32_bf16 v[74:77], v[168:171], v[242:245], v[74:77]
	v_mfma_f32_16x16x32_bf16 v[66:69], v[176:179], v[242:245], v[66:69]
	v_mfma_f32_16x16x32_bf16 v[122:125], v[172:175], v[202:205], v[122:125]
	v_mfma_f32_16x16x32_bf16 v[114:117], v[194:197], v[202:205], v[114:117]
	v_mfma_f32_16x16x32_bf16 v[106:109], v[172:175], v[210:213], v[106:109]
	v_mfma_f32_16x16x32_bf16 v[98:101], v[194:197], v[210:213], v[98:101]
	v_mfma_f32_16x16x32_bf16 v[90:93], v[172:175], v[238:241], v[90:93]
	v_mfma_f32_16x16x32_bf16 v[82:85], v[194:197], v[238:241], v[82:85]
	v_mfma_f32_16x16x32_bf16 v[74:77], v[172:175], v[246:249], v[74:77]
	v_mfma_f32_16x16x32_bf16 v[66:69], v[194:197], v[246:249], v[66:69]
	s_barrier
; #define PG8_STAGE(bufoff, gbase, voff) do { _Pragma("unroll") for (int _i = 0; _i < 2; ++_i) \
;         __builtin_amdgcn_global_load_lds((const unsigned*)((const char*)(gbase) + (voff)[_i]), (LAS unsigned*)(lds + (bufoff) + ldsw + _i * 8192), 16, 0, 0); } while (0)
; #define PG8_LDA(dst, b, h) do { _Pragma("unroll") for (int m = 0; m < 4; ++m) _Pragma("unroll") for (int k = 0; k < 2; ++k) dst[m][k] = *(const LAS bf16x8*)(lds + PG8_SA(b, h) + aoff + m * 2048 + k * 1024); } while (0)
; #define PG8_MMA(ai, bj, At, Bt) do { __builtin_amdgcn_s_setprio(1); _Pragma("unroll") for (int m = 0; m < 4; ++m) _Pragma("unroll") for (int n = 0; n < 2; ++n) _Pragma("unroll") for (int k = 0; k < 2; ++k) \
;         acc[ai][bj][m][n] = __builtin_amdgcn_mfma_f32_16x16x32_bf16(Bt[n][k], At[m][k], acc[ai][bj][m][n], 0, 0, 0); __builtin_amdgcn_s_setprio(0); } while (0)
; #define PG8_WAIT_V(n) asm volatile("s_waitcnt vmcnt(" #n ")" ::: "memory")
; #define PG8_WAIT_L(n) asm volatile("s_waitcnt lgkmcnt(" #n ")" ::: "memory")
; #define PG8_BAR __builtin_amdgcn_s_barrier()
; #define PG8_SCHED __builtin_amdgcn_sched_barrier(0)
; template <class Epi, class Sched, bool ALIGN_EPI = true, bool SP2 = true>
; __device__ __forceinline__ void gemm_phase(LAS unsigned char* lds, const Gemm g, const Sched& S, const Epi& E) {
;     ...
;             PG8_LDA(At, 1, 1); PG8_STAGE(PG8_SB(1, 0), b3, voffB); PG8_STAGE(PG8_SB(1, 1), b3 + hstep, voffB); PG8_STAGE(PG8_SA(1, 0), a3, voffA);
;             PG8_WAIT_V(8); PG8_WAIT_L(0); PG8_BAR; PG8_MMA(1, 0, At, B0); PG8_MMA(1, 1, At, B1); PG8_BAR; PG8_SCHED;
;     ...
;         if constexpr (ALIGN_EPI) { if (wr == 0) PG8_BAR; }
	s_setprio 0
	s_add_i32 s22, s58, s24
	v_lshl_add_u64 v[148:149], v[148:149], 0, s[92:93]
	s_mov_b32 m0, s22
	ds_read_b128 v[198:201], v159 offset:49152
	ds_read_b128 v[202:205], v159 offset:50176
	ds_read_b128 v[206:209], v159 offset:51200
	ds_read_b128 v[210:213], v159 offset:52224
	ds_read_b128 v[234:237], v159 offset:53248
	ds_read_b128 v[238:241], v159 offset:54272
	ds_read_b128 v[242:245], v159 offset:55296
	ds_read_b128 v[246:249], v159 offset:56320
	global_load_lds_dwordx4 v[148:149], off
	s_add_i32 m0, s22, 0x2000
	s_add_u32 s8, s8, 0x80080
	v_lshl_add_u64 v[148:149], v[156:157], 0, s[92:93]
	s_addc_u32 s9, s9, 0
	s_add_i32 s22, s59, s24
	global_load_lds_dwordx4 v[148:149], off
	v_lshl_add_u64 v[148:149], s[8:9], 0, v[0:1]
	s_mov_b32 m0, s22
	s_nop 0
	global_load_lds_dwordx4 v[148:149], off
	v_lshl_add_u64 v[148:149], s[8:9], 0, v[130:131]
	s_add_i32 m0, s22, 0x2000
	s_nop 0
	global_load_lds_dwordx4 v[148:149], off
	v_lshl_add_u64 v[148:149], v[214:215], 0, s[92:93]
	s_mov_b32 m0, s29
	s_nop 0
	global_load_lds_dwordx4 v[148:149], off
	v_lshl_add_u64 v[148:149], v[250:251], 0, s[92:93]
	s_mov_b32 m0, s30
	s_nop 0
	global_load_lds_dwordx4 v[148:149], off
	s_waitcnt vmcnt(8)
	s_waitcnt lgkmcnt(0)
	s_setprio 1
	s_barrier
	v_mfma_f32_16x16x32_bf16 v[62:65], v[140:143], v[198:201], v[62:65]
	v_mfma_f32_16x16x32_bf16 v[54:57], v[160:163], v[198:201], v[54:57]
	v_mfma_f32_16x16x32_bf16 v[46:49], v[140:143], v[206:209], v[46:49]
	v_mfma_f32_16x16x32_bf16 v[38:41], v[160:163], v[206:209], v[38:41]
	v_mfma_f32_16x16x32_bf16 v[30:33], v[140:143], v[234:237], v[30:33]
	v_mfma_f32_16x16x32_bf16 v[22:25], v[160:163], v[234:237], v[22:25]
	v_mfma_f32_16x16x32_bf16 v[14:17], v[140:143], v[242:245], v[14:17]
	v_mfma_f32_16x16x32_bf16 v[6:9], v[160:163], v[242:245], v[6:9]
	v_mfma_f32_16x16x32_bf16 v[62:65], v[144:147], v[202:205], v[62:65]
	v_mfma_f32_16x16x32_bf16 v[54:57], v[164:167], v[202:205], v[54:57]
	v_mfma_f32_16x16x32_bf16 v[46:49], v[144:147], v[210:213], v[46:49]
	v_mfma_f32_16x16x32_bf16 v[38:41], v[164:167], v[210:213], v[38:41]
	v_mfma_f32_16x16x32_bf16 v[30:33], v[144:147], v[238:241], v[30:33]
	v_mfma_f32_16x16x32_bf16 v[22:25], v[164:167], v[238:241], v[22:25]
	v_mfma_f32_16x16x32_bf16 v[14:17], v[144:147], v[246:249], v[14:17]
	v_mfma_f32_16x16x32_bf16 v[6:9], v[164:167], v[246:249], v[6:9]
	v_mfma_f32_16x16x32_bf16 v[58:61], v[168:171], v[198:201], v[58:61]
	v_mfma_f32_16x16x32_bf16 v[50:53], v[176:179], v[198:201], v[50:53]
	v_mfma_f32_16x16x32_bf16 v[42:45], v[168:171], v[206:209], v[42:45]
	v_mfma_f32_16x16x32_bf16 v[34:37], v[176:179], v[206:209], v[34:37]
	v_mfma_f32_16x16x32_bf16 v[26:29], v[168:171], v[234:237], v[26:29]
	v_mfma_f32_16x16x32_bf16 v[18:21], v[176:179], v[234:237], v[18:21]
	v_mfma_f32_16x16x32_bf16 v[10:13], v[168:171], v[242:245], v[10:13]
	v_mfma_f32_16x16x32_bf16 v[2:5], v[176:179], v[242:245], v[2:5]
	v_mfma_f32_16x16x32_bf16 v[58:61], v[172:175], v[202:205], v[58:61]
	v_mfma_f32_16x16x32_bf16 v[50:53], v[194:197], v[202:205], v[50:53]
	v_mfma_f32_16x16x32_bf16 v[42:45], v[172:175], v[210:213], v[42:45]
	v_mfma_f32_16x16x32_bf16 v[34:37], v[194:197], v[210:213], v[34:37]
	v_mfma_f32_16x16x32_bf16 v[26:29], v[172:175], v[238:241], v[26:29]
	v_mfma_f32_16x16x32_bf16 v[18:21], v[194:197], v[238:241], v[18:21]
	v_mfma_f32_16x16x32_bf16 v[10:13], v[172:175], v[246:249], v[10:13]
	v_mfma_f32_16x16x32_bf16 v[2:5], v[194:197], v[246:249], v[2:5]
	s_barrier
	s_setprio 0
	s_add_i32 s72, s72, 2
	s_add_u32 s6, s6, 0x100
	s_addc_u32 s7, s7, 0
	s_add_u32 s70, s70, 0x100
	s_addc_u32 s71, s71, 0
	s_cmp_gt_u32 s72, 29
	s_cbranch_scc0 .LBB0_94
	s_and_b64 vcc, exec, s[12:13]
	s_cbranch_vccz .LBB0_97
	s_barrier

; #define PG8_STAGE(bufoff, gbase, voff) do { _Pragma("unroll") for (int _i = 0; _i < 2; ++_i) \
;         __builtin_amdgcn_global_load_lds((const unsigned*)((const char*)(gbase) + (voff)[_i]), (LAS unsigned*)(lds + (bufoff) + ldsw + _i * 8192), 16, 0, 0); } while (0)
; #define PG8_LDA(dst, b, h) do { _Pragma("unroll") for (int m = 0; m < 4; ++m) _Pragma("unroll") for (int k = 0; k < 2; ++k) dst[m][k] = *(const LAS bf16x8*)(lds + PG8_SA(b, h) + aoff + m * 2048 + k * 1024); } while (0)
; #define PG8_LDB(dst, b, h) do { _Pragma("unroll") for (int n = 0; n < 2; ++n) _Pragma("unroll") for (int k = 0; k < 2; ++k) dst[n][k] = *(const LAS bf16x8*)(lds + PG8_SB(b, h) + boff + n * 2048 + k * 1024); } while (0)
; #define PG8_MMA(ai, bj, At, Bt) do { __builtin_amdgcn_s_setprio(1); _Pragma("unroll") for (int m = 0; m < 4; ++m) _Pragma("unroll") for (int n = 0; n < 2; ++n) _Pragma("unroll") for (int k = 0; k < 2; ++k) \
;         acc[ai][bj][m][n] = __builtin_amdgcn_mfma_f32_16x16x32_bf16(Bt[n][k], At[m][k], acc[ai][bj][m][n], 0, 0, 0); __builtin_amdgcn_s_setprio(0); } while (0)
; #define PG8_WAIT_V(n) asm volatile("s_waitcnt vmcnt(" #n ")" ::: "memory")
; #define PG8_WAIT_L(n) asm volatile("s_waitcnt lgkmcnt(" #n ")" ::: "memory")
; #define PG8_BAR __builtin_amdgcn_s_barrier()
; #define PG8_SCHED __builtin_amdgcn_sched_barrier(0)
; template <class Epi, class Sched, bool ALIGN_EPI = true, bool SP2 = true>
; __device__ __forceinline__ void gemm_phase(LAS unsigned char* lds, const Gemm g, const Sched& S, const Epi& E) {
;     ...
;         for (int t = 0; t < nt; t += 2) {
;             const bool last = (t == nt - 2);
;             const char* a1 = cA + (size_t)(t + 1) * kstep;
;             const char* a2 = last ? nA : cA + (size_t)(t + 2) * kstep; const char* b2 = last ? nB : cB + (size_t)(t + 2) * kstep;
;             const char* a3 = a2 + kstep; const char* b3 = b2 + kstep;
;             if constexpr (SP2) {
;             PG8_LDB(B0, 0, 0); PG8_LDB(B1, 0, 1); PG8_SCHED; PG8_LDA(At, 0, 0); PG8_STAGE(PG8_SA(1, 1), a1 + hstep, voffA);
;             PG8_WAIT_V(8); PG8_WAIT_L(0); PG8_BAR; PG8_MMA(0, 0, At, B0); PG8_MMA(0, 1, At, B1); PG8_BAR; PG8_SCHED;
;             PG8_LDA(At, 0, 1); PG8_STAGE(PG8_SB(0, 0), b2, voffB); PG8_STAGE(PG8_SB(0, 1), b2 + hstep, voffB); PG8_STAGE(PG8_SA(0, 0), a2, voffA);
.LBB0_186:
	s_add_u32 s6, s4, 0x100
	s_addc_u32 s7, s5, 0
	s_add_i32 s58, 0, 0x10000
	s_cmpk_eq_i32 s72, 0x54
	s_cselect_b32 s15, s1, s7
	s_cselect_b32 s14, s0, s6
	s_cselect_b32 s9, s31, s57
	s_cselect_b32 s8, s30, s56
	s_add_i32 s59, 0, 0x14000
	v_add_u32_e32 v142, s58, v208
	v_add_u32_e32 v164, s59, v208
	ds_read_b128 v[130:133], v142
	ds_read_b128 v[134:137], v142 offset:1024
	ds_read_b128 v[138:141], v142 offset:2048
	ds_read_b128 v[142:145], v142 offset:3072
	ds_read_b128 v[152:155], v164
	ds_read_b128 v[156:159], v164 offset:1024
	ds_read_b128 v[160:163], v164 offset:2048
	ds_read_b128 v[164:167], v164 offset:3072
	v_lshl_add_u64 v[206:207], s[4:5], 0, v[148:149]
	s_add_i32 m0, s71, 0xc000
	ds_read_b128 v[168:171], v210
	ds_read_b128 v[172:175], v210 offset:1024
	ds_read_b128 v[176:179], v210 offset:2048
	ds_read_b128 v[194:197], v210 offset:3072
	ds_read_b128 v[198:201], v210 offset:4096
	ds_read_b128 v[202:205], v210 offset:5120
	ds_read_b128 v[212:215], v210 offset:6144
	ds_read_b128 v[234:237], v210 offset:7168
	global_load_lds_dwordx4 v[206:207], off
	v_lshl_add_u64 v[206:207], s[4:5], 0, v[150:151]
	s_add_i32 m0, s71, 0xe000
	s_nop 0
	global_load_lds_dwordx4 v[206:207], off
	s_waitcnt vmcnt(8)
	s_waitcnt lgkmcnt(0)
	s_setprio 1
	s_barrier
	v_mfma_f32_16x16x32_bf16 v[126:129], v[130:133], v[168:171], v[126:129]
	v_mfma_f32_16x16x32_bf16 v[122:125], v[138:141], v[168:171], v[122:125]
	v_mfma_f32_16x16x32_bf16 v[110:113], v[130:133], v[176:179], v[110:113]
	v_mfma_f32_16x16x32_bf16 v[106:109], v[138:141], v[176:179], v[106:109]
	v_mfma_f32_16x16x32_bf16 v[94:97], v[130:133], v[198:201], v[94:97]
	v_mfma_f32_16x16x32_bf16 v[90:93], v[138:141], v[198:201], v[90:93]
	v_mfma_f32_16x16x32_bf16 v[78:81], v[130:133], v[212:215], v[78:81]
	v_mfma_f32_16x16x32_bf16 v[74:77], v[138:141], v[212:215], v[74:77]
	v_mfma_f32_16x16x32_bf16 v[126:129], v[134:137], v[172:175], v[126:129]
	v_mfma_f32_16x16x32_bf16 v[122:125], v[142:145], v[172:175], v[122:125]
	v_mfma_f32_16x16x32_bf16 v[110:113], v[134:137], v[194:197], v[110:113]
	v_mfma_f32_16x16x32_bf16 v[106:109], v[142:145], v[194:197], v[106:109]
	v_mfma_f32_16x16x32_bf16 v[94:97], v[134:137], v[202:205], v[94:97]
	v_mfma_f32_16x16x32_bf16 v[90:93], v[142:145], v[202:205], v[90:93]
	v_mfma_f32_16x16x32_bf16 v[78:81], v[134:137], v[234:237], v[78:81]
	v_mfma_f32_16x16x32_bf16 v[74:77], v[142:145], v[234:237], v[74:77]
	v_mfma_f32_16x16x32_bf16 v[118:121], v[152:155], v[168:171], v[118:121]
	v_mfma_f32_16x16x32_bf16 v[114:117], v[160:163], v[168:171], v[114:117]
	v_mfma_f32_16x16x32_bf16 v[102:105], v[152:155], v[176:179], v[102:105]
	v_mfma_f32_16x16x32_bf16 v[98:101], v[160:163], v[176:179], v[98:101]
	v_mfma_f32_16x16x32_bf16 v[86:89], v[152:155], v[198:201], v[86:89]
	v_mfma_f32_16x16x32_bf16 v[82:85], v[160:163], v[198:201], v[82:85]
	v_mfma_f32_16x16x32_bf16 v[70:73], v[152:155], v[212:215], v[70:73]
	v_mfma_f32_16x16x32_bf16 v[66:69], v[160:163], v[212:215], v[66:69]
	v_mfma_f32_16x16x32_bf16 v[118:121], v[156:159], v[172:175], v[118:121]
	v_mfma_f32_16x16x32_bf16 v[114:117], v[164:167], v[172:175], v[114:117]
	v_mfma_f32_16x16x32_bf16 v[102:105], v[156:159], v[194:197], v[102:105]
	v_mfma_f32_16x16x32_bf16 v[98:101], v[164:167], v[194:197], v[98:101]
	v_mfma_f32_16x16x32_bf16 v[86:89], v[156:159], v[202:205], v[86:89]
	v_mfma_f32_16x16x32_bf16 v[82:85], v[164:167], v[202:205], v[82:85]
	v_mfma_f32_16x16x32_bf16 v[70:73], v[156:159], v[234:237], v[70:73]
	v_mfma_f32_16x16x32_bf16 v[66:69], v[164:167], v[234:237], v[66:69]
	s_barrier
	s_setprio 0
	s_add_i32 s4, s58, s70
	v_lshl_add_u64 v[206:207], s[8:9], 0, v[0:1]
	s_mov_b32 m0, s4
	ds_read_b128 v[168:171], v210 offset:16384
	ds_read_b128 v[172:175], v210 offset:17408
	ds_read_b128 v[176:179], v210 offset:18432
	ds_read_b128 v[194:197], v210 offset:19456
	ds_read_b128 v[198:201], v210 offset:20480
	ds_read_b128 v[202:205], v210 offset:21504
	ds_read_b128 v[212:215], v210 offset:22528
	ds_read_b128 v[234:237], v210 offset:23552
	global_load_lds_dwordx4 v[206:207], off
	s_add_i32 m0, s4, 0x2000
	s_add_u32 s4, s8, 0x160000
	v_lshl_add_u64 v[224:225], s[8:9], 0, v[146:147]
	s_addc_u32 s5, s9, 0
	s_add_i32 s58, s59, s70
	global_load_lds_dwordx4 v[224:225], off
	v_lshl_add_u64 v[238:239], s[4:5], 0, v[0:1]
	s_mov_b32 m0, s58
	v_lshl_add_u64 v[240:241], s[14:15], 0, v[146:147]
	global_load_lds_dwordx4 v[238:239], off
	v_lshl_add_u64 v[238:239], s[4:5], 0, v[146:147]
	s_add_i32 m0, s58, 0x2000
	s_nop 0
	global_load_lds_dwordx4 v[238:239], off
	v_lshl_add_u64 v[238:239], s[14:15], 0, v[0:1]
	s_mov_b32 m0, s71
	s_nop 0
	global_load_lds_dwordx4 v[238:239], off
	s_mov_b32 m0, s74
	s_nop 0
	global_load_lds_dwordx4 v[240:241], off
	s_waitcnt vmcnt(8)
	s_waitcnt lgkmcnt(0)
	s_setprio 1
	s_barrier
; #define PG8_STAGE(bufoff, gbase, voff) do { _Pragma("unroll") for (int _i = 0; _i < 2; ++_i) \
;         __builtin_amdgcn_global_load_lds((const unsigned*)((const char*)(gbase) + (voff)[_i]), (LAS unsigned*)(lds + (bufoff) + ldsw + _i * 8192), 16, 0, 0); } while (0)
; #define PG8_LDA(dst, b, h) do { _Pragma("unroll") for (int m = 0; m < 4; ++m) _Pragma("unroll") for (int k = 0; k < 2; ++k) dst[m][k] = *(const LAS bf16x8*)(lds + PG8_SA(b, h) + aoff + m * 2048 + k * 1024); } while (0)
; #define PG8_LDB(dst, b, h) do { _Pragma("unroll") for (int n = 0; n < 2; ++n) _Pragma("unroll") for (int k = 0; k < 2; ++k) dst[n][k] = *(const LAS bf16x8*)(lds + PG8_SB(b, h) + boff + n * 2048 + k * 1024); } while (0)
; #define PG8_MMA(ai, bj, At, Bt) do { __builtin_amdgcn_s_setprio(1); _Pragma("unroll") for (int m = 0; m < 4; ++m) _Pragma("unroll") for (int n = 0; n < 2; ++n) _Pragma("unroll") for (int k = 0; k < 2; ++k) \
;         acc[ai][bj][m][n] = __builtin_amdgcn_mfma_f32_16x16x32_bf16(Bt[n][k], At[m][k], acc[ai][bj][m][n], 0, 0, 0); __builtin_amdgcn_s_setprio(0); } while (0)
; #define PG8_WAIT_V(n) asm volatile("s_waitcnt vmcnt(" #n ")" ::: "memory")
; #define PG8_WAIT_L(n) asm volatile("s_waitcnt lgkmcnt(" #n ")" ::: "memory")
; #define PG8_BAR __builtin_amdgcn_s_barrier()
; #define PG8_SCHED __builtin_amdgcn_sched_barrier(0)
; template <class Epi, class Sched, bool ALIGN_EPI = true, bool SP2 = true>
; __device__ __forceinline__ void gemm_phase(LAS unsigned char* lds, const Gemm g, const Sched& S, const Epi& E) {
;     ...
;             PG8_WAIT_V(8); PG8_WAIT_L(0); PG8_BAR; PG8_MMA(1, 0, At, B0); PG8_MMA(1, 1, At, B1); PG8_BAR; PG8_SCHED;
;             PG8_LDB(B0, 1, 0); PG8_LDB(B1, 1, 1); PG8_SCHED; PG8_LDA(At, 1, 0); PG8_STAGE(PG8_SA(0, 1), a2 + hstep, voffA);
;             PG8_WAIT_V(8); PG8_WAIT_L(0); PG8_BAR; PG8_MMA(0, 0, At, B0); PG8_MMA(0, 1, At, B1); PG8_BAR; PG8_SCHED;
	v_mfma_f32_16x16x32_bf16 v[62:65], v[130:133], v[168:171], v[62:65]
	v_mfma_f32_16x16x32_bf16 v[58:61], v[138:141], v[168:171], v[58:61]
	v_mfma_f32_16x16x32_bf16 v[46:49], v[130:133], v[176:179], v[46:49]
	v_mfma_f32_16x16x32_bf16 v[42:45], v[138:141], v[176:179], v[42:45]
	v_mfma_f32_16x16x32_bf16 v[30:33], v[130:133], v[198:201], v[30:33]
	v_mfma_f32_16x16x32_bf16 v[26:29], v[138:141], v[198:201], v[26:29]
	v_mfma_f32_16x16x32_bf16 v[14:17], v[130:133], v[212:215], v[14:17]
	v_mfma_f32_16x16x32_bf16 v[10:13], v[138:141], v[212:215], v[10:13]
	v_mfma_f32_16x16x32_bf16 v[62:65], v[134:137], v[172:175], v[62:65]
	v_mfma_f32_16x16x32_bf16 v[58:61], v[142:145], v[172:175], v[58:61]
	v_mfma_f32_16x16x32_bf16 v[46:49], v[134:137], v[194:197], v[46:49]
	v_mfma_f32_16x16x32_bf16 v[42:45], v[142:145], v[194:197], v[42:45]
	v_mfma_f32_16x16x32_bf16 v[30:33], v[134:137], v[202:205], v[30:33]
	v_mfma_f32_16x16x32_bf16 v[26:29], v[142:145], v[202:205], v[26:29]
	v_mfma_f32_16x16x32_bf16 v[14:17], v[134:137], v[234:237], v[14:17]
	v_mfma_f32_16x16x32_bf16 v[10:13], v[142:145], v[234:237], v[10:13]
	v_mfma_f32_16x16x32_bf16 v[54:57], v[152:155], v[168:171], v[54:57]
	v_mfma_f32_16x16x32_bf16 v[50:53], v[160:163], v[168:171], v[50:53]
	v_mfma_f32_16x16x32_bf16 v[38:41], v[152:155], v[176:179], v[38:41]
	v_mfma_f32_16x16x32_bf16 v[34:37], v[160:163], v[176:179], v[34:37]
	v_mfma_f32_16x16x32_bf16 v[22:25], v[152:155], v[198:201], v[22:25]
	v_mfma_f32_16x16x32_bf16 v[18:21], v[160:163], v[198:201], v[18:21]
	v_mfma_f32_16x16x32_bf16 v[6:9], v[152:155], v[212:215], v[6:9]
	v_mfma_f32_16x16x32_bf16 v[2:5], v[160:163], v[212:215], v[2:5]
	v_mfma_f32_16x16x32_bf16 v[54:57], v[156:159], v[172:175], v[54:57]
	v_mfma_f32_16x16x32_bf16 v[50:53], v[164:167], v[172:175], v[50:53]
	v_mfma_f32_16x16x32_bf16 v[38:41], v[156:159], v[194:197], v[38:41]
	v_mfma_f32_16x16x32_bf16 v[34:37], v[164:167], v[194:197], v[34:37]
	v_mfma_f32_16x16x32_bf16 v[22:25], v[156:159], v[202:205], v[22:25]
	v_mfma_f32_16x16x32_bf16 v[18:21], v[164:167], v[202:205], v[18:21]
	v_mfma_f32_16x16x32_bf16 v[6:9], v[156:159], v[234:237], v[6:9]
	v_mfma_f32_16x16x32_bf16 v[2:5], v[164:167], v[234:237], v[2:5]
	s_barrier
	s_setprio 0
	s_add_i32 s58, 0, 0x18000
	s_add_i32 s59, 0, 0x1c000
	v_add_u32_e32 v142, s58, v208
	v_add_u32_e32 v164, s59, v208
	ds_read_b128 v[130:133], v142
	ds_read_b128 v[134:137], v142 offset:1024
	ds_read_b128 v[138:141], v142 offset:2048
	ds_read_b128 v[142:145], v142 offset:3072
	ds_read_b128 v[152:155], v164
	ds_read_b128 v[156:159], v164 offset:1024
	ds_read_b128 v[160:163], v164 offset:2048
	ds_read_b128 v[164:167], v164 offset:3072
	s_add_u32 s4, s14, 0x160000
	s_addc_u32 s5, s15, 0
	s_mov_b32 m0, s75
	v_lshl_add_u64 v[242:243], s[4:5], 0, v[0:1]
	ds_read_b128 v[168:171], v210 offset:32768
	ds_read_b128 v[172:175], v210 offset:33792
	ds_read_b128 v[176:179], v210 offset:34816
	ds_read_b128 v[194:197], v210 offset:35840
	ds_read_b128 v[198:201], v210 offset:36864
	ds_read_b128 v[202:205], v210 offset:37888
	ds_read_b128 v[212:215], v210 offset:38912
	ds_read_b128 v[234:237], v210 offset:39936
	global_load_lds_dwordx4 v[242:243], off
	v_lshl_add_u64 v[242:243], s[4:5], 0, v[146:147]
	s_mov_b32 m0, s76
	s_nop 0
	global_load_lds_dwordx4 v[242:243], off
	s_waitcnt vmcnt(8)
	s_waitcnt lgkmcnt(0)
	s_setprio 1
	s_barrier
	v_mfma_f32_16x16x32_bf16 v[126:129], v[130:133], v[168:171], v[126:129]
	v_mfma_f32_16x16x32_bf16 v[122:125], v[138:141], v[168:171], v[122:125]
	v_mfma_f32_16x16x32_bf16 v[110:113], v[130:133], v[176:179], v[110:113]
	v_mfma_f32_16x16x32_bf16 v[106:109], v[138:141], v[176:179], v[106:109]
	v_mfma_f32_16x16x32_bf16 v[94:97], v[130:133], v[198:201], v[94:97]
	v_mfma_f32_16x16x32_bf16 v[90:93], v[138:141], v[198:201], v[90:93]
	v_mfma_f32_16x16x32_bf16 v[78:81], v[130:133], v[212:215], v[78:81]
	v_mfma_f32_16x16x32_bf16 v[74:77], v[138:141], v[212:215], v[74:77]
	v_mfma_f32_16x16x32_bf16 v[126:129], v[134:137], v[172:175], v[126:129]
	v_mfma_f32_16x16x32_bf16 v[122:125], v[142:145], v[172:175], v[122:125]
	v_mfma_f32_16x16x32_bf16 v[110:113], v[134:137], v[194:197], v[110:113]
	v_mfma_f32_16x16x32_bf16 v[106:109], v[142:145], v[194:197], v[106:109]
	v_mfma_f32_16x16x32_bf16 v[94:97], v[134:137], v[202:205], v[94:97]
	v_mfma_f32_16x16x32_bf16 v[90:93], v[142:145], v[202:205], v[90:93]
	v_mfma_f32_16x16x32_bf16 v[78:81], v[134:137], v[234:237], v[78:81]
	v_mfma_f32_16x16x32_bf16 v[74:77], v[142:145], v[234:237], v[74:77]
	v_mfma_f32_16x16x32_bf16 v[118:121], v[152:155], v[168:171], v[118:121]
	v_mfma_f32_16x16x32_bf16 v[114:117], v[160:163], v[168:171], v[114:117]
	v_mfma_f32_16x16x32_bf16 v[102:105], v[152:155], v[176:179], v[102:105]
	v_mfma_f32_16x16x32_bf16 v[98:101], v[160:163], v[176:179], v[98:101]
	v_mfma_f32_16x16x32_bf16 v[86:89], v[152:155], v[198:201], v[86:89]
	v_mfma_f32_16x16x32_bf16 v[82:85], v[160:163], v[198:201], v[82:85]
	v_mfma_f32_16x16x32_bf16 v[70:73], v[152:155], v[212:215], v[70:73]
	v_mfma_f32_16x16x32_bf16 v[66:69], v[160:163], v[212:215], v[66:69]
	v_mfma_f32_16x16x32_bf16 v[118:121], v[156:159], v[172:175], v[118:121]
	v_mfma_f32_16x16x32_bf16 v[114:117], v[164:167], v[172:175], v[114:117]
	v_mfma_f32_16x16x32_bf16 v[102:105], v[156:159], v[194:197], v[102:105]
	v_mfma_f32_16x16x32_bf16 v[98:101], v[164:167], v[194:197], v[98:101]
	v_mfma_f32_16x16x32_bf16 v[86:89], v[156:159], v[202:205], v[86:89]
	v_mfma_f32_16x16x32_bf16 v[82:85], v[164:167], v[202:205], v[82:85]
	v_mfma_f32_16x16x32_bf16 v[70:73], v[156:159], v[234:237], v[70:73]
	v_mfma_f32_16x16x32_bf16 v[66:69], v[164:167], v[234:237], v[66:69]
	s_barrier
; #define PG8_STAGE(bufoff, gbase, voff) do { _Pragma("unroll") for (int _i = 0; _i < 2; ++_i) \
;         __builtin_amdgcn_global_load_lds((const unsigned*)((const char*)(gbase) + (voff)[_i]), (LAS unsigned*)(lds + (bufoff) + ldsw + _i * 8192), 16, 0, 0); } while (0)
; #define PG8_LDA(dst, b, h) do { _Pragma("unroll") for (int m = 0; m < 4; ++m) _Pragma("unroll") for (int k = 0; k < 2; ++k) dst[m][k] = *(const LAS bf16x8*)(lds + PG8_SA(b, h) + aoff + m * 2048 + k * 1024); } while (0)
; #define PG8_MMA(ai, bj, At, Bt) do { __builtin_amdgcn_s_setprio(1); _Pragma("unroll") for (int m = 0; m < 4; ++m) _Pragma("unroll") for (int n = 0; n < 2; ++n) _Pragma("unroll") for (int k = 0; k < 2; ++k) \
;         acc[ai][bj][m][n] = __builtin_amdgcn_mfma_f32_16x16x32_bf16(Bt[n][k], At[m][k], acc[ai][bj][m][n], 0, 0, 0); __builtin_amdgcn_s_setprio(0); } while (0)
; #define PG8_WAIT_V(n) asm volatile("s_waitcnt vmcnt(" #n ")" ::: "memory")
; #define PG8_WAIT_L(n) asm volatile("s_waitcnt lgkmcnt(" #n ")" ::: "memory")
; #define PG8_BAR __builtin_amdgcn_s_barrier()
; #define PG8_SCHED __builtin_amdgcn_sched_barrier(0)
; template <class Epi, class Sched, bool ALIGN_EPI = true, bool SP2 = true>
; __device__ __forceinline__ void gemm_phase(LAS unsigned char* lds, const Gemm g, const Sched& S, const Epi& E) {
;     ...
;             PG8_LDA(At, 1, 1); PG8_STAGE(PG8_SB(1, 0), b3, voffB); PG8_STAGE(PG8_SB(1, 1), b3 + hstep, voffB); PG8_STAGE(PG8_SA(1, 0), a3, voffA);
;             PG8_WAIT_V(8); PG8_WAIT_L(0); PG8_BAR; PG8_MMA(1, 0, At, B0); PG8_MMA(1, 1, At, B1); PG8_BAR; PG8_SCHED;
;     ...
;         if constexpr (ALIGN_EPI) { if (wr == 0) PG8_BAR; }
	s_setprio 0
	s_add_i32 s4, s58, s70
	v_lshl_add_u64 v[206:207], v[206:207], 0, s[92:93]
	s_mov_b32 m0, s4
	ds_read_b128 v[168:171], v210 offset:49152
	ds_read_b128 v[172:175], v210 offset:50176
	ds_read_b128 v[176:179], v210 offset:51200
	ds_read_b128 v[194:197], v210 offset:52224
	ds_read_b128 v[198:201], v210 offset:53248
	ds_read_b128 v[202:205], v210 offset:54272
	ds_read_b128 v[212:215], v210 offset:55296
	ds_read_b128 v[234:237], v210 offset:56320
	global_load_lds_dwordx4 v[206:207], off
	s_add_i32 m0, s4, 0x2000
	s_add_u32 s4, s8, 0x160080
	v_lshl_add_u64 v[206:207], v[224:225], 0, s[92:93]
	s_addc_u32 s5, s9, 0
	s_add_i32 s8, s59, s70
	global_load_lds_dwordx4 v[206:207], off
	v_lshl_add_u64 v[206:207], s[4:5], 0, v[0:1]
	s_mov_b32 m0, s8
	s_nop 0
	global_load_lds_dwordx4 v[206:207], off
	v_lshl_add_u64 v[206:207], s[4:5], 0, v[146:147]
	s_add_i32 m0, s8, 0x2000
	s_nop 0
	global_load_lds_dwordx4 v[206:207], off
	v_lshl_add_u64 v[206:207], v[238:239], 0, s[92:93]
	s_mov_b32 m0, s78
	s_nop 0
	global_load_lds_dwordx4 v[206:207], off
	v_lshl_add_u64 v[206:207], v[240:241], 0, s[92:93]
	s_mov_b32 m0, s96
	s_nop 0
	global_load_lds_dwordx4 v[206:207], off
	s_waitcnt vmcnt(8)
	s_waitcnt lgkmcnt(0)
	s_setprio 1
	s_barrier
	v_mfma_f32_16x16x32_bf16 v[62:65], v[130:133], v[168:171], v[62:65]
	v_mfma_f32_16x16x32_bf16 v[58:61], v[138:141], v[168:171], v[58:61]
	v_mfma_f32_16x16x32_bf16 v[46:49], v[130:133], v[176:179], v[46:49]
	v_mfma_f32_16x16x32_bf16 v[42:45], v[138:141], v[176:179], v[42:45]
	v_mfma_f32_16x16x32_bf16 v[30:33], v[130:133], v[198:201], v[30:33]
	v_mfma_f32_16x16x32_bf16 v[26:29], v[138:141], v[198:201], v[26:29]
	v_mfma_f32_16x16x32_bf16 v[14:17], v[130:133], v[212:215], v[14:17]
	v_mfma_f32_16x16x32_bf16 v[10:13], v[138:141], v[212:215], v[10:13]
	v_mfma_f32_16x16x32_bf16 v[62:65], v[134:137], v[172:175], v[62:65]
	v_mfma_f32_16x16x32_bf16 v[58:61], v[142:145], v[172:175], v[58:61]
	v_mfma_f32_16x16x32_bf16 v[46:49], v[134:137], v[194:197], v[46:49]
	v_mfma_f32_16x16x32_bf16 v[42:45], v[142:145], v[194:197], v[42:45]
	v_mfma_f32_16x16x32_bf16 v[30:33], v[134:137], v[202:205], v[30:33]
	v_mfma_f32_16x16x32_bf16 v[26:29], v[142:145], v[202:205], v[26:29]
	v_mfma_f32_16x16x32_bf16 v[14:17], v[134:137], v[234:237], v[14:17]
	v_mfma_f32_16x16x32_bf16 v[10:13], v[142:145], v[234:237], v[10:13]
	v_mfma_f32_16x16x32_bf16 v[54:57], v[152:155], v[168:171], v[54:57]
	v_mfma_f32_16x16x32_bf16 v[50:53], v[160:163], v[168:171], v[50:53]
	v_mfma_f32_16x16x32_bf16 v[38:41], v[152:155], v[176:179], v[38:41]
	v_mfma_f32_16x16x32_bf16 v[34:37], v[160:163], v[176:179], v[34:37]
	v_mfma_f32_16x16x32_bf16 v[22:25], v[152:155], v[198:201], v[22:25]
	v_mfma_f32_16x16x32_bf16 v[18:21], v[160:163], v[198:201], v[18:21]
	v_mfma_f32_16x16x32_bf16 v[6:9], v[152:155], v[212:215], v[6:9]
	v_mfma_f32_16x16x32_bf16 v[2:5], v[160:163], v[212:215], v[2:5]
	v_mfma_f32_16x16x32_bf16 v[54:57], v[156:159], v[172:175], v[54:57]
	v_mfma_f32_16x16x32_bf16 v[50:53], v[164:167], v[172:175], v[50:53]
	v_mfma_f32_16x16x32_bf16 v[38:41], v[156:159], v[194:197], v[38:41]
	v_mfma_f32_16x16x32_bf16 v[34:37], v[164:167], v[194:197], v[34:37]
	v_mfma_f32_16x16x32_bf16 v[22:25], v[156:159], v[202:205], v[22:25]
	v_mfma_f32_16x16x32_bf16 v[18:21], v[164:167], v[202:205], v[18:21]
	v_mfma_f32_16x16x32_bf16 v[6:9], v[156:159], v[234:237], v[6:9]
	v_mfma_f32_16x16x32_bf16 v[2:5], v[164:167], v[234:237], v[2:5]
	s_barrier
	s_setprio 0
	s_add_i32 s72, s72, 2
	s_add_u32 s56, s56, 0x100
	s_addc_u32 s57, s57, 0
	s_cmpk_gt_u32 s72, 0x55
	s_mov_b64 s[4:5], s[6:7]
	s_cbranch_scc0 .LBB0_186
	s_and_b64 vcc, exec, s[24:25]
	s_cbranch_vccz .LBB0_189
	s_barrier

; #define PG8_STAGE(bufoff, gbase, voff) do { _Pragma("unroll") for (int _i = 0; _i < 2; ++_i) \
;         __builtin_amdgcn_global_load_lds((const unsigned*)((const char*)(gbase) + (voff)[_i]), (LAS unsigned*)(lds + (bufoff) + ldsw + _i * 8192), 16, 0, 0); } while (0)
; #define PG8_LDA(dst, b, h) do { _Pragma("unroll") for (int m = 0; m < 4; ++m) _Pragma("unroll") for (int k = 0; k < 2; ++k) dst[m][k] = *(const LAS bf16x8*)(lds + PG8_SA(b, h) + aoff + m * 2048 + k * 1024); } while (0)
; #define PG8_LDB(dst, b, h) do { _Pragma("unroll") for (int n = 0; n < 2; ++n) _Pragma("unroll") for (int k = 0; k < 2; ++k) dst[n][k] = *(const LAS bf16x8*)(lds + PG8_SB(b, h) + boff + n * 2048 + k * 1024); } while (0)
; #define PG8_MMA(ai, bj, At, Bt) do { __builtin_amdgcn_s_setprio(1); _Pragma("unroll") for (int m = 0; m < 4; ++m) _Pragma("unroll") for (int n = 0; n < 2; ++n) _Pragma("unroll") for (int k = 0; k < 2; ++k) \
;         acc[ai][bj][m][n] = __builtin_amdgcn_mfma_f32_16x16x32_bf16(Bt[n][k], At[m][k], acc[ai][bj][m][n], 0, 0, 0); __builtin_amdgcn_s_setprio(0); } while (0)
; #define PG8_WAIT_V(n) asm volatile("s_waitcnt vmcnt(" #n ")" ::: "memory")
; #define PG8_WAIT_L(n) asm volatile("s_waitcnt lgkmcnt(" #n ")" ::: "memory")
; #define PG8_BAR __builtin_amdgcn_s_barrier()
; #define PG8_SCHED __builtin_amdgcn_sched_barrier(0)
; template <class Epi, class Sched, bool ALIGN_EPI = true, bool SP2 = true>
; __device__ __forceinline__ void gemm_phase(LAS unsigned char* lds, const Gemm g, const Sched& S, const Epi& E) {
;     ...
;         for (int t = 0; t < nt; t += 2) {
;             const bool last = (t == nt - 2);
;             const char* a1 = cA + (size_t)(t + 1) * kstep;
;             const char* a2 = last ? nA : cA + (size_t)(t + 2) * kstep; const char* b2 = last ? nB : cB + (size_t)(t + 2) * kstep;
;             const char* a3 = a2 + kstep; const char* b3 = b2 + kstep;
;             if constexpr (SP2) {
;             PG8_LDB(B0, 0, 0); PG8_LDB(B1, 0, 1); PG8_SCHED; PG8_LDA(At, 0, 0); PG8_STAGE(PG8_SA(1, 1), a1 + hstep, voffA);
;             PG8_WAIT_V(8); PG8_WAIT_L(0); PG8_BAR; PG8_MMA(0, 0, At, B0); PG8_MMA(0, 1, At, B1); PG8_BAR; PG8_SCHED;
;             PG8_LDA(At, 0, 1); PG8_STAGE(PG8_SB(0, 0), b2, voffB); PG8_STAGE(PG8_SB(0, 1), b2 + hstep, voffB); PG8_STAGE(PG8_SA(0, 0), a2, voffA);
.LBB0_306:
	s_add_u32 s20, s16, 0xfff80080
	s_addc_u32 s21, s17, -1
	s_add_i32 s58, 0, 0x10000
	s_cmp_eq_u32 s74, 28
	s_cselect_b32 s23, s9, s21
	s_cselect_b32 s22, s70, s20
	v_add_u32_e32 v144, s58, v147
	s_cselect_b32 s21, s7, s73
	s_cselect_b32 s20, s71, s72
	s_add_i32 s75, 0, 0x14000
	ds_read_b128 v[140:143], v144
	ds_read_b128 v[154:157], v144 offset:1024
	ds_read_b128 v[158:161], v144 offset:2048
	ds_read_b128 v[162:165], v144 offset:3072
	v_add_u32_e32 v144, s75, v147
	ds_read_b128 v[166:169], v144
	ds_read_b128 v[170:173], v144 offset:1024
	ds_read_b128 v[174:177], v144 offset:2048
	ds_read_b128 v[194:197], v144 offset:3072
	v_lshl_add_u64 v[150:151], s[16:17], 0, v[136:137]
	s_add_i32 m0, s27, 0xc000
	ds_read_b128 v[198:201], v153
	ds_read_b128 v[202:205], v153 offset:1024
	ds_read_b128 v[206:209], v153 offset:2048
	ds_read_b128 v[210:213], v153 offset:3072
	ds_read_b128 v[234:237], v153 offset:4096
	ds_read_b128 v[238:241], v153 offset:5120
	ds_read_b128 v[242:245], v153 offset:6144
	ds_read_b128 v[246:249], v153 offset:7168
	global_load_lds_dwordx4 v[150:151], off
	v_lshl_add_u64 v[150:151], s[16:17], 0, v[138:139]
	s_add_i32 m0, s27, 0xe000
	s_nop 0
	global_load_lds_dwordx4 v[150:151], off
	s_waitcnt vmcnt(8)
	s_waitcnt lgkmcnt(0)
	s_setprio 1
	s_barrier
	v_mfma_f32_16x16x32_bf16 v[126:129], v[140:143], v[198:201], v[126:129]
	v_mfma_f32_16x16x32_bf16 v[122:125], v[158:161], v[198:201], v[122:125]
	v_mfma_f32_16x16x32_bf16 v[114:117], v[140:143], v[206:209], v[114:117]
	v_mfma_f32_16x16x32_bf16 v[106:109], v[158:161], v[206:209], v[106:109]
	v_mfma_f32_16x16x32_bf16 v[98:101], v[140:143], v[234:237], v[98:101]
	v_mfma_f32_16x16x32_bf16 v[90:93], v[158:161], v[234:237], v[90:93]
	v_mfma_f32_16x16x32_bf16 v[82:85], v[140:143], v[242:245], v[82:85]
	v_mfma_f32_16x16x32_bf16 v[74:77], v[158:161], v[242:245], v[74:77]
	v_mfma_f32_16x16x32_bf16 v[126:129], v[154:157], v[202:205], v[126:129]
	v_mfma_f32_16x16x32_bf16 v[122:125], v[162:165], v[202:205], v[122:125]
	v_mfma_f32_16x16x32_bf16 v[114:117], v[154:157], v[210:213], v[114:117]
	v_mfma_f32_16x16x32_bf16 v[106:109], v[162:165], v[210:213], v[106:109]
	v_mfma_f32_16x16x32_bf16 v[98:101], v[154:157], v[238:241], v[98:101]
	v_mfma_f32_16x16x32_bf16 v[90:93], v[162:165], v[238:241], v[90:93]
	v_mfma_f32_16x16x32_bf16 v[82:85], v[154:157], v[246:249], v[82:85]
	v_mfma_f32_16x16x32_bf16 v[74:77], v[162:165], v[246:249], v[74:77]
	v_mfma_f32_16x16x32_bf16 v[118:121], v[166:169], v[198:201], v[118:121]
	v_mfma_f32_16x16x32_bf16 v[110:113], v[174:177], v[198:201], v[110:113]
	v_mfma_f32_16x16x32_bf16 v[102:105], v[166:169], v[206:209], v[102:105]
	v_mfma_f32_16x16x32_bf16 v[94:97], v[174:177], v[206:209], v[94:97]
	v_mfma_f32_16x16x32_bf16 v[86:89], v[166:169], v[234:237], v[86:89]
	v_mfma_f32_16x16x32_bf16 v[78:81], v[174:177], v[234:237], v[78:81]
	v_mfma_f32_16x16x32_bf16 v[70:73], v[166:169], v[242:245], v[70:73]
	v_mfma_f32_16x16x32_bf16 v[66:69], v[174:177], v[242:245], v[66:69]
	v_mfma_f32_16x16x32_bf16 v[118:121], v[170:173], v[202:205], v[118:121]
	v_mfma_f32_16x16x32_bf16 v[110:113], v[194:197], v[202:205], v[110:113]
	v_mfma_f32_16x16x32_bf16 v[102:105], v[170:173], v[210:213], v[102:105]
	v_mfma_f32_16x16x32_bf16 v[94:97], v[194:197], v[210:213], v[94:97]
	v_mfma_f32_16x16x32_bf16 v[86:89], v[170:173], v[238:241], v[86:89]
	v_mfma_f32_16x16x32_bf16 v[78:81], v[194:197], v[238:241], v[78:81]
	v_mfma_f32_16x16x32_bf16 v[70:73], v[170:173], v[246:249], v[70:73]
	v_mfma_f32_16x16x32_bf16 v[66:69], v[194:197], v[246:249], v[66:69]
	s_barrier
	s_setprio 0
	s_add_i32 s58, s58, s26
	v_lshl_add_u64 v[150:151], s[20:21], 0, v[0:1]
	s_mov_b32 m0, s58
	ds_read_b128 v[198:201], v153 offset:16384
	ds_read_b128 v[202:205], v153 offset:17408
	ds_read_b128 v[206:209], v153 offset:18432
	ds_read_b128 v[210:213], v153 offset:19456
	ds_read_b128 v[234:237], v153 offset:20480
	ds_read_b128 v[238:241], v153 offset:21504
	ds_read_b128 v[242:245], v153 offset:22528
	ds_read_b128 v[246:249], v153 offset:23552
	global_load_lds_dwordx4 v[150:151], off
	s_add_i32 m0, s58, 0x2000
	s_add_u32 s58, s20, 0x80000
	v_lshl_add_u64 v[178:179], s[20:21], 0, v[130:131]
	s_addc_u32 s59, s21, 0
	s_add_i32 s75, s75, s26
	global_load_lds_dwordx4 v[178:179], off
	v_lshl_add_u64 v[214:215], s[58:59], 0, v[0:1]
	s_mov_b32 m0, s75
	v_lshl_add_u64 v[224:225], s[22:23], 0, v[132:133]
	global_load_lds_dwordx4 v[214:215], off
	v_lshl_add_u64 v[214:215], s[58:59], 0, v[130:131]
	s_add_i32 m0, s75, 0x2000
	s_nop 0
	global_load_lds_dwordx4 v[214:215], off
	v_lshl_add_u64 v[214:215], s[22:23], 0, v[134:135]
	s_mov_b32 m0, s27
	s_nop 0
	global_load_lds_dwordx4 v[214:215], off
	s_mov_b32 m0, s28
	s_nop 0
	global_load_lds_dwordx4 v[224:225], off
	s_waitcnt vmcnt(8)
	s_waitcnt lgkmcnt(0)
	s_setprio 1
	s_barrier
; #define PG8_STAGE(bufoff, gbase, voff) do { _Pragma("unroll") for (int _i = 0; _i < 2; ++_i) \
;         __builtin_amdgcn_global_load_lds((const unsigned*)((const char*)(gbase) + (voff)[_i]), (LAS unsigned*)(lds + (bufoff) + ldsw + _i * 8192), 16, 0, 0); } while (0)
; #define PG8_LDA(dst, b, h) do { _Pragma("unroll") for (int m = 0; m < 4; ++m) _Pragma("unroll") for (int k = 0; k < 2; ++k) dst[m][k] = *(const LAS bf16x8*)(lds + PG8_SA(b, h) + aoff + m * 2048 + k * 1024); } while (0)
; #define PG8_LDB(dst, b, h) do { _Pragma("unroll") for (int n = 0; n < 2; ++n) _Pragma("unroll") for (int k = 0; k < 2; ++k) dst[n][k] = *(const LAS bf16x8*)(lds + PG8_SB(b, h) + boff + n * 2048 + k * 1024); } while (0)
; #define PG8_MMA(ai, bj, At, Bt) do { __builtin_amdgcn_s_setprio(1); _Pragma("unroll") for (int m = 0; m < 4; ++m) _Pragma("unroll") for (int n = 0; n < 2; ++n) _Pragma("unroll") for (int k = 0; k < 2; ++k) \
;         acc[ai][bj][m][n] = __builtin_amdgcn_mfma_f32_16x16x32_bf16(Bt[n][k], At[m][k], acc[ai][bj][m][n], 0, 0, 0); __builtin_amdgcn_s_setprio(0); } while (0)
; #define PG8_WAIT_V(n) asm volatile("s_waitcnt vmcnt(" #n ")" ::: "memory")
; #define PG8_WAIT_L(n) asm volatile("s_waitcnt lgkmcnt(" #n ")" ::: "memory")
; #define PG8_BAR __builtin_amdgcn_s_barrier()
; #define PG8_SCHED __builtin_amdgcn_sched_barrier(0)
; template <class Epi, class Sched, bool ALIGN_EPI = true, bool SP2 = true>
; __device__ __forceinline__ void gemm_phase(LAS unsigned char* lds, const Gemm g, const Sched& S, const Epi& E) {
;     ...
;             PG8_WAIT_V(8); PG8_WAIT_L(0); PG8_BAR; PG8_MMA(1, 0, At, B0); PG8_MMA(1, 1, At, B1); PG8_BAR; PG8_SCHED;
;             PG8_LDB(B0, 1, 0); PG8_LDB(B1, 1, 1); PG8_SCHED; PG8_LDA(At, 1, 0); PG8_STAGE(PG8_SA(0, 1), a2 + hstep, voffA);
;             PG8_WAIT_V(8); PG8_WAIT_L(0); PG8_BAR; PG8_MMA(0, 0, At, B0); PG8_MMA(0, 1, At, B1); PG8_BAR; PG8_SCHED;
	v_mfma_f32_16x16x32_bf16 v[62:65], v[140:143], v[198:201], v[62:65]
	v_mfma_f32_16x16x32_bf16 v[58:61], v[158:161], v[198:201], v[58:61]
	v_mfma_f32_16x16x32_bf16 v[50:53], v[140:143], v[206:209], v[50:53]
	v_mfma_f32_16x16x32_bf16 v[42:45], v[158:161], v[206:209], v[42:45]
	v_mfma_f32_16x16x32_bf16 v[34:37], v[140:143], v[234:237], v[34:37]
	v_mfma_f32_16x16x32_bf16 v[26:29], v[158:161], v[234:237], v[26:29]
	v_mfma_f32_16x16x32_bf16 v[18:21], v[140:143], v[242:245], v[18:21]
	v_mfma_f32_16x16x32_bf16 v[10:13], v[158:161], v[242:245], v[10:13]
	v_mfma_f32_16x16x32_bf16 v[62:65], v[154:157], v[202:205], v[62:65]
	v_mfma_f32_16x16x32_bf16 v[58:61], v[162:165], v[202:205], v[58:61]
	v_mfma_f32_16x16x32_bf16 v[50:53], v[154:157], v[210:213], v[50:53]
	v_mfma_f32_16x16x32_bf16 v[42:45], v[162:165], v[210:213], v[42:45]
	v_mfma_f32_16x16x32_bf16 v[34:37], v[154:157], v[238:241], v[34:37]
	v_mfma_f32_16x16x32_bf16 v[26:29], v[162:165], v[238:241], v[26:29]
	v_mfma_f32_16x16x32_bf16 v[18:21], v[154:157], v[246:249], v[18:21]
	v_mfma_f32_16x16x32_bf16 v[10:13], v[162:165], v[246:249], v[10:13]
	v_mfma_f32_16x16x32_bf16 v[54:57], v[166:169], v[198:201], v[54:57]
	v_mfma_f32_16x16x32_bf16 v[46:49], v[174:177], v[198:201], v[46:49]
	v_mfma_f32_16x16x32_bf16 v[38:41], v[166:169], v[206:209], v[38:41]
	v_mfma_f32_16x16x32_bf16 v[30:33], v[174:177], v[206:209], v[30:33]
	v_mfma_f32_16x16x32_bf16 v[22:25], v[166:169], v[234:237], v[22:25]
	v_mfma_f32_16x16x32_bf16 v[14:17], v[174:177], v[234:237], v[14:17]
	v_mfma_f32_16x16x32_bf16 v[6:9], v[166:169], v[242:245], v[6:9]
	v_mfma_f32_16x16x32_bf16 v[2:5], v[174:177], v[242:245], v[2:5]
	v_mfma_f32_16x16x32_bf16 v[54:57], v[170:173], v[202:205], v[54:57]
	v_mfma_f32_16x16x32_bf16 v[46:49], v[194:197], v[202:205], v[46:49]
	v_mfma_f32_16x16x32_bf16 v[38:41], v[170:173], v[210:213], v[38:41]
	v_mfma_f32_16x16x32_bf16 v[30:33], v[194:197], v[210:213], v[30:33]
	v_mfma_f32_16x16x32_bf16 v[22:25], v[170:173], v[238:241], v[22:25]
	v_mfma_f32_16x16x32_bf16 v[14:17], v[194:197], v[238:241], v[14:17]
	v_mfma_f32_16x16x32_bf16 v[6:9], v[170:173], v[246:249], v[6:9]
	v_mfma_f32_16x16x32_bf16 v[2:5], v[194:197], v[246:249], v[2:5]
	s_barrier
	s_setprio 0
	s_add_i32 s58, 0, 0x18000
	v_add_u32_e32 v144, s58, v147
	s_add_i32 s59, 0, 0x1c000
	ds_read_b128 v[140:143], v144
	ds_read_b128 v[154:157], v144 offset:1024
	ds_read_b128 v[158:161], v144 offset:2048
	ds_read_b128 v[162:165], v144 offset:3072
	v_add_u32_e32 v144, s59, v147
	ds_read_b128 v[166:169], v144
	ds_read_b128 v[170:173], v144 offset:1024
	ds_read_b128 v[174:177], v144 offset:2048
	ds_read_b128 v[194:197], v144 offset:3072
	s_add_u32 s22, s22, 0x80000
	s_addc_u32 s23, s23, 0
	s_mov_b32 m0, s29
	v_lshl_add_u64 v[250:251], s[22:23], 0, v[134:135]
	ds_read_b128 v[198:201], v153 offset:32768
	ds_read_b128 v[202:205], v153 offset:33792
	ds_read_b128 v[206:209], v153 offset:34816
	ds_read_b128 v[210:213], v153 offset:35840
	ds_read_b128 v[234:237], v153 offset:36864
	ds_read_b128 v[238:241], v153 offset:37888
	ds_read_b128 v[242:245], v153 offset:38912
	ds_read_b128 v[246:249], v153 offset:39936
	global_load_lds_dwordx4 v[250:251], off
	v_lshl_add_u64 v[250:251], s[22:23], 0, v[132:133]
	s_mov_b32 m0, s30
	s_nop 0
	global_load_lds_dwordx4 v[250:251], off
	s_waitcnt vmcnt(8)
	s_waitcnt lgkmcnt(0)
	s_setprio 1
	s_barrier
	v_mfma_f32_16x16x32_bf16 v[126:129], v[140:143], v[198:201], v[126:129]
	v_mfma_f32_16x16x32_bf16 v[122:125], v[158:161], v[198:201], v[122:125]
	v_mfma_f32_16x16x32_bf16 v[114:117], v[140:143], v[206:209], v[114:117]
	v_mfma_f32_16x16x32_bf16 v[106:109], v[158:161], v[206:209], v[106:109]
	v_mfma_f32_16x16x32_bf16 v[98:101], v[140:143], v[234:237], v[98:101]
	v_mfma_f32_16x16x32_bf16 v[90:93], v[158:161], v[234:237], v[90:93]
	v_mfma_f32_16x16x32_bf16 v[82:85], v[140:143], v[242:245], v[82:85]
	v_mfma_f32_16x16x32_bf16 v[74:77], v[158:161], v[242:245], v[74:77]
	v_mfma_f32_16x16x32_bf16 v[126:129], v[154:157], v[202:205], v[126:129]
	v_mfma_f32_16x16x32_bf16 v[122:125], v[162:165], v[202:205], v[122:125]
	v_mfma_f32_16x16x32_bf16 v[114:117], v[154:157], v[210:213], v[114:117]
	v_mfma_f32_16x16x32_bf16 v[106:109], v[162:165], v[210:213], v[106:109]
	v_mfma_f32_16x16x32_bf16 v[98:101], v[154:157], v[238:241], v[98:101]
	v_mfma_f32_16x16x32_bf16 v[90:93], v[162:165], v[238:241], v[90:93]
	v_mfma_f32_16x16x32_bf16 v[82:85], v[154:157], v[246:249], v[82:85]
	v_mfma_f32_16x16x32_bf16 v[74:77], v[162:165], v[246:249], v[74:77]
	v_mfma_f32_16x16x32_bf16 v[118:121], v[166:169], v[198:201], v[118:121]
	v_mfma_f32_16x16x32_bf16 v[110:113], v[174:177], v[198:201], v[110:113]
	v_mfma_f32_16x16x32_bf16 v[102:105], v[166:169], v[206:209], v[102:105]
	v_mfma_f32_16x16x32_bf16 v[94:97], v[174:177], v[206:209], v[94:97]
	v_mfma_f32_16x16x32_bf16 v[86:89], v[166:169], v[234:237], v[86:89]
	v_mfma_f32_16x16x32_bf16 v[78:81], v[174:177], v[234:237], v[78:81]
	v_mfma_f32_16x16x32_bf16 v[70:73], v[166:169], v[242:245], v[70:73]
	v_mfma_f32_16x16x32_bf16 v[66:69], v[174:177], v[242:245], v[66:69]
	v_mfma_f32_16x16x32_bf16 v[118:121], v[170:173], v[202:205], v[118:121]
	v_mfma_f32_16x16x32_bf16 v[110:113], v[194:197], v[202:205], v[110:113]
	v_mfma_f32_16x16x32_bf16 v[102:105], v[170:173], v[210:213], v[102:105]
	v_mfma_f32_16x16x32_bf16 v[94:97], v[194:197], v[210:213], v[94:97]
	v_mfma_f32_16x16x32_bf16 v[86:89], v[170:173], v[238:241], v[86:89]
	v_mfma_f32_16x16x32_bf16 v[78:81], v[194:197], v[238:241], v[78:81]
	v_mfma_f32_16x16x32_bf16 v[70:73], v[170:173], v[246:249], v[70:73]
	v_mfma_f32_16x16x32_bf16 v[66:69], v[194:197], v[246:249], v[66:69]
	s_barrier
; #define PG8_STAGE(bufoff, gbase, voff) do { _Pragma("unroll") for (int _i = 0; _i < 2; ++_i) \
;         __builtin_amdgcn_global_load_lds((const unsigned*)((const char*)(gbase) + (voff)[_i]), (LAS unsigned*)(lds + (bufoff) + ldsw + _i * 8192), 16, 0, 0); } while (0)
; #define PG8_LDA(dst, b, h) do { _Pragma("unroll") for (int m = 0; m < 4; ++m) _Pragma("unroll") for (int k = 0; k < 2; ++k) dst[m][k] = *(const LAS bf16x8*)(lds + PG8_SA(b, h) + aoff + m * 2048 + k * 1024); } while (0)
; #define PG8_MMA(ai, bj, At, Bt) do { __builtin_amdgcn_s_setprio(1); _Pragma("unroll") for (int m = 0; m < 4; ++m) _Pragma("unroll") for (int n = 0; n < 2; ++n) _Pragma("unroll") for (int k = 0; k < 2; ++k) \
;         acc[ai][bj][m][n] = __builtin_amdgcn_mfma_f32_16x16x32_bf16(Bt[n][k], At[m][k], acc[ai][bj][m][n], 0, 0, 0); __builtin_amdgcn_s_setprio(0); } while (0)
; #define PG8_WAIT_V(n) asm volatile("s_waitcnt vmcnt(" #n ")" ::: "memory")
; #define PG8_WAIT_L(n) asm volatile("s_waitcnt lgkmcnt(" #n ")" ::: "memory")
; #define PG8_BAR __builtin_amdgcn_s_barrier()
; #define PG8_SCHED __builtin_amdgcn_sched_barrier(0)
; template <class Epi, class Sched, bool ALIGN_EPI = true, bool SP2 = true>
; __device__ __forceinline__ void gemm_phase(LAS unsigned char* lds, const Gemm g, const Sched& S, const Epi& E) {
;     ...
;             PG8_LDA(At, 1, 1); PG8_STAGE(PG8_SB(1, 0), b3, voffB); PG8_STAGE(PG8_SB(1, 1), b3 + hstep, voffB); PG8_STAGE(PG8_SA(1, 0), a3, voffA);
;             PG8_WAIT_V(8); PG8_WAIT_L(0); PG8_BAR; PG8_MMA(1, 0, At, B0); PG8_MMA(1, 1, At, B1); PG8_BAR; PG8_SCHED;
;     ...
;         if constexpr (ALIGN_EPI) { if (wr == 0) PG8_BAR; }
	s_setprio 0
	s_add_i32 s22, s58, s26
	v_lshl_add_u64 v[150:151], v[150:151], 0, s[92:93]
	s_mov_b32 m0, s22
	ds_read_b128 v[198:201], v153 offset:49152
	ds_read_b128 v[202:205], v153 offset:50176
	ds_read_b128 v[206:209], v153 offset:51200
	ds_read_b128 v[210:213], v153 offset:52224
	ds_read_b128 v[234:237], v153 offset:53248
	ds_read_b128 v[238:241], v153 offset:54272
	ds_read_b128 v[242:245], v153 offset:55296
	ds_read_b128 v[246:249], v153 offset:56320
	global_load_lds_dwordx4 v[150:151], off
	s_add_i32 m0, s22, 0x2000
	s_add_u32 s20, s20, 0x80080
	v_lshl_add_u64 v[150:151], v[178:179], 0, s[92:93]
	s_addc_u32 s21, s21, 0
	s_add_i32 s22, s59, s26
	global_load_lds_dwordx4 v[150:151], off
	v_lshl_add_u64 v[150:151], s[20:21], 0, v[0:1]
	s_mov_b32 m0, s22
	s_nop 0
	global_load_lds_dwordx4 v[150:151], off
	v_lshl_add_u64 v[150:151], s[20:21], 0, v[130:131]
	s_add_i32 m0, s22, 0x2000
	s_nop 0
	global_load_lds_dwordx4 v[150:151], off
	v_lshl_add_u64 v[150:151], v[214:215], 0, s[92:93]
	s_mov_b32 m0, s31
	s_nop 0
	global_load_lds_dwordx4 v[150:151], off
	v_lshl_add_u64 v[150:151], v[224:225], 0, s[92:93]
	s_mov_b32 m0, s34
	s_nop 0
	global_load_lds_dwordx4 v[150:151], off
	s_waitcnt vmcnt(8)
	s_waitcnt lgkmcnt(0)
	s_setprio 1
	s_barrier
	v_mfma_f32_16x16x32_bf16 v[62:65], v[140:143], v[198:201], v[62:65]
	v_mfma_f32_16x16x32_bf16 v[58:61], v[158:161], v[198:201], v[58:61]
	v_mfma_f32_16x16x32_bf16 v[50:53], v[140:143], v[206:209], v[50:53]
	v_mfma_f32_16x16x32_bf16 v[42:45], v[158:161], v[206:209], v[42:45]
	v_mfma_f32_16x16x32_bf16 v[34:37], v[140:143], v[234:237], v[34:37]
	v_mfma_f32_16x16x32_bf16 v[26:29], v[158:161], v[234:237], v[26:29]
	v_mfma_f32_16x16x32_bf16 v[18:21], v[140:143], v[242:245], v[18:21]
	v_mfma_f32_16x16x32_bf16 v[10:13], v[158:161], v[242:245], v[10:13]
	v_mfma_f32_16x16x32_bf16 v[62:65], v[154:157], v[202:205], v[62:65]
	v_mfma_f32_16x16x32_bf16 v[58:61], v[162:165], v[202:205], v[58:61]
	v_mfma_f32_16x16x32_bf16 v[50:53], v[154:157], v[210:213], v[50:53]
	v_mfma_f32_16x16x32_bf16 v[42:45], v[162:165], v[210:213], v[42:45]
	v_mfma_f32_16x16x32_bf16 v[34:37], v[154:157], v[238:241], v[34:37]
	v_mfma_f32_16x16x32_bf16 v[26:29], v[162:165], v[238:241], v[26:29]
	v_mfma_f32_16x16x32_bf16 v[18:21], v[154:157], v[246:249], v[18:21]
	v_mfma_f32_16x16x32_bf16 v[10:13], v[162:165], v[246:249], v[10:13]
	v_mfma_f32_16x16x32_bf16 v[54:57], v[166:169], v[198:201], v[54:57]
	v_mfma_f32_16x16x32_bf16 v[46:49], v[174:177], v[198:201], v[46:49]
	v_mfma_f32_16x16x32_bf16 v[38:41], v[166:169], v[206:209], v[38:41]
	v_mfma_f32_16x16x32_bf16 v[30:33], v[174:177], v[206:209], v[30:33]
	v_mfma_f32_16x16x32_bf16 v[22:25], v[166:169], v[234:237], v[22:25]
	v_mfma_f32_16x16x32_bf16 v[14:17], v[174:177], v[234:237], v[14:17]
	v_mfma_f32_16x16x32_bf16 v[6:9], v[166:169], v[242:245], v[6:9]
	v_mfma_f32_16x16x32_bf16 v[2:5], v[174:177], v[242:245], v[2:5]
	v_mfma_f32_16x16x32_bf16 v[54:57], v[170:173], v[202:205], v[54:57]
	v_mfma_f32_16x16x32_bf16 v[46:49], v[194:197], v[202:205], v[46:49]
	v_mfma_f32_16x16x32_bf16 v[38:41], v[170:173], v[210:213], v[38:41]
	v_mfma_f32_16x16x32_bf16 v[30:33], v[194:197], v[210:213], v[30:33]
	v_mfma_f32_16x16x32_bf16 v[22:25], v[170:173], v[238:241], v[22:25]
	v_mfma_f32_16x16x32_bf16 v[14:17], v[194:197], v[238:241], v[14:17]
	v_mfma_f32_16x16x32_bf16 v[6:9], v[170:173], v[246:249], v[6:9]
	v_mfma_f32_16x16x32_bf16 v[2:5], v[194:197], v[246:249], v[2:5]
	s_barrier
	s_setprio 0
	s_add_i32 s74, s74, 2
	s_add_u32 s16, s16, 0x100
	s_addc_u32 s17, s17, 0
	s_add_u32 s72, s72, 0x100
	s_addc_u32 s73, s73, 0
	s_cmp_gt_u32 s74, 29
	s_cbranch_scc0 .LBB0_306
	s_and_b64 vcc, exec, s[4:5]
	s_cbranch_vccz .LBB0_309
	s_barrier

; #define PG8_STAGE(bufoff, gbase, voff) do { _Pragma("unroll") for (int _i = 0; _i < 2; ++_i) \
;         __builtin_amdgcn_global_load_lds((const unsigned*)((const char*)(gbase) + (voff)[_i]), (LAS unsigned*)(lds + (bufoff) + ldsw + _i * 8192), 16, 0, 0); } while (0)
; #define PG8_LDA(dst, b, h) do { _Pragma("unroll") for (int m = 0; m < 4; ++m) _Pragma("unroll") for (int k = 0; k < 2; ++k) dst[m][k] = *(const LAS bf16x8*)(lds + PG8_SA(b, h) + aoff + m * 2048 + k * 1024); } while (0)
; #define PG8_LDB(dst, b, h) do { _Pragma("unroll") for (int n = 0; n < 2; ++n) _Pragma("unroll") for (int k = 0; k < 2; ++k) dst[n][k] = *(const LAS bf16x8*)(lds + PG8_SB(b, h) + boff + n * 2048 + k * 1024); } while (0)
; #define PG8_MMA(ai, bj, At, Bt) do { __builtin_amdgcn_s_setprio(1); _Pragma("unroll") for (int m = 0; m < 4; ++m) _Pragma("unroll") for (int n = 0; n < 2; ++n) _Pragma("unroll") for (int k = 0; k < 2; ++k) \
;         acc[ai][bj][m][n] = __builtin_amdgcn_mfma_f32_16x16x32_bf16(Bt[n][k], At[m][k], acc[ai][bj][m][n], 0, 0, 0); __builtin_amdgcn_s_setprio(0); } while (0)
; #define PG8_WAIT_V(n) asm volatile("s_waitcnt vmcnt(" #n ")" ::: "memory")
; #define PG8_WAIT_L(n) asm volatile("s_waitcnt lgkmcnt(" #n ")" ::: "memory")
; #define PG8_BAR __builtin_amdgcn_s_barrier()
; #define PG8_SCHED __builtin_amdgcn_sched_barrier(0)
; template <class Epi, class Sched, bool ALIGN_EPI = true, bool SP2 = true>
; __device__ __forceinline__ void gemm_phase(LAS unsigned char* lds, const Gemm g, const Sched& S, const Epi& E) {
;     ...
;         for (int t = 0; t < nt; t += 2) {
;             const bool last = (t == nt - 2);
;             const char* a1 = cA + (size_t)(t + 1) * kstep;
;             const char* a2 = last ? nA : cA + (size_t)(t + 2) * kstep; const char* b2 = last ? nB : cB + (size_t)(t + 2) * kstep;
;             const char* a3 = a2 + kstep; const char* b3 = b2 + kstep;
;             if constexpr (SP2) {
;             PG8_LDB(B0, 0, 0); PG8_LDB(B1, 0, 1); PG8_SCHED; PG8_LDA(At, 0, 0); PG8_STAGE(PG8_SA(1, 1), a1 + hstep, voffA);
;             PG8_WAIT_V(8); PG8_WAIT_L(0); PG8_BAR; PG8_MMA(0, 0, At, B0); PG8_MMA(0, 1, At, B1); PG8_BAR; PG8_SCHED;
;             PG8_LDA(At, 0, 1); PG8_STAGE(PG8_SB(0, 0), b2, voffB); PG8_STAGE(PG8_SB(0, 1), b2 + hstep, voffB); PG8_STAGE(PG8_SA(0, 0), a2, voffA);
.LBB0_617:
	s_add_u32 s6, s4, 0xfffc0080
	s_addc_u32 s7, s5, -1
	s_add_i32 s72, 0, 0x10000
	s_cmp_eq_u32 s59, 12
	s_cselect_b32 s9, s15, s7
	s_cselect_b32 s8, s21, s6
	v_add_u32_e32 v0, s72, v234
	s_cselect_b32 s7, s19, s58
	s_cselect_b32 s6, s56, s57
	s_add_i32 s77, 0, 0x14000
	ds_read_b128 v[132:135], v0
	ds_read_b128 v[136:139], v0 offset:1024
	ds_read_b128 v[140:143], v0 offset:2048
	ds_read_b128 v[144:147], v0 offset:3072
	v_add_u32_e32 v0, s77, v234
	ds_read_b128 v[148:151], v0
	ds_read_b128 v[152:155], v0 offset:1024
	ds_read_b128 v[156:159], v0 offset:2048
	ds_read_b128 v[160:163], v0 offset:3072
	v_lshl_add_u64 v[2:3], s[4:5], 0, v[202:203]
	s_add_i32 m0, s29, 0xc000
	ds_read_b128 v[164:167], v236
	ds_read_b128 v[168:171], v236 offset:1024
	ds_read_b128 v[172:175], v236 offset:2048
	ds_read_b128 v[176:179], v236 offset:3072
	ds_read_b128 v[206:209], v236 offset:4096
	ds_read_b128 v[210:213], v236 offset:5120
	ds_read_b128 v[238:241], v236 offset:6144
	ds_read_b128 v[242:245], v236 offset:7168
	global_load_lds_dwordx4 v[2:3], off
	v_lshl_add_u64 v[2:3], s[4:5], 0, v[204:205]
	s_add_i32 m0, s29, 0xe000
	s_nop 0
	global_load_lds_dwordx4 v[2:3], off
	s_waitcnt vmcnt(8)
	s_waitcnt lgkmcnt(0)
	s_setprio 1
	s_barrier
	v_mfma_f32_16x16x32_bf16 v[128:131], v[132:135], v[164:167], v[128:131]
	v_mfma_f32_16x16x32_bf16 v[124:127], v[140:143], v[164:167], v[124:127]
	v_mfma_f32_16x16x32_bf16 v[120:123], v[132:135], v[172:175], v[120:123]
	v_mfma_f32_16x16x32_bf16 v[116:119], v[140:143], v[172:175], v[116:119]
	v_mfma_f32_16x16x32_bf16 v[112:115], v[132:135], v[206:209], v[112:115]
	v_mfma_f32_16x16x32_bf16 v[108:111], v[140:143], v[206:209], v[108:111]
	v_mfma_f32_16x16x32_bf16 v[104:107], v[132:135], v[238:241], v[104:107]
	v_mfma_f32_16x16x32_bf16 v[100:103], v[140:143], v[238:241], v[100:103]
	v_mfma_f32_16x16x32_bf16 v[128:131], v[136:139], v[168:171], v[128:131]
	v_mfma_f32_16x16x32_bf16 v[124:127], v[144:147], v[168:171], v[124:127]
	v_mfma_f32_16x16x32_bf16 v[120:123], v[136:139], v[176:179], v[120:123]
	v_mfma_f32_16x16x32_bf16 v[116:119], v[144:147], v[176:179], v[116:119]
	v_mfma_f32_16x16x32_bf16 v[112:115], v[136:139], v[210:213], v[112:115]
	v_mfma_f32_16x16x32_bf16 v[108:111], v[144:147], v[210:213], v[108:111]
	v_mfma_f32_16x16x32_bf16 v[104:107], v[136:139], v[242:245], v[104:107]
	v_mfma_f32_16x16x32_bf16 v[100:103], v[144:147], v[242:245], v[100:103]
	v_mfma_f32_16x16x32_bf16 v[96:99], v[148:151], v[164:167], v[96:99]
	v_mfma_f32_16x16x32_bf16 v[92:95], v[156:159], v[164:167], v[92:95]
	v_mfma_f32_16x16x32_bf16 v[88:91], v[148:151], v[172:175], v[88:91]
	v_mfma_f32_16x16x32_bf16 v[84:87], v[156:159], v[172:175], v[84:87]
	v_mfma_f32_16x16x32_bf16 v[80:83], v[148:151], v[206:209], v[80:83]
	v_mfma_f32_16x16x32_bf16 v[76:79], v[156:159], v[206:209], v[76:79]
	v_mfma_f32_16x16x32_bf16 v[72:75], v[148:151], v[238:241], v[72:75]
	v_mfma_f32_16x16x32_bf16 v[68:71], v[156:159], v[238:241], v[68:71]
	v_mfma_f32_16x16x32_bf16 v[96:99], v[152:155], v[168:171], v[96:99]
	v_mfma_f32_16x16x32_bf16 v[92:95], v[160:163], v[168:171], v[92:95]
	v_mfma_f32_16x16x32_bf16 v[88:91], v[152:155], v[176:179], v[88:91]
	v_mfma_f32_16x16x32_bf16 v[84:87], v[160:163], v[176:179], v[84:87]
	v_mfma_f32_16x16x32_bf16 v[80:83], v[152:155], v[210:213], v[80:83]
	v_mfma_f32_16x16x32_bf16 v[76:79], v[160:163], v[210:213], v[76:79]
	v_mfma_f32_16x16x32_bf16 v[72:75], v[152:155], v[242:245], v[72:75]
	v_mfma_f32_16x16x32_bf16 v[68:71], v[160:163], v[242:245], v[68:71]
	s_barrier
	s_setprio 0
	s_add_i32 s72, s72, s28
	v_lshl_add_u64 v[214:215], s[6:7], 0, v[198:199]
	s_mov_b32 m0, s72
	ds_read_b128 v[164:167], v236 offset:16384
	ds_read_b128 v[168:171], v236 offset:17408
	ds_read_b128 v[172:175], v236 offset:18432
	ds_read_b128 v[176:179], v236 offset:19456
	ds_read_b128 v[206:209], v236 offset:20480
	ds_read_b128 v[210:213], v236 offset:21504
	ds_read_b128 v[238:241], v236 offset:22528
	ds_read_b128 v[242:245], v236 offset:23552
	global_load_lds_dwordx4 v[214:215], off
	s_add_i32 m0, s72, 0x2000
	s_add_u32 s72, s6, 0x40000
	v_lshl_add_u64 v[224:225], s[6:7], 0, v[194:195]
	s_addc_u32 s73, s7, 0
	s_add_i32 s77, s77, s28
	global_load_lds_dwordx4 v[224:225], off
	v_lshl_add_u64 v[2:3], s[72:73], 0, v[198:199]
	s_mov_b32 m0, s77
	v_lshl_add_u64 v[246:247], s[8:9], 0, v[200:201]
	global_load_lds_dwordx4 v[2:3], off
	v_lshl_add_u64 v[2:3], s[72:73], 0, v[194:195]
	s_add_i32 m0, s77, 0x2000
	v_lshl_add_u64 v[248:249], s[8:9], 0, v[196:197]
	global_load_lds_dwordx4 v[2:3], off
	s_mov_b32 m0, s29
	s_nop 0
	global_load_lds_dwordx4 v[246:247], off
	s_mov_b32 m0, s30
	s_nop 0
	global_load_lds_dwordx4 v[248:249], off
	s_waitcnt vmcnt(8)
	s_waitcnt lgkmcnt(0)
	s_setprio 1
	s_barrier
; #define PG8_STAGE(bufoff, gbase, voff) do { _Pragma("unroll") for (int _i = 0; _i < 2; ++_i) \
;         __builtin_amdgcn_global_load_lds((const unsigned*)((const char*)(gbase) + (voff)[_i]), (LAS unsigned*)(lds + (bufoff) + ldsw + _i * 8192), 16, 0, 0); } while (0)
; #define PG8_LDA(dst, b, h) do { _Pragma("unroll") for (int m = 0; m < 4; ++m) _Pragma("unroll") for (int k = 0; k < 2; ++k) dst[m][k] = *(const LAS bf16x8*)(lds + PG8_SA(b, h) + aoff + m * 2048 + k * 1024); } while (0)
; #define PG8_LDB(dst, b, h) do { _Pragma("unroll") for (int n = 0; n < 2; ++n) _Pragma("unroll") for (int k = 0; k < 2; ++k) dst[n][k] = *(const LAS bf16x8*)(lds + PG8_SB(b, h) + boff + n * 2048 + k * 1024); } while (0)
; #define PG8_MMA(ai, bj, At, Bt) do { __builtin_amdgcn_s_setprio(1); _Pragma("unroll") for (int m = 0; m < 4; ++m) _Pragma("unroll") for (int n = 0; n < 2; ++n) _Pragma("unroll") for (int k = 0; k < 2; ++k) \
;         acc[ai][bj][m][n] = __builtin_amdgcn_mfma_f32_16x16x32_bf16(Bt[n][k], At[m][k], acc[ai][bj][m][n], 0, 0, 0); __builtin_amdgcn_s_setprio(0); } while (0)
; #define PG8_WAIT_V(n) asm volatile("s_waitcnt vmcnt(" #n ")" ::: "memory")
; #define PG8_WAIT_L(n) asm volatile("s_waitcnt lgkmcnt(" #n ")" ::: "memory")
; #define PG8_BAR __builtin_amdgcn_s_barrier()
; #define PG8_SCHED __builtin_amdgcn_sched_barrier(0)
; template <class Epi, class Sched, bool ALIGN_EPI = true, bool SP2 = true>
; __device__ __forceinline__ void gemm_phase(LAS unsigned char* lds, const Gemm g, const Sched& S, const Epi& E) {
;     ...
;             PG8_WAIT_V(8); PG8_WAIT_L(0); PG8_BAR; PG8_MMA(1, 0, At, B0); PG8_MMA(1, 1, At, B1); PG8_BAR; PG8_SCHED;
;             PG8_LDB(B0, 1, 0); PG8_LDB(B1, 1, 1); PG8_SCHED; PG8_LDA(At, 1, 0); PG8_STAGE(PG8_SA(0, 1), a2 + hstep, voffA);
;             PG8_WAIT_V(8); PG8_WAIT_L(0); PG8_BAR; PG8_MMA(0, 0, At, B0); PG8_MMA(0, 1, At, B1); PG8_BAR; PG8_SCHED;
	v_mfma_f32_16x16x32_bf16 v[64:67], v[132:135], v[164:167], v[64:67]
	v_mfma_f32_16x16x32_bf16 v[60:63], v[140:143], v[164:167], v[60:63]
	v_mfma_f32_16x16x32_bf16 v[56:59], v[132:135], v[172:175], v[56:59]
	v_mfma_f32_16x16x32_bf16 v[52:55], v[140:143], v[172:175], v[52:55]
	v_mfma_f32_16x16x32_bf16 v[48:51], v[132:135], v[206:209], v[48:51]
	v_mfma_f32_16x16x32_bf16 v[44:47], v[140:143], v[206:209], v[44:47]
	v_mfma_f32_16x16x32_bf16 v[40:43], v[132:135], v[238:241], v[40:43]
	v_mfma_f32_16x16x32_bf16 v[36:39], v[140:143], v[238:241], v[36:39]
	v_mfma_f32_16x16x32_bf16 v[64:67], v[136:139], v[168:171], v[64:67]
	v_mfma_f32_16x16x32_bf16 v[60:63], v[144:147], v[168:171], v[60:63]
	v_mfma_f32_16x16x32_bf16 v[56:59], v[136:139], v[176:179], v[56:59]
	v_mfma_f32_16x16x32_bf16 v[52:55], v[144:147], v[176:179], v[52:55]
	v_mfma_f32_16x16x32_bf16 v[48:51], v[136:139], v[210:213], v[48:51]
	v_mfma_f32_16x16x32_bf16 v[44:47], v[144:147], v[210:213], v[44:47]
	v_mfma_f32_16x16x32_bf16 v[40:43], v[136:139], v[242:245], v[40:43]
	v_mfma_f32_16x16x32_bf16 v[36:39], v[144:147], v[242:245], v[36:39]
	v_mfma_f32_16x16x32_bf16 v[32:35], v[148:151], v[164:167], v[32:35]
	v_mfma_f32_16x16x32_bf16 v[28:31], v[156:159], v[164:167], v[28:31]
	v_mfma_f32_16x16x32_bf16 v[24:27], v[148:151], v[172:175], v[24:27]
	v_mfma_f32_16x16x32_bf16 v[20:23], v[156:159], v[172:175], v[20:23]
	v_mfma_f32_16x16x32_bf16 v[16:19], v[148:151], v[206:209], v[16:19]
	v_mfma_f32_16x16x32_bf16 v[12:15], v[156:159], v[206:209], v[12:15]
	v_mfma_f32_16x16x32_bf16 v[8:11], v[148:151], v[238:241], v[8:11]
	v_mfma_f32_16x16x32_bf16 v[2:5], v[156:159], v[238:241], v[4:7]
	v_mfma_f32_16x16x32_bf16 v[32:35], v[152:155], v[168:171], v[32:35]
	v_mfma_f32_16x16x32_bf16 v[28:31], v[160:163], v[168:171], v[28:31]
	v_mfma_f32_16x16x32_bf16 v[24:27], v[152:155], v[176:179], v[24:27]
	v_mfma_f32_16x16x32_bf16 v[20:23], v[160:163], v[176:179], v[20:23]
	v_mfma_f32_16x16x32_bf16 v[16:19], v[152:155], v[210:213], v[16:19]
	v_mfma_f32_16x16x32_bf16 v[12:15], v[160:163], v[210:213], v[12:15]
	v_mfma_f32_16x16x32_bf16 v[8:11], v[152:155], v[242:245], v[8:11]
	v_mfma_f32_16x16x32_bf16 v[2:5], v[160:163], v[242:245], v[2:5]
	s_barrier
	s_setprio 0
	s_add_i32 s72, 0, 0x18000
	v_add_u32_e32 v0, s72, v234
	s_add_i32 s73, 0, 0x1c000
	ds_read_b128 v[132:135], v0
	ds_read_b128 v[136:139], v0 offset:1024
	ds_read_b128 v[140:143], v0 offset:2048
	ds_read_b128 v[144:147], v0 offset:3072
	v_add_u32_e32 v0, s73, v234
	ds_read_b128 v[148:151], v0
	ds_read_b128 v[152:155], v0 offset:1024
	ds_read_b128 v[156:159], v0 offset:2048
	ds_read_b128 v[160:163], v0 offset:3072
	s_add_u32 s8, s8, 0x40000
	s_addc_u32 s9, s9, 0
	s_mov_b32 m0, s31
	v_lshl_add_u64 v[6:7], s[8:9], 0, v[200:201]
	ds_read_b128 v[164:167], v236 offset:32768
	ds_read_b128 v[168:171], v236 offset:33792
	ds_read_b128 v[172:175], v236 offset:34816
	ds_read_b128 v[176:179], v236 offset:35840
	ds_read_b128 v[206:209], v236 offset:36864
	ds_read_b128 v[210:213], v236 offset:37888
	ds_read_b128 v[238:241], v236 offset:38912
	ds_read_b128 v[242:245], v236 offset:39936
	global_load_lds_dwordx4 v[6:7], off
	v_lshl_add_u64 v[6:7], s[8:9], 0, v[196:197]
	s_mov_b32 m0, s34
	s_nop 0
	global_load_lds_dwordx4 v[6:7], off
	s_waitcnt vmcnt(8)
	s_waitcnt lgkmcnt(0)
	s_setprio 1
	s_barrier
	v_mfma_f32_16x16x32_bf16 v[128:131], v[132:135], v[164:167], v[128:131]
	v_mfma_f32_16x16x32_bf16 v[124:127], v[140:143], v[164:167], v[124:127]
	v_mfma_f32_16x16x32_bf16 v[120:123], v[132:135], v[172:175], v[120:123]
	v_mfma_f32_16x16x32_bf16 v[116:119], v[140:143], v[172:175], v[116:119]
	v_mfma_f32_16x16x32_bf16 v[112:115], v[132:135], v[206:209], v[112:115]
	v_mfma_f32_16x16x32_bf16 v[108:111], v[140:143], v[206:209], v[108:111]
	v_mfma_f32_16x16x32_bf16 v[104:107], v[132:135], v[238:241], v[104:107]
	v_mfma_f32_16x16x32_bf16 v[100:103], v[140:143], v[238:241], v[100:103]
	v_mfma_f32_16x16x32_bf16 v[128:131], v[136:139], v[168:171], v[128:131]
	v_mfma_f32_16x16x32_bf16 v[124:127], v[144:147], v[168:171], v[124:127]
	v_mfma_f32_16x16x32_bf16 v[120:123], v[136:139], v[176:179], v[120:123]
	v_mfma_f32_16x16x32_bf16 v[116:119], v[144:147], v[176:179], v[116:119]
	v_mfma_f32_16x16x32_bf16 v[112:115], v[136:139], v[210:213], v[112:115]
	v_mfma_f32_16x16x32_bf16 v[108:111], v[144:147], v[210:213], v[108:111]
	v_mfma_f32_16x16x32_bf16 v[104:107], v[136:139], v[242:245], v[104:107]
	v_mfma_f32_16x16x32_bf16 v[100:103], v[144:147], v[242:245], v[100:103]
	v_mfma_f32_16x16x32_bf16 v[96:99], v[148:151], v[164:167], v[96:99]
	v_mfma_f32_16x16x32_bf16 v[92:95], v[156:159], v[164:167], v[92:95]
	v_mfma_f32_16x16x32_bf16 v[88:91], v[148:151], v[172:175], v[88:91]
	v_mfma_f32_16x16x32_bf16 v[84:87], v[156:159], v[172:175], v[84:87]
	v_mfma_f32_16x16x32_bf16 v[80:83], v[148:151], v[206:209], v[80:83]
	v_mfma_f32_16x16x32_bf16 v[76:79], v[156:159], v[206:209], v[76:79]
	v_mfma_f32_16x16x32_bf16 v[72:75], v[148:151], v[238:241], v[72:75]
	v_mfma_f32_16x16x32_bf16 v[68:71], v[156:159], v[238:241], v[68:71]
	v_mfma_f32_16x16x32_bf16 v[96:99], v[152:155], v[168:171], v[96:99]
	v_mfma_f32_16x16x32_bf16 v[92:95], v[160:163], v[168:171], v[92:95]
	v_mfma_f32_16x16x32_bf16 v[88:91], v[152:155], v[176:179], v[88:91]
	v_mfma_f32_16x16x32_bf16 v[84:87], v[160:163], v[176:179], v[84:87]
	v_mfma_f32_16x16x32_bf16 v[80:83], v[152:155], v[210:213], v[80:83]
	v_mfma_f32_16x16x32_bf16 v[76:79], v[160:163], v[210:213], v[76:79]
	v_mfma_f32_16x16x32_bf16 v[72:75], v[152:155], v[242:245], v[72:75]
	v_mfma_f32_16x16x32_bf16 v[68:71], v[160:163], v[242:245], v[68:71]
	s_barrier
; #define PG8_STAGE(bufoff, gbase, voff) do { _Pragma("unroll") for (int _i = 0; _i < 2; ++_i) \
;         __builtin_amdgcn_global_load_lds((const unsigned*)((const char*)(gbase) + (voff)[_i]), (LAS unsigned*)(lds + (bufoff) + ldsw + _i * 8192), 16, 0, 0); } while (0)
; #define PG8_LDA(dst, b, h) do { _Pragma("unroll") for (int m = 0; m < 4; ++m) _Pragma("unroll") for (int k = 0; k < 2; ++k) dst[m][k] = *(const LAS bf16x8*)(lds + PG8_SA(b, h) + aoff + m * 2048 + k * 1024); } while (0)
; #define PG8_MMA(ai, bj, At, Bt) do { __builtin_amdgcn_s_setprio(1); _Pragma("unroll") for (int m = 0; m < 4; ++m) _Pragma("unroll") for (int n = 0; n < 2; ++n) _Pragma("unroll") for (int k = 0; k < 2; ++k) \
;         acc[ai][bj][m][n] = __builtin_amdgcn_mfma_f32_16x16x32_bf16(Bt[n][k], At[m][k], acc[ai][bj][m][n], 0, 0, 0); __builtin_amdgcn_s_setprio(0); } while (0)
; #define PG8_WAIT_V(n) asm volatile("s_waitcnt vmcnt(" #n ")" ::: "memory")
; #define PG8_WAIT_L(n) asm volatile("s_waitcnt lgkmcnt(" #n ")" ::: "memory")
; #define PG8_BAR __builtin_amdgcn_s_barrier()
; #define PG8_SCHED __builtin_amdgcn_sched_barrier(0)
; template <class Epi, class Sched, bool ALIGN_EPI = true, bool SP2 = true>
; __device__ __forceinline__ void gemm_phase(LAS unsigned char* lds, const Gemm g, const Sched& S, const Epi& E) {
;     ...
;             PG8_LDA(At, 1, 1); PG8_STAGE(PG8_SB(1, 0), b3, voffB); PG8_STAGE(PG8_SB(1, 1), b3 + hstep, voffB); PG8_STAGE(PG8_SA(1, 0), a3, voffA);
;             PG8_WAIT_V(8); PG8_WAIT_L(0); PG8_BAR; PG8_MMA(1, 0, At, B0); PG8_MMA(1, 1, At, B1); PG8_BAR; PG8_SCHED;
;     ...
;         if constexpr (ALIGN_EPI) { if (wr == 0) PG8_BAR; }
	s_setprio 0
	s_add_i32 s8, s72, s28
	v_lshl_add_u64 v[6:7], v[214:215], 0, s[92:93]
	s_mov_b32 m0, s8
	ds_read_b128 v[164:167], v236 offset:49152
	ds_read_b128 v[168:171], v236 offset:50176
	ds_read_b128 v[172:175], v236 offset:51200
	ds_read_b128 v[176:179], v236 offset:52224
	ds_read_b128 v[206:209], v236 offset:53248
	ds_read_b128 v[210:213], v236 offset:54272
	ds_read_b128 v[238:241], v236 offset:55296
	ds_read_b128 v[242:245], v236 offset:56320
	global_load_lds_dwordx4 v[6:7], off
	s_add_i32 m0, s8, 0x2000
	s_add_u32 s6, s6, 0x40080
	v_lshl_add_u64 v[6:7], v[224:225], 0, s[92:93]
	s_addc_u32 s7, s7, 0
	s_add_i32 s8, s73, s28
	global_load_lds_dwordx4 v[6:7], off
	v_lshl_add_u64 v[6:7], s[6:7], 0, v[198:199]
	s_mov_b32 m0, s8
	s_nop 0
	global_load_lds_dwordx4 v[6:7], off
	v_lshl_add_u64 v[6:7], s[6:7], 0, v[194:195]
	s_add_i32 m0, s8, 0x2000
	s_nop 0
	global_load_lds_dwordx4 v[6:7], off
	v_lshl_add_u64 v[6:7], v[246:247], 0, s[92:93]
	s_mov_b32 m0, s71
	s_nop 0
	global_load_lds_dwordx4 v[6:7], off
	v_lshl_add_u64 v[6:7], v[248:249], 0, s[92:93]
	s_mov_b32 m0, s74
	s_nop 0
	global_load_lds_dwordx4 v[6:7], off
	s_waitcnt vmcnt(8)
	s_waitcnt lgkmcnt(0)
	s_setprio 1
	s_barrier
	v_mfma_f32_16x16x32_bf16 v[64:67], v[132:135], v[164:167], v[64:67]
	v_mfma_f32_16x16x32_bf16 v[60:63], v[140:143], v[164:167], v[60:63]
	v_mfma_f32_16x16x32_bf16 v[56:59], v[132:135], v[172:175], v[56:59]
	v_mfma_f32_16x16x32_bf16 v[52:55], v[140:143], v[172:175], v[52:55]
	v_mfma_f32_16x16x32_bf16 v[48:51], v[132:135], v[206:209], v[48:51]
	v_mfma_f32_16x16x32_bf16 v[44:47], v[140:143], v[206:209], v[44:47]
	v_mfma_f32_16x16x32_bf16 v[40:43], v[132:135], v[238:241], v[40:43]
	v_mfma_f32_16x16x32_bf16 v[36:39], v[140:143], v[238:241], v[36:39]
	v_mfma_f32_16x16x32_bf16 v[64:67], v[136:139], v[168:171], v[64:67]
	v_mfma_f32_16x16x32_bf16 v[60:63], v[144:147], v[168:171], v[60:63]
	v_mfma_f32_16x16x32_bf16 v[56:59], v[136:139], v[176:179], v[56:59]
	v_mfma_f32_16x16x32_bf16 v[52:55], v[144:147], v[176:179], v[52:55]
	v_mfma_f32_16x16x32_bf16 v[48:51], v[136:139], v[210:213], v[48:51]
	v_mfma_f32_16x16x32_bf16 v[44:47], v[144:147], v[210:213], v[44:47]
	v_mfma_f32_16x16x32_bf16 v[40:43], v[136:139], v[242:245], v[40:43]
	v_mfma_f32_16x16x32_bf16 v[36:39], v[144:147], v[242:245], v[36:39]
	v_mfma_f32_16x16x32_bf16 v[32:35], v[148:151], v[164:167], v[32:35]
	v_mfma_f32_16x16x32_bf16 v[28:31], v[156:159], v[164:167], v[28:31]
	v_mfma_f32_16x16x32_bf16 v[24:27], v[148:151], v[172:175], v[24:27]
	v_mfma_f32_16x16x32_bf16 v[20:23], v[156:159], v[172:175], v[20:23]
	v_mfma_f32_16x16x32_bf16 v[16:19], v[148:151], v[206:209], v[16:19]
	v_mfma_f32_16x16x32_bf16 v[12:15], v[156:159], v[206:209], v[12:15]
	v_mfma_f32_16x16x32_bf16 v[6:9], v[148:151], v[238:241], v[8:11]
	v_mfma_f32_16x16x32_bf16 v[2:5], v[156:159], v[238:241], v[2:5]
	v_mfma_f32_16x16x32_bf16 v[32:35], v[152:155], v[168:171], v[32:35]
	v_mfma_f32_16x16x32_bf16 v[28:31], v[160:163], v[168:171], v[28:31]
	v_mfma_f32_16x16x32_bf16 v[24:27], v[152:155], v[176:179], v[24:27]
	v_mfma_f32_16x16x32_bf16 v[20:23], v[160:163], v[176:179], v[20:23]
	v_mfma_f32_16x16x32_bf16 v[16:19], v[152:155], v[210:213], v[16:19]
	v_mfma_f32_16x16x32_bf16 v[12:15], v[160:163], v[210:213], v[12:15]
	v_mfma_f32_16x16x32_bf16 v[8:11], v[152:155], v[242:245], v[6:9]
	v_mfma_f32_16x16x32_bf16 v[4:7], v[160:163], v[242:245], v[2:5]
	s_barrier
	s_setprio 0
	s_add_i32 s59, s59, 2
	s_add_u32 s4, s4, 0x100
	s_addc_u32 s5, s5, 0
	s_add_u32 s57, s57, 0x100
	s_addc_u32 s58, s58, 0
	s_cmp_gt_u32 s59, 13
	s_cbranch_scc0 .LBB0_617
	s_and_b64 vcc, exec, s[16:17]
	s_cbranch_vccz .LBB0_620
	s_barrier

; #define PG8_STAGE(bufoff, gbase, voff) do { _Pragma("unroll") for (int _i = 0; _i < 2; ++_i) \
;         __builtin_amdgcn_global_load_lds((const unsigned*)((const char*)(gbase) + (voff)[_i]), (LAS unsigned*)(lds + (bufoff) + ldsw + _i * 8192), 16, 0, 0); } while (0)
; #define PG8_LDA(dst, b, h) do { _Pragma("unroll") for (int m = 0; m < 4; ++m) _Pragma("unroll") for (int k = 0; k < 2; ++k) dst[m][k] = *(const LAS bf16x8*)(lds + PG8_SA(b, h) + aoff + m * 2048 + k * 1024); } while (0)
; #define PG8_LDB(dst, b, h) do { _Pragma("unroll") for (int n = 0; n < 2; ++n) _Pragma("unroll") for (int k = 0; k < 2; ++k) dst[n][k] = *(const LAS bf16x8*)(lds + PG8_SB(b, h) + boff + n * 2048 + k * 1024); } while (0)
; #define PG8_MMA(ai, bj, At, Bt) do { __builtin_amdgcn_s_setprio(1); _Pragma("unroll") for (int m = 0; m < 4; ++m) _Pragma("unroll") for (int n = 0; n < 2; ++n) _Pragma("unroll") for (int k = 0; k < 2; ++k) \
;         acc[ai][bj][m][n] = __builtin_amdgcn_mfma_f32_16x16x32_bf16(Bt[n][k], At[m][k], acc[ai][bj][m][n], 0, 0, 0); __builtin_amdgcn_s_setprio(0); } while (0)
; #define PG8_WAIT_V(n) asm volatile("s_waitcnt vmcnt(" #n ")" ::: "memory")
; #define PG8_WAIT_L(n) asm volatile("s_waitcnt lgkmcnt(" #n ")" ::: "memory")
; #define PG8_BAR __builtin_amdgcn_s_barrier()
; #define PG8_SCHED __builtin_amdgcn_sched_barrier(0)
; template <class Epi, class Sched, bool ALIGN_EPI = true, bool SP2 = true>
; __device__ __forceinline__ void gemm_phase(LAS unsigned char* lds, const Gemm g, const Sched& S, const Epi& E) {
;     ...
;         for (int t = 0; t < nt; t += 2) {
;             const bool last = (t == nt - 2);
;             const char* a1 = cA + (size_t)(t + 1) * kstep;
;             const char* a2 = last ? nA : cA + (size_t)(t + 2) * kstep; const char* b2 = last ? nB : cB + (size_t)(t + 2) * kstep;
;             const char* a3 = a2 + kstep; const char* b3 = b2 + kstep;
;             if constexpr (SP2) {
;             PG8_LDB(B0, 0, 0); PG8_LDB(B1, 0, 1); PG8_SCHED; PG8_LDA(At, 0, 0); PG8_STAGE(PG8_SA(1, 1), a1 + hstep, voffA);
;             PG8_WAIT_V(8); PG8_WAIT_L(0); PG8_BAR; PG8_MMA(0, 0, At, B0); PG8_MMA(0, 1, At, B1); PG8_BAR; PG8_SCHED;
;             PG8_LDA(At, 0, 1); PG8_STAGE(PG8_SB(0, 0), b2, voffB); PG8_STAGE(PG8_SB(0, 1), b2 + hstep, voffB); PG8_STAGE(PG8_SA(0, 0), a2, voffA);
.LBB0_787:
	s_add_u32 s22, s20, 0x100
	s_addc_u32 s23, s21, 0
	s_add_i32 s58, 0, 0x10000
	s_cmp_eq_u32 s78, 28
	s_cselect_b32 s27, s15, s23
	s_cselect_b32 s26, s72, s22
	s_cselect_b32 s25, s9, s77
	s_cselect_b32 s24, s73, s76
	s_add_i32 s59, 0, 0x14000
	v_add_u32_e32 v148, s58, v179
	v_add_u32_e32 v164, s59, v179
	ds_read_b128 v[136:139], v148
	ds_read_b128 v[140:143], v148 offset:1024
	ds_read_b128 v[144:147], v148 offset:2048
	ds_read_b128 v[148:151], v148 offset:3072
	ds_read_b128 v[152:155], v164
	ds_read_b128 v[156:159], v164 offset:1024
	ds_read_b128 v[160:163], v164 offset:2048
	ds_read_b128 v[164:167], v164 offset:3072
	v_lshl_add_u64 v[176:177], s[20:21], 0, v[132:133]
	s_add_i32 m0, s31, 0xc000
	ds_read_b128 v[168:171], v194
	ds_read_b128 v[172:175], v194 offset:1024
	ds_read_b128 v[196:199], v194 offset:2048
	ds_read_b128 v[200:203], v194 offset:3072
	ds_read_b128 v[204:207], v194 offset:4096
	ds_read_b128 v[208:211], v194 offset:5120
	ds_read_b128 v[212:215], v194 offset:6144
	ds_read_b128 v[234:237], v194 offset:7168
	global_load_lds_dwordx4 v[176:177], off
	v_lshl_add_u64 v[176:177], s[20:21], 0, v[134:135]
	s_add_i32 m0, s31, 0xe000
	s_nop 0
	global_load_lds_dwordx4 v[176:177], off
	s_waitcnt vmcnt(8)
	s_waitcnt lgkmcnt(0)
	s_setprio 1
	s_barrier
	v_mfma_f32_16x16x32_bf16 v[126:129], v[136:139], v[168:171], v[126:129]
	v_mfma_f32_16x16x32_bf16 v[122:125], v[144:147], v[168:171], v[122:125]
	v_mfma_f32_16x16x32_bf16 v[110:113], v[136:139], v[196:199], v[110:113]
	v_mfma_f32_16x16x32_bf16 v[106:109], v[144:147], v[196:199], v[106:109]
	v_mfma_f32_16x16x32_bf16 v[94:97], v[136:139], v[204:207], v[94:97]
	v_mfma_f32_16x16x32_bf16 v[90:93], v[144:147], v[204:207], v[90:93]
	v_mfma_f32_16x16x32_bf16 v[78:81], v[136:139], v[212:215], v[78:81]
	v_mfma_f32_16x16x32_bf16 v[74:77], v[144:147], v[212:215], v[74:77]
	v_mfma_f32_16x16x32_bf16 v[126:129], v[140:143], v[172:175], v[126:129]
	v_mfma_f32_16x16x32_bf16 v[122:125], v[148:151], v[172:175], v[122:125]
	v_mfma_f32_16x16x32_bf16 v[110:113], v[140:143], v[200:203], v[110:113]
	v_mfma_f32_16x16x32_bf16 v[106:109], v[148:151], v[200:203], v[106:109]
	v_mfma_f32_16x16x32_bf16 v[94:97], v[140:143], v[208:211], v[94:97]
	v_mfma_f32_16x16x32_bf16 v[90:93], v[148:151], v[208:211], v[90:93]
	v_mfma_f32_16x16x32_bf16 v[78:81], v[140:143], v[234:237], v[78:81]
	v_mfma_f32_16x16x32_bf16 v[74:77], v[148:151], v[234:237], v[74:77]
	v_mfma_f32_16x16x32_bf16 v[118:121], v[152:155], v[168:171], v[118:121]
	v_mfma_f32_16x16x32_bf16 v[114:117], v[160:163], v[168:171], v[114:117]
	v_mfma_f32_16x16x32_bf16 v[102:105], v[152:155], v[196:199], v[102:105]
	v_mfma_f32_16x16x32_bf16 v[98:101], v[160:163], v[196:199], v[98:101]
	v_mfma_f32_16x16x32_bf16 v[86:89], v[152:155], v[204:207], v[86:89]
	v_mfma_f32_16x16x32_bf16 v[82:85], v[160:163], v[204:207], v[82:85]
	v_mfma_f32_16x16x32_bf16 v[70:73], v[152:155], v[212:215], v[70:73]
	v_mfma_f32_16x16x32_bf16 v[66:69], v[160:163], v[212:215], v[66:69]
	v_mfma_f32_16x16x32_bf16 v[118:121], v[156:159], v[172:175], v[118:121]
	v_mfma_f32_16x16x32_bf16 v[114:117], v[164:167], v[172:175], v[114:117]
	v_mfma_f32_16x16x32_bf16 v[102:105], v[156:159], v[200:203], v[102:105]
	v_mfma_f32_16x16x32_bf16 v[98:101], v[164:167], v[200:203], v[98:101]
	v_mfma_f32_16x16x32_bf16 v[86:89], v[156:159], v[208:211], v[86:89]
	v_mfma_f32_16x16x32_bf16 v[82:85], v[164:167], v[208:211], v[82:85]
	v_mfma_f32_16x16x32_bf16 v[70:73], v[156:159], v[234:237], v[70:73]
	v_mfma_f32_16x16x32_bf16 v[66:69], v[164:167], v[234:237], v[66:69]
	s_barrier
	s_setprio 0
	s_add_i32 s20, s58, s30
	v_lshl_add_u64 v[176:177], s[24:25], 0, v[0:1]
	s_mov_b32 m0, s20
	ds_read_b128 v[168:171], v194 offset:16384
	ds_read_b128 v[172:175], v194 offset:17408
	ds_read_b128 v[196:199], v194 offset:18432
	ds_read_b128 v[200:203], v194 offset:19456
	ds_read_b128 v[204:207], v194 offset:20480
	ds_read_b128 v[208:211], v194 offset:21504
	ds_read_b128 v[212:215], v194 offset:22528
	ds_read_b128 v[234:237], v194 offset:23552
	global_load_lds_dwordx4 v[176:177], off
	s_add_i32 m0, s20, 0x2000
	s_add_u32 s20, s24, 0x80000
	v_lshl_add_u64 v[224:225], s[24:25], 0, v[130:131]
	s_addc_u32 s21, s25, 0
	s_add_i32 s58, s59, s30
	global_load_lds_dwordx4 v[224:225], off
	v_lshl_add_u64 v[238:239], s[20:21], 0, v[0:1]
	s_mov_b32 m0, s58
	v_lshl_add_u64 v[240:241], s[26:27], 0, v[130:131]
	global_load_lds_dwordx4 v[238:239], off
	v_lshl_add_u64 v[238:239], s[20:21], 0, v[130:131]
	s_add_i32 m0, s58, 0x2000
	s_nop 0
	global_load_lds_dwordx4 v[238:239], off
	v_lshl_add_u64 v[238:239], s[26:27], 0, v[0:1]
	s_mov_b32 m0, s31
	s_nop 0
	global_load_lds_dwordx4 v[238:239], off
	s_mov_b32 m0, s34
	s_nop 0
	global_load_lds_dwordx4 v[240:241], off
	s_waitcnt vmcnt(8)
	s_waitcnt lgkmcnt(0)
	s_setprio 1
	s_barrier
; #define PG8_STAGE(bufoff, gbase, voff) do { _Pragma("unroll") for (int _i = 0; _i < 2; ++_i) \
;         __builtin_amdgcn_global_load_lds((const unsigned*)((const char*)(gbase) + (voff)[_i]), (LAS unsigned*)(lds + (bufoff) + ldsw + _i * 8192), 16, 0, 0); } while (0)
; #define PG8_LDA(dst, b, h) do { _Pragma("unroll") for (int m = 0; m < 4; ++m) _Pragma("unroll") for (int k = 0; k < 2; ++k) dst[m][k] = *(const LAS bf16x8*)(lds + PG8_SA(b, h) + aoff + m * 2048 + k * 1024); } while (0)
; #define PG8_LDB(dst, b, h) do { _Pragma("unroll") for (int n = 0; n < 2; ++n) _Pragma("unroll") for (int k = 0; k < 2; ++k) dst[n][k] = *(const LAS bf16x8*)(lds + PG8_SB(b, h) + boff + n * 2048 + k * 1024); } while (0)
; #define PG8_MMA(ai, bj, At, Bt) do { __builtin_amdgcn_s_setprio(1); _Pragma("unroll") for (int m = 0; m < 4; ++m) _Pragma("unroll") for (int n = 0; n < 2; ++n) _Pragma("unroll") for (int k = 0; k < 2; ++k) \
;         acc[ai][bj][m][n] = __builtin_amdgcn_mfma_f32_16x16x32_bf16(Bt[n][k], At[m][k], acc[ai][bj][m][n], 0, 0, 0); __builtin_amdgcn_s_setprio(0); } while (0)
; #define PG8_WAIT_V(n) asm volatile("s_waitcnt vmcnt(" #n ")" ::: "memory")
; #define PG8_WAIT_L(n) asm volatile("s_waitcnt lgkmcnt(" #n ")" ::: "memory")
; #define PG8_BAR __builtin_amdgcn_s_barrier()
; #define PG8_SCHED __builtin_amdgcn_sched_barrier(0)
; template <class Epi, class Sched, bool ALIGN_EPI = true, bool SP2 = true>
; __device__ __forceinline__ void gemm_phase(LAS unsigned char* lds, const Gemm g, const Sched& S, const Epi& E) {
;     ...
;             PG8_WAIT_V(8); PG8_WAIT_L(0); PG8_BAR; PG8_MMA(1, 0, At, B0); PG8_MMA(1, 1, At, B1); PG8_BAR; PG8_SCHED;
;             PG8_LDB(B0, 1, 0); PG8_LDB(B1, 1, 1); PG8_SCHED; PG8_LDA(At, 1, 0); PG8_STAGE(PG8_SA(0, 1), a2 + hstep, voffA);
;             PG8_WAIT_V(8); PG8_WAIT_L(0); PG8_BAR; PG8_MMA(0, 0, At, B0); PG8_MMA(0, 1, At, B1); PG8_BAR; PG8_SCHED;
	v_mfma_f32_16x16x32_bf16 v[62:65], v[136:139], v[168:171], v[62:65]
	v_mfma_f32_16x16x32_bf16 v[58:61], v[144:147], v[168:171], v[58:61]
	v_mfma_f32_16x16x32_bf16 v[46:49], v[136:139], v[196:199], v[46:49]
	v_mfma_f32_16x16x32_bf16 v[42:45], v[144:147], v[196:199], v[42:45]
	v_mfma_f32_16x16x32_bf16 v[30:33], v[136:139], v[204:207], v[30:33]
	v_mfma_f32_16x16x32_bf16 v[26:29], v[144:147], v[204:207], v[26:29]
	v_mfma_f32_16x16x32_bf16 v[14:17], v[136:139], v[212:215], v[14:17]
	v_mfma_f32_16x16x32_bf16 v[10:13], v[144:147], v[212:215], v[10:13]
	v_mfma_f32_16x16x32_bf16 v[62:65], v[140:143], v[172:175], v[62:65]
	v_mfma_f32_16x16x32_bf16 v[58:61], v[148:151], v[172:175], v[58:61]
	v_mfma_f32_16x16x32_bf16 v[46:49], v[140:143], v[200:203], v[46:49]
	v_mfma_f32_16x16x32_bf16 v[42:45], v[148:151], v[200:203], v[42:45]
	v_mfma_f32_16x16x32_bf16 v[30:33], v[140:143], v[208:211], v[30:33]
	v_mfma_f32_16x16x32_bf16 v[26:29], v[148:151], v[208:211], v[26:29]
	v_mfma_f32_16x16x32_bf16 v[14:17], v[140:143], v[234:237], v[14:17]
	v_mfma_f32_16x16x32_bf16 v[10:13], v[148:151], v[234:237], v[10:13]
	v_mfma_f32_16x16x32_bf16 v[54:57], v[152:155], v[168:171], v[54:57]
	v_mfma_f32_16x16x32_bf16 v[50:53], v[160:163], v[168:171], v[50:53]
	v_mfma_f32_16x16x32_bf16 v[38:41], v[152:155], v[196:199], v[38:41]
	v_mfma_f32_16x16x32_bf16 v[34:37], v[160:163], v[196:199], v[34:37]
	v_mfma_f32_16x16x32_bf16 v[22:25], v[152:155], v[204:207], v[22:25]
	v_mfma_f32_16x16x32_bf16 v[18:21], v[160:163], v[204:207], v[18:21]
	v_mfma_f32_16x16x32_bf16 v[6:9], v[152:155], v[212:215], v[6:9]
	v_mfma_f32_16x16x32_bf16 v[2:5], v[160:163], v[212:215], v[2:5]
	v_mfma_f32_16x16x32_bf16 v[54:57], v[156:159], v[172:175], v[54:57]
	v_mfma_f32_16x16x32_bf16 v[50:53], v[164:167], v[172:175], v[50:53]
	v_mfma_f32_16x16x32_bf16 v[38:41], v[156:159], v[200:203], v[38:41]
	v_mfma_f32_16x16x32_bf16 v[34:37], v[164:167], v[200:203], v[34:37]
	v_mfma_f32_16x16x32_bf16 v[22:25], v[156:159], v[208:211], v[22:25]
	v_mfma_f32_16x16x32_bf16 v[18:21], v[164:167], v[208:211], v[18:21]
	v_mfma_f32_16x16x32_bf16 v[6:9], v[156:159], v[234:237], v[6:9]
	v_mfma_f32_16x16x32_bf16 v[2:5], v[164:167], v[234:237], v[2:5]
	s_barrier
	s_setprio 0
	s_add_i32 s58, 0, 0x18000
	s_add_i32 s59, 0, 0x1c000
	v_add_u32_e32 v148, s58, v179
	v_add_u32_e32 v164, s59, v179
	ds_read_b128 v[136:139], v148
	ds_read_b128 v[140:143], v148 offset:1024
	ds_read_b128 v[144:147], v148 offset:2048
	ds_read_b128 v[148:151], v148 offset:3072
	ds_read_b128 v[152:155], v164
	ds_read_b128 v[156:159], v164 offset:1024
	ds_read_b128 v[160:163], v164 offset:2048
	ds_read_b128 v[164:167], v164 offset:3072
	s_add_u32 s20, s26, 0x80000
	s_addc_u32 s21, s27, 0
	s_mov_b32 m0, s35
	v_lshl_add_u64 v[242:243], s[20:21], 0, v[0:1]
	ds_read_b128 v[168:171], v194 offset:32768
	ds_read_b128 v[172:175], v194 offset:33792
	ds_read_b128 v[196:199], v194 offset:34816
	ds_read_b128 v[200:203], v194 offset:35840
	ds_read_b128 v[204:207], v194 offset:36864
	ds_read_b128 v[208:211], v194 offset:37888
	ds_read_b128 v[212:215], v194 offset:38912
	ds_read_b128 v[234:237], v194 offset:39936
	global_load_lds_dwordx4 v[242:243], off
	v_lshl_add_u64 v[242:243], s[20:21], 0, v[130:131]
	s_mov_b32 m0, s70
	s_nop 0
	global_load_lds_dwordx4 v[242:243], off
	s_waitcnt vmcnt(8)
	s_waitcnt lgkmcnt(0)
	s_setprio 1
	s_barrier
	v_mfma_f32_16x16x32_bf16 v[126:129], v[136:139], v[168:171], v[126:129]
	v_mfma_f32_16x16x32_bf16 v[122:125], v[144:147], v[168:171], v[122:125]
	v_mfma_f32_16x16x32_bf16 v[110:113], v[136:139], v[196:199], v[110:113]
	v_mfma_f32_16x16x32_bf16 v[106:109], v[144:147], v[196:199], v[106:109]
	v_mfma_f32_16x16x32_bf16 v[94:97], v[136:139], v[204:207], v[94:97]
	v_mfma_f32_16x16x32_bf16 v[90:93], v[144:147], v[204:207], v[90:93]
	v_mfma_f32_16x16x32_bf16 v[78:81], v[136:139], v[212:215], v[78:81]
	v_mfma_f32_16x16x32_bf16 v[74:77], v[144:147], v[212:215], v[74:77]
	v_mfma_f32_16x16x32_bf16 v[126:129], v[140:143], v[172:175], v[126:129]
	v_mfma_f32_16x16x32_bf16 v[122:125], v[148:151], v[172:175], v[122:125]
	v_mfma_f32_16x16x32_bf16 v[110:113], v[140:143], v[200:203], v[110:113]
	v_mfma_f32_16x16x32_bf16 v[106:109], v[148:151], v[200:203], v[106:109]
	v_mfma_f32_16x16x32_bf16 v[94:97], v[140:143], v[208:211], v[94:97]
	v_mfma_f32_16x16x32_bf16 v[90:93], v[148:151], v[208:211], v[90:93]
	v_mfma_f32_16x16x32_bf16 v[78:81], v[140:143], v[234:237], v[78:81]
	v_mfma_f32_16x16x32_bf16 v[74:77], v[148:151], v[234:237], v[74:77]
	v_mfma_f32_16x16x32_bf16 v[118:121], v[152:155], v[168:171], v[118:121]
	v_mfma_f32_16x16x32_bf16 v[114:117], v[160:163], v[168:171], v[114:117]
	v_mfma_f32_16x16x32_bf16 v[102:105], v[152:155], v[196:199], v[102:105]
	v_mfma_f32_16x16x32_bf16 v[98:101], v[160:163], v[196:199], v[98:101]
	v_mfma_f32_16x16x32_bf16 v[86:89], v[152:155], v[204:207], v[86:89]
	v_mfma_f32_16x16x32_bf16 v[82:85], v[160:163], v[204:207], v[82:85]
	v_mfma_f32_16x16x32_bf16 v[70:73], v[152:155], v[212:215], v[70:73]
	v_mfma_f32_16x16x32_bf16 v[66:69], v[160:163], v[212:215], v[66:69]
	v_mfma_f32_16x16x32_bf16 v[118:121], v[156:159], v[172:175], v[118:121]
	v_mfma_f32_16x16x32_bf16 v[114:117], v[164:167], v[172:175], v[114:117]
	v_mfma_f32_16x16x32_bf16 v[102:105], v[156:159], v[200:203], v[102:105]
	v_mfma_f32_16x16x32_bf16 v[98:101], v[164:167], v[200:203], v[98:101]
	v_mfma_f32_16x16x32_bf16 v[86:89], v[156:159], v[208:211], v[86:89]
	v_mfma_f32_16x16x32_bf16 v[82:85], v[164:167], v[208:211], v[82:85]
	v_mfma_f32_16x16x32_bf16 v[70:73], v[156:159], v[234:237], v[70:73]
	v_mfma_f32_16x16x32_bf16 v[66:69], v[164:167], v[234:237], v[66:69]
	s_barrier
; #define PG8_STAGE(bufoff, gbase, voff) do { _Pragma("unroll") for (int _i = 0; _i < 2; ++_i) \
;         __builtin_amdgcn_global_load_lds((const unsigned*)((const char*)(gbase) + (voff)[_i]), (LAS unsigned*)(lds + (bufoff) + ldsw + _i * 8192), 16, 0, 0); } while (0)
; #define PG8_LDA(dst, b, h) do { _Pragma("unroll") for (int m = 0; m < 4; ++m) _Pragma("unroll") for (int k = 0; k < 2; ++k) dst[m][k] = *(const LAS bf16x8*)(lds + PG8_SA(b, h) + aoff + m * 2048 + k * 1024); } while (0)
; #define PG8_MMA(ai, bj, At, Bt) do { __builtin_amdgcn_s_setprio(1); _Pragma("unroll") for (int m = 0; m < 4; ++m) _Pragma("unroll") for (int n = 0; n < 2; ++n) _Pragma("unroll") for (int k = 0; k < 2; ++k) \
;         acc[ai][bj][m][n] = __builtin_amdgcn_mfma_f32_16x16x32_bf16(Bt[n][k], At[m][k], acc[ai][bj][m][n], 0, 0, 0); __builtin_amdgcn_s_setprio(0); } while (0)
; #define PG8_WAIT_V(n) asm volatile("s_waitcnt vmcnt(" #n ")" ::: "memory")
; #define PG8_WAIT_L(n) asm volatile("s_waitcnt lgkmcnt(" #n ")" ::: "memory")
; #define PG8_BAR __builtin_amdgcn_s_barrier()
; #define PG8_SCHED __builtin_amdgcn_sched_barrier(0)
; template <class Epi, class Sched, bool ALIGN_EPI = true, bool SP2 = true>
; __device__ __forceinline__ void gemm_phase(LAS unsigned char* lds, const Gemm g, const Sched& S, const Epi& E) {
;     ...
;             PG8_LDA(At, 1, 1); PG8_STAGE(PG8_SB(1, 0), b3, voffB); PG8_STAGE(PG8_SB(1, 1), b3 + hstep, voffB); PG8_STAGE(PG8_SA(1, 0), a3, voffA);
;             PG8_WAIT_V(8); PG8_WAIT_L(0); PG8_BAR; PG8_MMA(1, 0, At, B0); PG8_MMA(1, 1, At, B1); PG8_BAR; PG8_SCHED;
;     ...
;         if constexpr (ALIGN_EPI) { if (wr == 0) PG8_BAR; }
	s_setprio 0
	s_add_i32 s20, s58, s30
	v_lshl_add_u64 v[176:177], v[176:177], 0, s[92:93]
	s_mov_b32 m0, s20
	ds_read_b128 v[168:171], v194 offset:49152
	ds_read_b128 v[172:175], v194 offset:50176
	ds_read_b128 v[196:199], v194 offset:51200
	ds_read_b128 v[200:203], v194 offset:52224
	ds_read_b128 v[204:207], v194 offset:53248
	ds_read_b128 v[208:211], v194 offset:54272
	ds_read_b128 v[212:215], v194 offset:55296
	ds_read_b128 v[234:237], v194 offset:56320
	global_load_lds_dwordx4 v[176:177], off
	s_add_i32 m0, s20, 0x2000
	s_add_u32 s20, s24, 0x80080
	v_lshl_add_u64 v[176:177], v[224:225], 0, s[92:93]
	s_addc_u32 s21, s25, 0
	s_add_i32 s24, s59, s30
	global_load_lds_dwordx4 v[176:177], off
	v_lshl_add_u64 v[176:177], s[20:21], 0, v[0:1]
	s_mov_b32 m0, s24
	s_nop 0
	global_load_lds_dwordx4 v[176:177], off
	v_lshl_add_u64 v[176:177], s[20:21], 0, v[130:131]
	s_add_i32 m0, s24, 0x2000
	s_nop 0
	global_load_lds_dwordx4 v[176:177], off
	v_lshl_add_u64 v[176:177], v[238:239], 0, s[92:93]
	s_mov_b32 m0, s71
	s_nop 0
	global_load_lds_dwordx4 v[176:177], off
	v_lshl_add_u64 v[176:177], v[240:241], 0, s[92:93]
	s_mov_b32 m0, s74
	s_nop 0
	global_load_lds_dwordx4 v[176:177], off
	s_waitcnt vmcnt(8)
	s_waitcnt lgkmcnt(0)
	s_setprio 1
	s_barrier
	v_mfma_f32_16x16x32_bf16 v[62:65], v[136:139], v[168:171], v[62:65]
	v_mfma_f32_16x16x32_bf16 v[58:61], v[144:147], v[168:171], v[58:61]
	v_mfma_f32_16x16x32_bf16 v[46:49], v[136:139], v[196:199], v[46:49]
	v_mfma_f32_16x16x32_bf16 v[42:45], v[144:147], v[196:199], v[42:45]
	v_mfma_f32_16x16x32_bf16 v[30:33], v[136:139], v[204:207], v[30:33]
	v_mfma_f32_16x16x32_bf16 v[26:29], v[144:147], v[204:207], v[26:29]
	v_mfma_f32_16x16x32_bf16 v[14:17], v[136:139], v[212:215], v[14:17]
	v_mfma_f32_16x16x32_bf16 v[10:13], v[144:147], v[212:215], v[10:13]
	v_mfma_f32_16x16x32_bf16 v[62:65], v[140:143], v[172:175], v[62:65]
	v_mfma_f32_16x16x32_bf16 v[58:61], v[148:151], v[172:175], v[58:61]
	v_mfma_f32_16x16x32_bf16 v[46:49], v[140:143], v[200:203], v[46:49]
	v_mfma_f32_16x16x32_bf16 v[42:45], v[148:151], v[200:203], v[42:45]
	v_mfma_f32_16x16x32_bf16 v[30:33], v[140:143], v[208:211], v[30:33]
	v_mfma_f32_16x16x32_bf16 v[26:29], v[148:151], v[208:211], v[26:29]
	v_mfma_f32_16x16x32_bf16 v[14:17], v[140:143], v[234:237], v[14:17]
	v_mfma_f32_16x16x32_bf16 v[10:13], v[148:151], v[234:237], v[10:13]
	v_mfma_f32_16x16x32_bf16 v[54:57], v[152:155], v[168:171], v[54:57]
	v_mfma_f32_16x16x32_bf16 v[50:53], v[160:163], v[168:171], v[50:53]
	v_mfma_f32_16x16x32_bf16 v[38:41], v[152:155], v[196:199], v[38:41]
	v_mfma_f32_16x16x32_bf16 v[34:37], v[160:163], v[196:199], v[34:37]
	v_mfma_f32_16x16x32_bf16 v[22:25], v[152:155], v[204:207], v[22:25]
	v_mfma_f32_16x16x32_bf16 v[18:21], v[160:163], v[204:207], v[18:21]
	v_mfma_f32_16x16x32_bf16 v[6:9], v[152:155], v[212:215], v[6:9]
	v_mfma_f32_16x16x32_bf16 v[2:5], v[160:163], v[212:215], v[2:5]
	v_mfma_f32_16x16x32_bf16 v[54:57], v[156:159], v[172:175], v[54:57]
	v_mfma_f32_16x16x32_bf16 v[50:53], v[164:167], v[172:175], v[50:53]
	v_mfma_f32_16x16x32_bf16 v[38:41], v[156:159], v[200:203], v[38:41]
	v_mfma_f32_16x16x32_bf16 v[34:37], v[164:167], v[200:203], v[34:37]
	v_mfma_f32_16x16x32_bf16 v[22:25], v[156:159], v[208:211], v[22:25]
	v_mfma_f32_16x16x32_bf16 v[18:21], v[164:167], v[208:211], v[18:21]
	v_mfma_f32_16x16x32_bf16 v[6:9], v[156:159], v[234:237], v[6:9]
	v_mfma_f32_16x16x32_bf16 v[2:5], v[164:167], v[234:237], v[2:5]
	s_barrier
	s_setprio 0
	s_add_i32 s78, s78, 2
	s_add_u32 s76, s76, 0x100
	s_addc_u32 s77, s77, 0
	s_cmp_gt_u32 s78, 29
	s_mov_b64 s[20:21], s[22:23]
	s_cbranch_scc0 .LBB0_787
	s_and_b64 vcc, exec, s[6:7]
	s_cbranch_vccz .LBB0_790
	s_barrier

; #define PG8_STAGE(bufoff, gbase, voff) do { _Pragma("unroll") for (int _i = 0; _i < 2; ++_i) \
;         __builtin_amdgcn_global_load_lds((const unsigned*)((const char*)(gbase) + (voff)[_i]), (LAS unsigned*)(lds + (bufoff) + ldsw + _i * 8192), 16, 0, 0); } while (0)
; #define PG8_LDA(dst, b, h) do { _Pragma("unroll") for (int m = 0; m < 4; ++m) _Pragma("unroll") for (int k = 0; k < 2; ++k) dst[m][k] = *(const LAS bf16x8*)(lds + PG8_SA(b, h) + aoff + m * 2048 + k * 1024); } while (0)
; #define PG8_LDB(dst, b, h) do { _Pragma("unroll") for (int n = 0; n < 2; ++n) _Pragma("unroll") for (int k = 0; k < 2; ++k) dst[n][k] = *(const LAS bf16x8*)(lds + PG8_SB(b, h) + boff + n * 2048 + k * 1024); } while (0)
; #define PG8_MMA(ai, bj, At, Bt) do { __builtin_amdgcn_s_setprio(1); _Pragma("unroll") for (int m = 0; m < 4; ++m) _Pragma("unroll") for (int n = 0; n < 2; ++n) _Pragma("unroll") for (int k = 0; k < 2; ++k) \
;         acc[ai][bj][m][n] = __builtin_amdgcn_mfma_f32_16x16x32_bf16(Bt[n][k], At[m][k], acc[ai][bj][m][n], 0, 0, 0); __builtin_amdgcn_s_setprio(0); } while (0)
; #define PG8_WAIT_V(n) asm volatile("s_waitcnt vmcnt(" #n ")" ::: "memory")
; #define PG8_WAIT_L(n) asm volatile("s_waitcnt lgkmcnt(" #n ")" ::: "memory")
; #define PG8_BAR __builtin_amdgcn_s_barrier()
; #define PG8_SCHED __builtin_amdgcn_sched_barrier(0)
; template <class Epi, class Sched, bool ALIGN_EPI = true, bool SP2 = true>
; __device__ __forceinline__ void gemm_phase(LAS unsigned char* lds, const Gemm g, const Sched& S, const Epi& E) {
;     ...
;         for (int t = 0; t < nt; t += 2) {
;             const bool last = (t == nt - 2);
;             const char* a1 = cA + (size_t)(t + 1) * kstep;
;             const char* a2 = last ? nA : cA + (size_t)(t + 2) * kstep; const char* b2 = last ? nB : cB + (size_t)(t + 2) * kstep;
;             const char* a3 = a2 + kstep; const char* b3 = b2 + kstep;
;             if constexpr (SP2) {
;             PG8_LDB(B0, 0, 0); PG8_LDB(B1, 0, 1); PG8_SCHED; PG8_LDA(At, 0, 0); PG8_STAGE(PG8_SA(1, 1), a1 + hstep, voffA);
;             PG8_WAIT_V(8); PG8_WAIT_L(0); PG8_BAR; PG8_MMA(0, 0, At, B0); PG8_MMA(0, 1, At, B1); PG8_BAR; PG8_SCHED;
;             PG8_LDA(At, 0, 1); PG8_STAGE(PG8_SB(0, 0), b2, voffB); PG8_STAGE(PG8_SB(0, 1), b2 + hstep, voffB); PG8_STAGE(PG8_SA(0, 0), a2, voffA);
.LBB0_871:
	s_add_u32 s6, s4, 0xfff80080
	s_addc_u32 s7, s5, -1
	s_add_i32 s58, 0, 0x10000
	s_cmp_eq_u32 s74, 28
	s_cselect_b32 s23, s17, s7
	s_cselect_b32 s22, s70, s6
	v_add_u32_e32 v148, s58, v153
	s_cselect_b32 s7, s15, s73
	s_cselect_b32 s6, s71, s72
	s_add_i32 s75, 0, 0x14000
	ds_read_b128 v[140:143], v148
	ds_read_b128 v[144:147], v148 offset:1024
	ds_read_b128 v[160:163], v148 offset:2048
	ds_read_b128 v[164:167], v148 offset:3072
	v_add_u32_e32 v148, s75, v153
	ds_read_b128 v[168:171], v148
	ds_read_b128 v[172:175], v148 offset:1024
	ds_read_b128 v[176:179], v148 offset:2048
	ds_read_b128 v[194:197], v148 offset:3072
	v_lshl_add_u64 v[148:149], s[4:5], 0, v[136:137]
	s_add_i32 m0, s27, 0xc000
	ds_read_b128 v[198:201], v159
	ds_read_b128 v[202:205], v159 offset:1024
	ds_read_b128 v[206:209], v159 offset:2048
	ds_read_b128 v[210:213], v159 offset:3072
	ds_read_b128 v[234:237], v159 offset:4096
	ds_read_b128 v[238:241], v159 offset:5120
	ds_read_b128 v[242:245], v159 offset:6144
	ds_read_b128 v[246:249], v159 offset:7168
	global_load_lds_dwordx4 v[148:149], off
	v_lshl_add_u64 v[148:149], s[4:5], 0, v[138:139]
	s_add_i32 m0, s27, 0xe000
	s_nop 0
	global_load_lds_dwordx4 v[148:149], off
	s_waitcnt vmcnt(8)
	s_waitcnt lgkmcnt(0)
	s_setprio 1
	s_barrier
	v_mfma_f32_16x16x32_bf16 v[126:129], v[140:143], v[198:201], v[126:129]
	v_mfma_f32_16x16x32_bf16 v[118:121], v[160:163], v[198:201], v[118:121]
	v_mfma_f32_16x16x32_bf16 v[110:113], v[140:143], v[206:209], v[110:113]
	v_mfma_f32_16x16x32_bf16 v[102:105], v[160:163], v[206:209], v[102:105]
	v_mfma_f32_16x16x32_bf16 v[94:97], v[140:143], v[234:237], v[94:97]
	v_mfma_f32_16x16x32_bf16 v[86:89], v[160:163], v[234:237], v[86:89]
	v_mfma_f32_16x16x32_bf16 v[78:81], v[140:143], v[242:245], v[78:81]
	v_mfma_f32_16x16x32_bf16 v[70:73], v[160:163], v[242:245], v[70:73]
	v_mfma_f32_16x16x32_bf16 v[126:129], v[144:147], v[202:205], v[126:129]
	v_mfma_f32_16x16x32_bf16 v[118:121], v[164:167], v[202:205], v[118:121]
	v_mfma_f32_16x16x32_bf16 v[110:113], v[144:147], v[210:213], v[110:113]
	v_mfma_f32_16x16x32_bf16 v[102:105], v[164:167], v[210:213], v[102:105]
	v_mfma_f32_16x16x32_bf16 v[94:97], v[144:147], v[238:241], v[94:97]
	v_mfma_f32_16x16x32_bf16 v[86:89], v[164:167], v[238:241], v[86:89]
	v_mfma_f32_16x16x32_bf16 v[78:81], v[144:147], v[246:249], v[78:81]
	v_mfma_f32_16x16x32_bf16 v[70:73], v[164:167], v[246:249], v[70:73]
	v_mfma_f32_16x16x32_bf16 v[122:125], v[168:171], v[198:201], v[122:125]
	v_mfma_f32_16x16x32_bf16 v[114:117], v[176:179], v[198:201], v[114:117]
	v_mfma_f32_16x16x32_bf16 v[106:109], v[168:171], v[206:209], v[106:109]
	v_mfma_f32_16x16x32_bf16 v[98:101], v[176:179], v[206:209], v[98:101]
	v_mfma_f32_16x16x32_bf16 v[90:93], v[168:171], v[234:237], v[90:93]
	v_mfma_f32_16x16x32_bf16 v[82:85], v[176:179], v[234:237], v[82:85]
	v_mfma_f32_16x16x32_bf16 v[74:77], v[168:171], v[242:245], v[74:77]
	v_mfma_f32_16x16x32_bf16 v[66:69], v[176:179], v[242:245], v[66:69]
	v_mfma_f32_16x16x32_bf16 v[122:125], v[172:175], v[202:205], v[122:125]
	v_mfma_f32_16x16x32_bf16 v[114:117], v[194:197], v[202:205], v[114:117]
	v_mfma_f32_16x16x32_bf16 v[106:109], v[172:175], v[210:213], v[106:109]
	v_mfma_f32_16x16x32_bf16 v[98:101], v[194:197], v[210:213], v[98:101]
	v_mfma_f32_16x16x32_bf16 v[90:93], v[172:175], v[238:241], v[90:93]
	v_mfma_f32_16x16x32_bf16 v[82:85], v[194:197], v[238:241], v[82:85]
	v_mfma_f32_16x16x32_bf16 v[74:77], v[172:175], v[246:249], v[74:77]
	v_mfma_f32_16x16x32_bf16 v[66:69], v[194:197], v[246:249], v[66:69]
	s_barrier
	s_setprio 0
	s_add_i32 s58, s58, s26
	v_lshl_add_u64 v[148:149], s[6:7], 0, v[0:1]
	s_mov_b32 m0, s58
	ds_read_b128 v[198:201], v159 offset:16384
	ds_read_b128 v[202:205], v159 offset:17408
	ds_read_b128 v[206:209], v159 offset:18432
	ds_read_b128 v[210:213], v159 offset:19456
	ds_read_b128 v[234:237], v159 offset:20480
	ds_read_b128 v[238:241], v159 offset:21504
	ds_read_b128 v[242:245], v159 offset:22528
	ds_read_b128 v[246:249], v159 offset:23552
	global_load_lds_dwordx4 v[148:149], off
	s_add_i32 m0, s58, 0x2000
	s_add_u32 s58, s6, 0x80000
	v_lshl_add_u64 v[156:157], s[6:7], 0, v[130:131]
	s_addc_u32 s59, s7, 0
	s_add_i32 s75, s75, s26
	global_load_lds_dwordx4 v[156:157], off
	v_lshl_add_u64 v[214:215], s[58:59], 0, v[0:1]
	s_mov_b32 m0, s75
	v_lshl_add_u64 v[224:225], s[22:23], 0, v[132:133]
	global_load_lds_dwordx4 v[214:215], off
	v_lshl_add_u64 v[214:215], s[58:59], 0, v[130:131]
	s_add_i32 m0, s75, 0x2000
	s_nop 0
	global_load_lds_dwordx4 v[214:215], off
	v_lshl_add_u64 v[214:215], s[22:23], 0, v[134:135]
	s_mov_b32 m0, s27
	s_nop 0
	global_load_lds_dwordx4 v[214:215], off
	s_mov_b32 m0, s28
	s_nop 0
	global_load_lds_dwordx4 v[224:225], off
	s_waitcnt vmcnt(8)
	s_waitcnt lgkmcnt(0)
	s_setprio 1
	s_barrier
; #define PG8_STAGE(bufoff, gbase, voff) do { _Pragma("unroll") for (int _i = 0; _i < 2; ++_i) \
;         __builtin_amdgcn_global_load_lds((const unsigned*)((const char*)(gbase) + (voff)[_i]), (LAS unsigned*)(lds + (bufoff) + ldsw + _i * 8192), 16, 0, 0); } while (0)
; #define PG8_LDA(dst, b, h) do { _Pragma("unroll") for (int m = 0; m < 4; ++m) _Pragma("unroll") for (int k = 0; k < 2; ++k) dst[m][k] = *(const LAS bf16x8*)(lds + PG8_SA(b, h) + aoff + m * 2048 + k * 1024); } while (0)
; #define PG8_LDB(dst, b, h) do { _Pragma("unroll") for (int n = 0; n < 2; ++n) _Pragma("unroll") for (int k = 0; k < 2; ++k) dst[n][k] = *(const LAS bf16x8*)(lds + PG8_SB(b, h) + boff + n * 2048 + k * 1024); } while (0)
; #define PG8_MMA(ai, bj, At, Bt) do { __builtin_amdgcn_s_setprio(1); _Pragma("unroll") for (int m = 0; m < 4; ++m) _Pragma("unroll") for (int n = 0; n < 2; ++n) _Pragma("unroll") for (int k = 0; k < 2; ++k) \
;         acc[ai][bj][m][n] = __builtin_amdgcn_mfma_f32_16x16x32_bf16(Bt[n][k], At[m][k], acc[ai][bj][m][n], 0, 0, 0); __builtin_amdgcn_s_setprio(0); } while (0)
; #define PG8_WAIT_V(n) asm volatile("s_waitcnt vmcnt(" #n ")" ::: "memory")
; #define PG8_WAIT_L(n) asm volatile("s_waitcnt lgkmcnt(" #n ")" ::: "memory")
; #define PG8_BAR __builtin_amdgcn_s_barrier()
; #define PG8_SCHED __builtin_amdgcn_sched_barrier(0)
; template <class Epi, class Sched, bool ALIGN_EPI = true, bool SP2 = true>
; __device__ __forceinline__ void gemm_phase(LAS unsigned char* lds, const Gemm g, const Sched& S, const Epi& E) {
;     ...
;             PG8_WAIT_V(8); PG8_WAIT_L(0); PG8_BAR; PG8_MMA(1, 0, At, B0); PG8_MMA(1, 1, At, B1); PG8_BAR; PG8_SCHED;
;             PG8_LDB(B0, 1, 0); PG8_LDB(B1, 1, 1); PG8_SCHED; PG8_LDA(At, 1, 0); PG8_STAGE(PG8_SA(0, 1), a2 + hstep, voffA);
;             PG8_WAIT_V(8); PG8_WAIT_L(0); PG8_BAR; PG8_MMA(0, 0, At, B0); PG8_MMA(0, 1, At, B1); PG8_BAR; PG8_SCHED;
	v_mfma_f32_16x16x32_bf16 v[62:65], v[140:143], v[198:201], v[62:65]
	v_mfma_f32_16x16x32_bf16 v[54:57], v[160:163], v[198:201], v[54:57]
	v_mfma_f32_16x16x32_bf16 v[46:49], v[140:143], v[206:209], v[46:49]
	v_mfma_f32_16x16x32_bf16 v[38:41], v[160:163], v[206:209], v[38:41]
	v_mfma_f32_16x16x32_bf16 v[30:33], v[140:143], v[234:237], v[30:33]
	v_mfma_f32_16x16x32_bf16 v[22:25], v[160:163], v[234:237], v[22:25]
	v_mfma_f32_16x16x32_bf16 v[14:17], v[140:143], v[242:245], v[14:17]
	v_mfma_f32_16x16x32_bf16 v[6:9], v[160:163], v[242:245], v[6:9]
	v_mfma_f32_16x16x32_bf16 v[62:65], v[144:147], v[202:205], v[62:65]
	v_mfma_f32_16x16x32_bf16 v[54:57], v[164:167], v[202:205], v[54:57]
	v_mfma_f32_16x16x32_bf16 v[46:49], v[144:147], v[210:213], v[46:49]
	v_mfma_f32_16x16x32_bf16 v[38:41], v[164:167], v[210:213], v[38:41]
	v_mfma_f32_16x16x32_bf16 v[30:33], v[144:147], v[238:241], v[30:33]
	v_mfma_f32_16x16x32_bf16 v[22:25], v[164:167], v[238:241], v[22:25]
	v_mfma_f32_16x16x32_bf16 v[14:17], v[144:147], v[246:249], v[14:17]
	v_mfma_f32_16x16x32_bf16 v[6:9], v[164:167], v[246:249], v[6:9]
	v_mfma_f32_16x16x32_bf16 v[58:61], v[168:171], v[198:201], v[58:61]
	v_mfma_f32_16x16x32_bf16 v[50:53], v[176:179], v[198:201], v[50:53]
	v_mfma_f32_16x16x32_bf16 v[42:45], v[168:171], v[206:209], v[42:45]
	v_mfma_f32_16x16x32_bf16 v[34:37], v[176:179], v[206:209], v[34:37]
	v_mfma_f32_16x16x32_bf16 v[26:29], v[168:171], v[234:237], v[26:29]
	v_mfma_f32_16x16x32_bf16 v[18:21], v[176:179], v[234:237], v[18:21]
	v_mfma_f32_16x16x32_bf16 v[10:13], v[168:171], v[242:245], v[10:13]
	v_mfma_f32_16x16x32_bf16 v[2:5], v[176:179], v[242:245], v[2:5]
	v_mfma_f32_16x16x32_bf16 v[58:61], v[172:175], v[202:205], v[58:61]
	v_mfma_f32_16x16x32_bf16 v[50:53], v[194:197], v[202:205], v[50:53]
	v_mfma_f32_16x16x32_bf16 v[42:45], v[172:175], v[210:213], v[42:45]
	v_mfma_f32_16x16x32_bf16 v[34:37], v[194:197], v[210:213], v[34:37]
	v_mfma_f32_16x16x32_bf16 v[26:29], v[172:175], v[238:241], v[26:29]
	v_mfma_f32_16x16x32_bf16 v[18:21], v[194:197], v[238:241], v[18:21]
	v_mfma_f32_16x16x32_bf16 v[10:13], v[172:175], v[246:249], v[10:13]
	v_mfma_f32_16x16x32_bf16 v[2:5], v[194:197], v[246:249], v[2:5]
	s_barrier
	s_setprio 0
	s_add_i32 s58, 0, 0x18000
	v_add_u32_e32 v150, s58, v153
	s_add_i32 s59, 0, 0x1c000
	ds_read_b128 v[140:143], v150
	ds_read_b128 v[144:147], v150 offset:1024
	ds_read_b128 v[160:163], v150 offset:2048
	ds_read_b128 v[164:167], v150 offset:3072
	v_add_u32_e32 v150, s59, v153
	ds_read_b128 v[168:171], v150
	ds_read_b128 v[172:175], v150 offset:1024
	ds_read_b128 v[176:179], v150 offset:2048
	ds_read_b128 v[194:197], v150 offset:3072
	s_add_u32 s22, s22, 0x80000
	s_addc_u32 s23, s23, 0
	s_mov_b32 m0, s29
	v_lshl_add_u64 v[250:251], s[22:23], 0, v[134:135]
	ds_read_b128 v[198:201], v159 offset:32768
	ds_read_b128 v[202:205], v159 offset:33792
	ds_read_b128 v[206:209], v159 offset:34816
	ds_read_b128 v[210:213], v159 offset:35840
	ds_read_b128 v[234:237], v159 offset:36864
	ds_read_b128 v[238:241], v159 offset:37888
	ds_read_b128 v[242:245], v159 offset:38912
	ds_read_b128 v[246:249], v159 offset:39936
	global_load_lds_dwordx4 v[250:251], off
	v_lshl_add_u64 v[250:251], s[22:23], 0, v[132:133]
	s_mov_b32 m0, s30
	s_nop 0
	global_load_lds_dwordx4 v[250:251], off
	s_waitcnt vmcnt(8)
	s_waitcnt lgkmcnt(0)
	s_setprio 1
	s_barrier
	v_mfma_f32_16x16x32_bf16 v[126:129], v[140:143], v[198:201], v[126:129]
	v_mfma_f32_16x16x32_bf16 v[118:121], v[160:163], v[198:201], v[118:121]
	v_mfma_f32_16x16x32_bf16 v[110:113], v[140:143], v[206:209], v[110:113]
	v_mfma_f32_16x16x32_bf16 v[102:105], v[160:163], v[206:209], v[102:105]
	v_mfma_f32_16x16x32_bf16 v[94:97], v[140:143], v[234:237], v[94:97]
	v_mfma_f32_16x16x32_bf16 v[86:89], v[160:163], v[234:237], v[86:89]
	v_mfma_f32_16x16x32_bf16 v[78:81], v[140:143], v[242:245], v[78:81]
	v_mfma_f32_16x16x32_bf16 v[70:73], v[160:163], v[242:245], v[70:73]
	v_mfma_f32_16x16x32_bf16 v[126:129], v[144:147], v[202:205], v[126:129]
	v_mfma_f32_16x16x32_bf16 v[118:121], v[164:167], v[202:205], v[118:121]
	v_mfma_f32_16x16x32_bf16 v[110:113], v[144:147], v[210:213], v[110:113]
	v_mfma_f32_16x16x32_bf16 v[102:105], v[164:167], v[210:213], v[102:105]
	v_mfma_f32_16x16x32_bf16 v[94:97], v[144:147], v[238:241], v[94:97]
	v_mfma_f32_16x16x32_bf16 v[86:89], v[164:167], v[238:241], v[86:89]
	v_mfma_f32_16x16x32_bf16 v[78:81], v[144:147], v[246:249], v[78:81]
	v_mfma_f32_16x16x32_bf16 v[70:73], v[164:167], v[246:249], v[70:73]
	v_mfma_f32_16x16x32_bf16 v[122:125], v[168:171], v[198:201], v[122:125]
	v_mfma_f32_16x16x32_bf16 v[114:117], v[176:179], v[198:201], v[114:117]
	v_mfma_f32_16x16x32_bf16 v[106:109], v[168:171], v[206:209], v[106:109]
	v_mfma_f32_16x16x32_bf16 v[98:101], v[176:179], v[206:209], v[98:101]
	v_mfma_f32_16x16x32_bf16 v[90:93], v[168:171], v[234:237], v[90:93]
	v_mfma_f32_16x16x32_bf16 v[82:85], v[176:179], v[234:237], v[82:85]
	v_mfma_f32_16x16x32_bf16 v[74:77], v[168:171], v[242:245], v[74:77]
	v_mfma_f32_16x16x32_bf16 v[66:69], v[176:179], v[242:245], v[66:69]
	v_mfma_f32_16x16x32_bf16 v[122:125], v[172:175], v[202:205], v[122:125]
	v_mfma_f32_16x16x32_bf16 v[114:117], v[194:197], v[202:205], v[114:117]
	v_mfma_f32_16x16x32_bf16 v[106:109], v[172:175], v[210:213], v[106:109]
	v_mfma_f32_16x16x32_bf16 v[98:101], v[194:197], v[210:213], v[98:101]
	v_mfma_f32_16x16x32_bf16 v[90:93], v[172:175], v[238:241], v[90:93]
	v_mfma_f32_16x16x32_bf16 v[82:85], v[194:197], v[238:241], v[82:85]
	v_mfma_f32_16x16x32_bf16 v[74:77], v[172:175], v[246:249], v[74:77]
	v_mfma_f32_16x16x32_bf16 v[66:69], v[194:197], v[246:249], v[66:69]
	s_barrier
; #define PG8_STAGE(bufoff, gbase, voff) do { _Pragma("unroll") for (int _i = 0; _i < 2; ++_i) \
;         __builtin_amdgcn_global_load_lds((const unsigned*)((const char*)(gbase) + (voff)[_i]), (LAS unsigned*)(lds + (bufoff) + ldsw + _i * 8192), 16, 0, 0); } while (0)
; #define PG8_LDA(dst, b, h) do { _Pragma("unroll") for (int m = 0; m < 4; ++m) _Pragma("unroll") for (int k = 0; k < 2; ++k) dst[m][k] = *(const LAS bf16x8*)(lds + PG8_SA(b, h) + aoff + m * 2048 + k * 1024); } while (0)
; #define PG8_MMA(ai, bj, At, Bt) do { __builtin_amdgcn_s_setprio(1); _Pragma("unroll") for (int m = 0; m < 4; ++m) _Pragma("unroll") for (int n = 0; n < 2; ++n) _Pragma("unroll") for (int k = 0; k < 2; ++k) \
;         acc[ai][bj][m][n] = __builtin_amdgcn_mfma_f32_16x16x32_bf16(Bt[n][k], At[m][k], acc[ai][bj][m][n], 0, 0, 0); __builtin_amdgcn_s_setprio(0); } while (0)
; #define PG8_WAIT_V(n) asm volatile("s_waitcnt vmcnt(" #n ")" ::: "memory")
; #define PG8_WAIT_L(n) asm volatile("s_waitcnt lgkmcnt(" #n ")" ::: "memory")
; #define PG8_BAR __builtin_amdgcn_s_barrier()
; #define PG8_SCHED __builtin_amdgcn_sched_barrier(0)
; template <class Epi, class Sched, bool ALIGN_EPI = true, bool SP2 = true>
; __device__ __forceinline__ void gemm_phase(LAS unsigned char* lds, const Gemm g, const Sched& S, const Epi& E) {
;     ...
;             PG8_LDA(At, 1, 1); PG8_STAGE(PG8_SB(1, 0), b3, voffB); PG8_STAGE(PG8_SB(1, 1), b3 + hstep, voffB); PG8_STAGE(PG8_SA(1, 0), a3, voffA);
;             PG8_WAIT_V(8); PG8_WAIT_L(0); PG8_BAR; PG8_MMA(1, 0, At, B0); PG8_MMA(1, 1, At, B1); PG8_BAR; PG8_SCHED;
;     ...
;         if constexpr (ALIGN_EPI) { if (wr == 0) PG8_BAR; }
	s_setprio 0
	s_add_i32 s22, s58, s26
	v_lshl_add_u64 v[148:149], v[148:149], 0, s[92:93]
	s_mov_b32 m0, s22
	ds_read_b128 v[198:201], v159 offset:49152
	ds_read_b128 v[202:205], v159 offset:50176
	ds_read_b128 v[206:209], v159 offset:51200
	ds_read_b128 v[210:213], v159 offset:52224
	ds_read_b128 v[234:237], v159 offset:53248
	ds_read_b128 v[238:241], v159 offset:54272
	ds_read_b128 v[242:245], v159 offset:55296
	ds_read_b128 v[246:249], v159 offset:56320
	global_load_lds_dwordx4 v[148:149], off
	s_add_i32 m0, s22, 0x2000
	s_add_u32 s6, s6, 0x80080
	v_lshl_add_u64 v[148:149], v[156:157], 0, s[92:93]
	s_addc_u32 s7, s7, 0
	s_add_i32 s22, s59, s26
	global_load_lds_dwordx4 v[148:149], off
	v_lshl_add_u64 v[148:149], s[6:7], 0, v[0:1]
	s_mov_b32 m0, s22
	s_nop 0
	global_load_lds_dwordx4 v[148:149], off
	v_lshl_add_u64 v[148:149], s[6:7], 0, v[130:131]
	s_add_i32 m0, s22, 0x2000
	s_nop 0
	global_load_lds_dwordx4 v[148:149], off
	v_lshl_add_u64 v[148:149], v[214:215], 0, s[92:93]
	s_mov_b32 m0, s31
	s_nop 0
	global_load_lds_dwordx4 v[148:149], off
	v_lshl_add_u64 v[148:149], v[224:225], 0, s[92:93]
	s_mov_b32 m0, s34
	s_nop 0
	global_load_lds_dwordx4 v[148:149], off
	s_waitcnt vmcnt(8)
	s_waitcnt lgkmcnt(0)
	s_setprio 1
	s_barrier
	v_mfma_f32_16x16x32_bf16 v[62:65], v[140:143], v[198:201], v[62:65]
	v_mfma_f32_16x16x32_bf16 v[54:57], v[160:163], v[198:201], v[54:57]
	v_mfma_f32_16x16x32_bf16 v[46:49], v[140:143], v[206:209], v[46:49]
	v_mfma_f32_16x16x32_bf16 v[38:41], v[160:163], v[206:209], v[38:41]
	v_mfma_f32_16x16x32_bf16 v[30:33], v[140:143], v[234:237], v[30:33]
	v_mfma_f32_16x16x32_bf16 v[22:25], v[160:163], v[234:237], v[22:25]
	v_mfma_f32_16x16x32_bf16 v[14:17], v[140:143], v[242:245], v[14:17]
	v_mfma_f32_16x16x32_bf16 v[6:9], v[160:163], v[242:245], v[6:9]
	v_mfma_f32_16x16x32_bf16 v[62:65], v[144:147], v[202:205], v[62:65]
	v_mfma_f32_16x16x32_bf16 v[54:57], v[164:167], v[202:205], v[54:57]
	v_mfma_f32_16x16x32_bf16 v[46:49], v[144:147], v[210:213], v[46:49]
	v_mfma_f32_16x16x32_bf16 v[38:41], v[164:167], v[210:213], v[38:41]
	v_mfma_f32_16x16x32_bf16 v[30:33], v[144:147], v[238:241], v[30:33]
	v_mfma_f32_16x16x32_bf16 v[22:25], v[164:167], v[238:241], v[22:25]
	v_mfma_f32_16x16x32_bf16 v[14:17], v[144:147], v[246:249], v[14:17]
	v_mfma_f32_16x16x32_bf16 v[6:9], v[164:167], v[246:249], v[6:9]
	v_mfma_f32_16x16x32_bf16 v[58:61], v[168:171], v[198:201], v[58:61]
	v_mfma_f32_16x16x32_bf16 v[50:53], v[176:179], v[198:201], v[50:53]
	v_mfma_f32_16x16x32_bf16 v[42:45], v[168:171], v[206:209], v[42:45]
	v_mfma_f32_16x16x32_bf16 v[34:37], v[176:179], v[206:209], v[34:37]
	v_mfma_f32_16x16x32_bf16 v[26:29], v[168:171], v[234:237], v[26:29]
	v_mfma_f32_16x16x32_bf16 v[18:21], v[176:179], v[234:237], v[18:21]
	v_mfma_f32_16x16x32_bf16 v[10:13], v[168:171], v[242:245], v[10:13]
	v_mfma_f32_16x16x32_bf16 v[2:5], v[176:179], v[242:245], v[2:5]
	v_mfma_f32_16x16x32_bf16 v[58:61], v[172:175], v[202:205], v[58:61]
	v_mfma_f32_16x16x32_bf16 v[50:53], v[194:197], v[202:205], v[50:53]
	v_mfma_f32_16x16x32_bf16 v[42:45], v[172:175], v[210:213], v[42:45]
	v_mfma_f32_16x16x32_bf16 v[34:37], v[194:197], v[210:213], v[34:37]
	v_mfma_f32_16x16x32_bf16 v[26:29], v[172:175], v[238:241], v[26:29]
	v_mfma_f32_16x16x32_bf16 v[18:21], v[194:197], v[238:241], v[18:21]
	v_mfma_f32_16x16x32_bf16 v[10:13], v[172:175], v[246:249], v[10:13]
	v_mfma_f32_16x16x32_bf16 v[2:5], v[194:197], v[246:249], v[2:5]
	s_barrier
	s_setprio 0
	s_add_i32 s74, s74, 2
	s_add_u32 s4, s4, 0x100
	s_addc_u32 s5, s5, 0
	s_add_u32 s72, s72, 0x100
	s_addc_u32 s73, s73, 0
	s_cmp_gt_u32 s74, 29
	s_cbranch_scc0 .LBB0_871
	s_and_b64 vcc, exec, s[12:13]
	s_cbranch_vccz .LBB0_874
	s_barrier

; #define PG8_STAGE(bufoff, gbase, voff) do { _Pragma("unroll") for (int _i = 0; _i < 2; ++_i) \
;         __builtin_amdgcn_global_load_lds((const unsigned*)((const char*)(gbase) + (voff)[_i]), (LAS unsigned*)(lds + (bufoff) + ldsw + _i * 8192), 16, 0, 0); } while (0)
; #define PG8_LDA(dst, b, h) do { _Pragma("unroll") for (int m = 0; m < 4; ++m) _Pragma("unroll") for (int k = 0; k < 2; ++k) dst[m][k] = *(const LAS bf16x8*)(lds + PG8_SA(b, h) + aoff + m * 2048 + k * 1024); } while (0)
; #define PG8_LDB(dst, b, h) do { _Pragma("unroll") for (int n = 0; n < 2; ++n) _Pragma("unroll") for (int k = 0; k < 2; ++k) dst[n][k] = *(const LAS bf16x8*)(lds + PG8_SB(b, h) + boff + n * 2048 + k * 1024); } while (0)
; #define PG8_MMA(ai, bj, At, Bt) do { __builtin_amdgcn_s_setprio(1); _Pragma("unroll") for (int m = 0; m < 4; ++m) _Pragma("unroll") for (int n = 0; n < 2; ++n) _Pragma("unroll") for (int k = 0; k < 2; ++k) \
;         acc[ai][bj][m][n] = __builtin_amdgcn_mfma_f32_16x16x32_bf16(Bt[n][k], At[m][k], acc[ai][bj][m][n], 0, 0, 0); __builtin_amdgcn_s_setprio(0); } while (0)
; #define PG8_WAIT_V(n) asm volatile("s_waitcnt vmcnt(" #n ")" ::: "memory")
; #define PG8_WAIT_L(n) asm volatile("s_waitcnt lgkmcnt(" #n ")" ::: "memory")
; #define PG8_BAR __builtin_amdgcn_s_barrier()
; #define PG8_SCHED __builtin_amdgcn_sched_barrier(0)
; template <class Epi, class Sched, bool ALIGN_EPI = true, bool SP2 = true>
; __device__ __forceinline__ void gemm_phase(LAS unsigned char* lds, const Gemm g, const Sched& S, const Epi& E) {
;     ...
;         for (int t = 0; t < nt; t += 2) {
;             const bool last = (t == nt - 2);
;             const char* a1 = cA + (size_t)(t + 1) * kstep;
;             const char* a2 = last ? nA : cA + (size_t)(t + 2) * kstep; const char* b2 = last ? nB : cB + (size_t)(t + 2) * kstep;
;             const char* a3 = a2 + kstep; const char* b3 = b2 + kstep;
;             if constexpr (SP2) {
;             PG8_LDB(B0, 0, 0); PG8_LDB(B1, 0, 1); PG8_SCHED; PG8_LDA(At, 0, 0); PG8_STAGE(PG8_SA(1, 1), a1 + hstep, voffA);
;             PG8_WAIT_V(8); PG8_WAIT_L(0); PG8_BAR; PG8_MMA(0, 0, At, B0); PG8_MMA(0, 1, At, B1); PG8_BAR; PG8_SCHED;
;             PG8_LDA(At, 0, 1); PG8_STAGE(PG8_SB(0, 0), b2, voffB); PG8_STAGE(PG8_SB(0, 1), b2 + hstep, voffB); PG8_STAGE(PG8_SA(0, 0), a2, voffA);
.LBB0_991:
	s_add_u32 s18, s16, 0x100
	s_addc_u32 s19, s17, 0
	s_add_i32 s58, 0, 0x10000
	s_cmpk_eq_i32 s74, 0x54
	s_cselect_b32 s23, s1, s19
	s_cselect_b32 s22, s0, s18
	s_cselect_b32 s21, s15, s73
	s_cselect_b32 s20, s14, s72
	s_add_i32 s59, 0, 0x14000
	v_add_u32_e32 v148, s58, v179
	v_add_u32_e32 v164, s59, v179
	ds_read_b128 v[136:139], v148
	ds_read_b128 v[140:143], v148 offset:1024
	ds_read_b128 v[144:147], v148 offset:2048
	ds_read_b128 v[148:151], v148 offset:3072
	ds_read_b128 v[152:155], v164
	ds_read_b128 v[156:159], v164 offset:1024
	ds_read_b128 v[160:163], v164 offset:2048
	ds_read_b128 v[164:167], v164 offset:3072
	v_lshl_add_u64 v[176:177], s[16:17], 0, v[132:133]
	s_add_i32 m0, s27, 0xc000
	ds_read_b128 v[168:171], v194
	ds_read_b128 v[172:175], v194 offset:1024
	ds_read_b128 v[196:199], v194 offset:2048
	ds_read_b128 v[200:203], v194 offset:3072
	ds_read_b128 v[204:207], v194 offset:4096
	ds_read_b128 v[208:211], v194 offset:5120
	ds_read_b128 v[212:215], v194 offset:6144
	ds_read_b128 v[234:237], v194 offset:7168
	global_load_lds_dwordx4 v[176:177], off
	v_lshl_add_u64 v[176:177], s[16:17], 0, v[134:135]
	s_add_i32 m0, s27, 0xe000
	s_nop 0
	global_load_lds_dwordx4 v[176:177], off
	s_waitcnt vmcnt(8)
	s_waitcnt lgkmcnt(0)
	s_setprio 1
	s_barrier
	v_mfma_f32_16x16x32_bf16 v[126:129], v[136:139], v[168:171], v[126:129]
	v_mfma_f32_16x16x32_bf16 v[122:125], v[144:147], v[168:171], v[122:125]
	v_mfma_f32_16x16x32_bf16 v[110:113], v[136:139], v[196:199], v[110:113]
	v_mfma_f32_16x16x32_bf16 v[106:109], v[144:147], v[196:199], v[106:109]
	v_mfma_f32_16x16x32_bf16 v[94:97], v[136:139], v[204:207], v[94:97]
	v_mfma_f32_16x16x32_bf16 v[90:93], v[144:147], v[204:207], v[90:93]
	v_mfma_f32_16x16x32_bf16 v[78:81], v[136:139], v[212:215], v[78:81]
	v_mfma_f32_16x16x32_bf16 v[74:77], v[144:147], v[212:215], v[74:77]
	v_mfma_f32_16x16x32_bf16 v[126:129], v[140:143], v[172:175], v[126:129]
	v_mfma_f32_16x16x32_bf16 v[122:125], v[148:151], v[172:175], v[122:125]
	v_mfma_f32_16x16x32_bf16 v[110:113], v[140:143], v[200:203], v[110:113]
	v_mfma_f32_16x16x32_bf16 v[106:109], v[148:151], v[200:203], v[106:109]
	v_mfma_f32_16x16x32_bf16 v[94:97], v[140:143], v[208:211], v[94:97]
	v_mfma_f32_16x16x32_bf16 v[90:93], v[148:151], v[208:211], v[90:93]
	v_mfma_f32_16x16x32_bf16 v[78:81], v[140:143], v[234:237], v[78:81]
	v_mfma_f32_16x16x32_bf16 v[74:77], v[148:151], v[234:237], v[74:77]
	v_mfma_f32_16x16x32_bf16 v[118:121], v[152:155], v[168:171], v[118:121]
	v_mfma_f32_16x16x32_bf16 v[114:117], v[160:163], v[168:171], v[114:117]
	v_mfma_f32_16x16x32_bf16 v[102:105], v[152:155], v[196:199], v[102:105]
	v_mfma_f32_16x16x32_bf16 v[98:101], v[160:163], v[196:199], v[98:101]
	v_mfma_f32_16x16x32_bf16 v[86:89], v[152:155], v[204:207], v[86:89]
	v_mfma_f32_16x16x32_bf16 v[82:85], v[160:163], v[204:207], v[82:85]
	v_mfma_f32_16x16x32_bf16 v[70:73], v[152:155], v[212:215], v[70:73]
	v_mfma_f32_16x16x32_bf16 v[66:69], v[160:163], v[212:215], v[66:69]
	v_mfma_f32_16x16x32_bf16 v[118:121], v[156:159], v[172:175], v[118:121]
	v_mfma_f32_16x16x32_bf16 v[114:117], v[164:167], v[172:175], v[114:117]
	v_mfma_f32_16x16x32_bf16 v[102:105], v[156:159], v[200:203], v[102:105]
	v_mfma_f32_16x16x32_bf16 v[98:101], v[164:167], v[200:203], v[98:101]
	v_mfma_f32_16x16x32_bf16 v[86:89], v[156:159], v[208:211], v[86:89]
	v_mfma_f32_16x16x32_bf16 v[82:85], v[164:167], v[208:211], v[82:85]
	v_mfma_f32_16x16x32_bf16 v[70:73], v[156:159], v[234:237], v[70:73]
	v_mfma_f32_16x16x32_bf16 v[66:69], v[164:167], v[234:237], v[66:69]
	s_barrier
	s_setprio 0
	s_add_i32 s16, s58, s26
	v_lshl_add_u64 v[176:177], s[20:21], 0, v[0:1]
	s_mov_b32 m0, s16
	ds_read_b128 v[168:171], v194 offset:16384
	ds_read_b128 v[172:175], v194 offset:17408
	ds_read_b128 v[196:199], v194 offset:18432
	ds_read_b128 v[200:203], v194 offset:19456
	ds_read_b128 v[204:207], v194 offset:20480
	ds_read_b128 v[208:211], v194 offset:21504
	ds_read_b128 v[212:215], v194 offset:22528
	ds_read_b128 v[234:237], v194 offset:23552
	global_load_lds_dwordx4 v[176:177], off
	s_add_i32 m0, s16, 0x2000
	s_add_u32 s16, s20, 0x160000
	v_lshl_add_u64 v[224:225], s[20:21], 0, v[130:131]
	s_addc_u32 s17, s21, 0
	s_add_i32 s58, s59, s26
	global_load_lds_dwordx4 v[224:225], off
	v_lshl_add_u64 v[238:239], s[16:17], 0, v[0:1]
	s_mov_b32 m0, s58
	v_lshl_add_u64 v[240:241], s[22:23], 0, v[130:131]
	global_load_lds_dwordx4 v[238:239], off
	v_lshl_add_u64 v[238:239], s[16:17], 0, v[130:131]
	s_add_i32 m0, s58, 0x2000
	s_nop 0
	global_load_lds_dwordx4 v[238:239], off
	v_lshl_add_u64 v[238:239], s[22:23], 0, v[0:1]
	s_mov_b32 m0, s27
	s_nop 0
	global_load_lds_dwordx4 v[238:239], off
	s_mov_b32 m0, s28
	s_nop 0
	global_load_lds_dwordx4 v[240:241], off
	s_waitcnt vmcnt(8)
	s_waitcnt lgkmcnt(0)
	s_setprio 1
	s_barrier
; #define PG8_STAGE(bufoff, gbase, voff) do { _Pragma("unroll") for (int _i = 0; _i < 2; ++_i) \
;         __builtin_amdgcn_global_load_lds((const unsigned*)((const char*)(gbase) + (voff)[_i]), (LAS unsigned*)(lds + (bufoff) + ldsw + _i * 8192), 16, 0, 0); } while (0)
; #define PG8_LDA(dst, b, h) do { _Pragma("unroll") for (int m = 0; m < 4; ++m) _Pragma("unroll") for (int k = 0; k < 2; ++k) dst[m][k] = *(const LAS bf16x8*)(lds + PG8_SA(b, h) + aoff + m * 2048 + k * 1024); } while (0)
; #define PG8_LDB(dst, b, h) do { _Pragma("unroll") for (int n = 0; n < 2; ++n) _Pragma("unroll") for (int k = 0; k < 2; ++k) dst[n][k] = *(const LAS bf16x8*)(lds + PG8_SB(b, h) + boff + n * 2048 + k * 1024); } while (0)
; #define PG8_MMA(ai, bj, At, Bt) do { __builtin_amdgcn_s_setprio(1); _Pragma("unroll") for (int m = 0; m < 4; ++m) _Pragma("unroll") for (int n = 0; n < 2; ++n) _Pragma("unroll") for (int k = 0; k < 2; ++k) \
;         acc[ai][bj][m][n] = __builtin_amdgcn_mfma_f32_16x16x32_bf16(Bt[n][k], At[m][k], acc[ai][bj][m][n], 0, 0, 0); __builtin_amdgcn_s_setprio(0); } while (0)
; #define PG8_WAIT_V(n) asm volatile("s_waitcnt vmcnt(" #n ")" ::: "memory")
; #define PG8_WAIT_L(n) asm volatile("s_waitcnt lgkmcnt(" #n ")" ::: "memory")
; #define PG8_BAR __builtin_amdgcn_s_barrier()
; #define PG8_SCHED __builtin_amdgcn_sched_barrier(0)
; template <class Epi, class Sched, bool ALIGN_EPI = true, bool SP2 = true>
; __device__ __forceinline__ void gemm_phase(LAS unsigned char* lds, const Gemm g, const Sched& S, const Epi& E) {
;     ...
;             PG8_WAIT_V(8); PG8_WAIT_L(0); PG8_BAR; PG8_MMA(1, 0, At, B0); PG8_MMA(1, 1, At, B1); PG8_BAR; PG8_SCHED;
;             PG8_LDB(B0, 1, 0); PG8_LDB(B1, 1, 1); PG8_SCHED; PG8_LDA(At, 1, 0); PG8_STAGE(PG8_SA(0, 1), a2 + hstep, voffA);
;             PG8_WAIT_V(8); PG8_WAIT_L(0); PG8_BAR; PG8_MMA(0, 0, At, B0); PG8_MMA(0, 1, At, B1); PG8_BAR; PG8_SCHED;
	v_mfma_f32_16x16x32_bf16 v[62:65], v[136:139], v[168:171], v[62:65]
	v_mfma_f32_16x16x32_bf16 v[58:61], v[144:147], v[168:171], v[58:61]
	v_mfma_f32_16x16x32_bf16 v[46:49], v[136:139], v[196:199], v[46:49]
	v_mfma_f32_16x16x32_bf16 v[42:45], v[144:147], v[196:199], v[42:45]
	v_mfma_f32_16x16x32_bf16 v[30:33], v[136:139], v[204:207], v[30:33]
	v_mfma_f32_16x16x32_bf16 v[26:29], v[144:147], v[204:207], v[26:29]
	v_mfma_f32_16x16x32_bf16 v[14:17], v[136:139], v[212:215], v[14:17]
	v_mfma_f32_16x16x32_bf16 v[10:13], v[144:147], v[212:215], v[10:13]
	v_mfma_f32_16x16x32_bf16 v[62:65], v[140:143], v[172:175], v[62:65]
	v_mfma_f32_16x16x32_bf16 v[58:61], v[148:151], v[172:175], v[58:61]
	v_mfma_f32_16x16x32_bf16 v[46:49], v[140:143], v[200:203], v[46:49]
	v_mfma_f32_16x16x32_bf16 v[42:45], v[148:151], v[200:203], v[42:45]
	v_mfma_f32_16x16x32_bf16 v[30:33], v[140:143], v[208:211], v[30:33]
	v_mfma_f32_16x16x32_bf16 v[26:29], v[148:151], v[208:211], v[26:29]
	v_mfma_f32_16x16x32_bf16 v[14:17], v[140:143], v[234:237], v[14:17]
	v_mfma_f32_16x16x32_bf16 v[10:13], v[148:151], v[234:237], v[10:13]
	v_mfma_f32_16x16x32_bf16 v[54:57], v[152:155], v[168:171], v[54:57]
	v_mfma_f32_16x16x32_bf16 v[50:53], v[160:163], v[168:171], v[50:53]
	v_mfma_f32_16x16x32_bf16 v[38:41], v[152:155], v[196:199], v[38:41]
	v_mfma_f32_16x16x32_bf16 v[34:37], v[160:163], v[196:199], v[34:37]
	v_mfma_f32_16x16x32_bf16 v[22:25], v[152:155], v[204:207], v[22:25]
	v_mfma_f32_16x16x32_bf16 v[18:21], v[160:163], v[204:207], v[18:21]
	v_mfma_f32_16x16x32_bf16 v[6:9], v[152:155], v[212:215], v[6:9]
	v_mfma_f32_16x16x32_bf16 v[2:5], v[160:163], v[212:215], v[2:5]
	v_mfma_f32_16x16x32_bf16 v[54:57], v[156:159], v[172:175], v[54:57]
	v_mfma_f32_16x16x32_bf16 v[50:53], v[164:167], v[172:175], v[50:53]
	v_mfma_f32_16x16x32_bf16 v[38:41], v[156:159], v[200:203], v[38:41]
	v_mfma_f32_16x16x32_bf16 v[34:37], v[164:167], v[200:203], v[34:37]
	v_mfma_f32_16x16x32_bf16 v[22:25], v[156:159], v[208:211], v[22:25]
	v_mfma_f32_16x16x32_bf16 v[18:21], v[164:167], v[208:211], v[18:21]
	v_mfma_f32_16x16x32_bf16 v[6:9], v[156:159], v[234:237], v[6:9]
	v_mfma_f32_16x16x32_bf16 v[2:5], v[164:167], v[234:237], v[2:5]
	s_barrier
	s_setprio 0
	s_add_i32 s58, 0, 0x18000
	s_add_i32 s59, 0, 0x1c000
	v_add_u32_e32 v148, s58, v179
	v_add_u32_e32 v164, s59, v179
	ds_read_b128 v[136:139], v148
	ds_read_b128 v[140:143], v148 offset:1024
	ds_read_b128 v[144:147], v148 offset:2048
	ds_read_b128 v[148:151], v148 offset:3072
	ds_read_b128 v[152:155], v164
	ds_read_b128 v[156:159], v164 offset:1024
	ds_read_b128 v[160:163], v164 offset:2048
	ds_read_b128 v[164:167], v164 offset:3072
	s_add_u32 s16, s22, 0x160000
	s_addc_u32 s17, s23, 0
	s_mov_b32 m0, s29
	v_lshl_add_u64 v[242:243], s[16:17], 0, v[0:1]
	ds_read_b128 v[168:171], v194 offset:32768
	ds_read_b128 v[172:175], v194 offset:33792
	ds_read_b128 v[196:199], v194 offset:34816
	ds_read_b128 v[200:203], v194 offset:35840
	ds_read_b128 v[204:207], v194 offset:36864
	ds_read_b128 v[208:211], v194 offset:37888
	ds_read_b128 v[212:215], v194 offset:38912
	ds_read_b128 v[234:237], v194 offset:39936
	global_load_lds_dwordx4 v[242:243], off
	v_lshl_add_u64 v[242:243], s[16:17], 0, v[130:131]
	s_mov_b32 m0, s30
	s_nop 0
	global_load_lds_dwordx4 v[242:243], off
	s_waitcnt vmcnt(8)
	s_waitcnt lgkmcnt(0)
	s_setprio 1
	s_barrier
	v_mfma_f32_16x16x32_bf16 v[126:129], v[136:139], v[168:171], v[126:129]
	v_mfma_f32_16x16x32_bf16 v[122:125], v[144:147], v[168:171], v[122:125]
	v_mfma_f32_16x16x32_bf16 v[110:113], v[136:139], v[196:199], v[110:113]
	v_mfma_f32_16x16x32_bf16 v[106:109], v[144:147], v[196:199], v[106:109]
	v_mfma_f32_16x16x32_bf16 v[94:97], v[136:139], v[204:207], v[94:97]
	v_mfma_f32_16x16x32_bf16 v[90:93], v[144:147], v[204:207], v[90:93]
	v_mfma_f32_16x16x32_bf16 v[78:81], v[136:139], v[212:215], v[78:81]
	v_mfma_f32_16x16x32_bf16 v[74:77], v[144:147], v[212:215], v[74:77]
	v_mfma_f32_16x16x32_bf16 v[126:129], v[140:143], v[172:175], v[126:129]
	v_mfma_f32_16x16x32_bf16 v[122:125], v[148:151], v[172:175], v[122:125]
	v_mfma_f32_16x16x32_bf16 v[110:113], v[140:143], v[200:203], v[110:113]
	v_mfma_f32_16x16x32_bf16 v[106:109], v[148:151], v[200:203], v[106:109]
	v_mfma_f32_16x16x32_bf16 v[94:97], v[140:143], v[208:211], v[94:97]
	v_mfma_f32_16x16x32_bf16 v[90:93], v[148:151], v[208:211], v[90:93]
	v_mfma_f32_16x16x32_bf16 v[78:81], v[140:143], v[234:237], v[78:81]
	v_mfma_f32_16x16x32_bf16 v[74:77], v[148:151], v[234:237], v[74:77]
	v_mfma_f32_16x16x32_bf16 v[118:121], v[152:155], v[168:171], v[118:121]
	v_mfma_f32_16x16x32_bf16 v[114:117], v[160:163], v[168:171], v[114:117]
	v_mfma_f32_16x16x32_bf16 v[102:105], v[152:155], v[196:199], v[102:105]
	v_mfma_f32_16x16x32_bf16 v[98:101], v[160:163], v[196:199], v[98:101]
	v_mfma_f32_16x16x32_bf16 v[86:89], v[152:155], v[204:207], v[86:89]
	v_mfma_f32_16x16x32_bf16 v[82:85], v[160:163], v[204:207], v[82:85]
	v_mfma_f32_16x16x32_bf16 v[70:73], v[152:155], v[212:215], v[70:73]
	v_mfma_f32_16x16x32_bf16 v[66:69], v[160:163], v[212:215], v[66:69]
	v_mfma_f32_16x16x32_bf16 v[118:121], v[156:159], v[172:175], v[118:121]
	v_mfma_f32_16x16x32_bf16 v[114:117], v[164:167], v[172:175], v[114:117]
	v_mfma_f32_16x16x32_bf16 v[102:105], v[156:159], v[200:203], v[102:105]
	v_mfma_f32_16x16x32_bf16 v[98:101], v[164:167], v[200:203], v[98:101]
	v_mfma_f32_16x16x32_bf16 v[86:89], v[156:159], v[208:211], v[86:89]
	v_mfma_f32_16x16x32_bf16 v[82:85], v[164:167], v[208:211], v[82:85]
	v_mfma_f32_16x16x32_bf16 v[70:73], v[156:159], v[234:237], v[70:73]
	v_mfma_f32_16x16x32_bf16 v[66:69], v[164:167], v[234:237], v[66:69]
	s_barrier
; #define PG8_STAGE(bufoff, gbase, voff) do { _Pragma("unroll") for (int _i = 0; _i < 2; ++_i) \
;         __builtin_amdgcn_global_load_lds((const unsigned*)((const char*)(gbase) + (voff)[_i]), (LAS unsigned*)(lds + (bufoff) + ldsw + _i * 8192), 16, 0, 0); } while (0)
; #define PG8_LDA(dst, b, h) do { _Pragma("unroll") for (int m = 0; m < 4; ++m) _Pragma("unroll") for (int k = 0; k < 2; ++k) dst[m][k] = *(const LAS bf16x8*)(lds + PG8_SA(b, h) + aoff + m * 2048 + k * 1024); } while (0)
; #define PG8_MMA(ai, bj, At, Bt) do { __builtin_amdgcn_s_setprio(1); _Pragma("unroll") for (int m = 0; m < 4; ++m) _Pragma("unroll") for (int n = 0; n < 2; ++n) _Pragma("unroll") for (int k = 0; k < 2; ++k) \
;         acc[ai][bj][m][n] = __builtin_amdgcn_mfma_f32_16x16x32_bf16(Bt[n][k], At[m][k], acc[ai][bj][m][n], 0, 0, 0); __builtin_amdgcn_s_setprio(0); } while (0)
; #define PG8_WAIT_V(n) asm volatile("s_waitcnt vmcnt(" #n ")" ::: "memory")
; #define PG8_WAIT_L(n) asm volatile("s_waitcnt lgkmcnt(" #n ")" ::: "memory")
; #define PG8_BAR __builtin_amdgcn_s_barrier()
; #define PG8_SCHED __builtin_amdgcn_sched_barrier(0)
; template <class Epi, class Sched, bool ALIGN_EPI = true, bool SP2 = true>
; __device__ __forceinline__ void gemm_phase(LAS unsigned char* lds, const Gemm g, const Sched& S, const Epi& E) {
;     ...
;             PG8_LDA(At, 1, 1); PG8_STAGE(PG8_SB(1, 0), b3, voffB); PG8_STAGE(PG8_SB(1, 1), b3 + hstep, voffB); PG8_STAGE(PG8_SA(1, 0), a3, voffA);
;             PG8_WAIT_V(8); PG8_WAIT_L(0); PG8_BAR; PG8_MMA(1, 0, At, B0); PG8_MMA(1, 1, At, B1); PG8_BAR; PG8_SCHED;
;     ...
;         if constexpr (ALIGN_EPI) { if (wr == 0) PG8_BAR; }
	s_setprio 0
	s_add_i32 s16, s58, s26
	v_lshl_add_u64 v[176:177], v[176:177], 0, s[92:93]
	s_mov_b32 m0, s16
	ds_read_b128 v[168:171], v194 offset:49152
	ds_read_b128 v[172:175], v194 offset:50176
	ds_read_b128 v[196:199], v194 offset:51200
	ds_read_b128 v[200:203], v194 offset:52224
	ds_read_b128 v[204:207], v194 offset:53248
	ds_read_b128 v[208:211], v194 offset:54272
	ds_read_b128 v[212:215], v194 offset:55296
	ds_read_b128 v[234:237], v194 offset:56320
	global_load_lds_dwordx4 v[176:177], off
	s_add_i32 m0, s16, 0x2000
	s_add_u32 s16, s20, 0x160080
	v_lshl_add_u64 v[176:177], v[224:225], 0, s[92:93]
	s_addc_u32 s17, s21, 0
	s_add_i32 s20, s59, s26
	global_load_lds_dwordx4 v[176:177], off
	v_lshl_add_u64 v[176:177], s[16:17], 0, v[0:1]
	s_mov_b32 m0, s20
	s_nop 0
	global_load_lds_dwordx4 v[176:177], off
	v_lshl_add_u64 v[176:177], s[16:17], 0, v[130:131]
	s_add_i32 m0, s20, 0x2000
	s_nop 0
	global_load_lds_dwordx4 v[176:177], off
	v_lshl_add_u64 v[176:177], v[238:239], 0, s[92:93]
	s_mov_b32 m0, s31
	s_nop 0
	global_load_lds_dwordx4 v[176:177], off
	v_lshl_add_u64 v[176:177], v[240:241], 0, s[92:93]
	s_mov_b32 m0, s34
	s_nop 0
	global_load_lds_dwordx4 v[176:177], off
	s_waitcnt vmcnt(8)
	s_waitcnt lgkmcnt(0)
	s_setprio 1
	s_barrier
	v_mfma_f32_16x16x32_bf16 v[62:65], v[136:139], v[168:171], v[62:65]
	v_mfma_f32_16x16x32_bf16 v[58:61], v[144:147], v[168:171], v[58:61]
	v_mfma_f32_16x16x32_bf16 v[46:49], v[136:139], v[196:199], v[46:49]
	v_mfma_f32_16x16x32_bf16 v[42:45], v[144:147], v[196:199], v[42:45]
	v_mfma_f32_16x16x32_bf16 v[30:33], v[136:139], v[204:207], v[30:33]
	v_mfma_f32_16x16x32_bf16 v[26:29], v[144:147], v[204:207], v[26:29]
	v_mfma_f32_16x16x32_bf16 v[14:17], v[136:139], v[212:215], v[14:17]
	v_mfma_f32_16x16x32_bf16 v[10:13], v[144:147], v[212:215], v[10:13]
	v_mfma_f32_16x16x32_bf16 v[62:65], v[140:143], v[172:175], v[62:65]
	v_mfma_f32_16x16x32_bf16 v[58:61], v[148:151], v[172:175], v[58:61]
	v_mfma_f32_16x16x32_bf16 v[46:49], v[140:143], v[200:203], v[46:49]
	v_mfma_f32_16x16x32_bf16 v[42:45], v[148:151], v[200:203], v[42:45]
	v_mfma_f32_16x16x32_bf16 v[30:33], v[140:143], v[208:211], v[30:33]
	v_mfma_f32_16x16x32_bf16 v[26:29], v[148:151], v[208:211], v[26:29]
	v_mfma_f32_16x16x32_bf16 v[14:17], v[140:143], v[234:237], v[14:17]
	v_mfma_f32_16x16x32_bf16 v[10:13], v[148:151], v[234:237], v[10:13]
	v_mfma_f32_16x16x32_bf16 v[54:57], v[152:155], v[168:171], v[54:57]
	v_mfma_f32_16x16x32_bf16 v[50:53], v[160:163], v[168:171], v[50:53]
	v_mfma_f32_16x16x32_bf16 v[38:41], v[152:155], v[196:199], v[38:41]
	v_mfma_f32_16x16x32_bf16 v[34:37], v[160:163], v[196:199], v[34:37]
	v_mfma_f32_16x16x32_bf16 v[22:25], v[152:155], v[204:207], v[22:25]
	v_mfma_f32_16x16x32_bf16 v[18:21], v[160:163], v[204:207], v[18:21]
	v_mfma_f32_16x16x32_bf16 v[6:9], v[152:155], v[212:215], v[6:9]
	v_mfma_f32_16x16x32_bf16 v[2:5], v[160:163], v[212:215], v[2:5]
	v_mfma_f32_16x16x32_bf16 v[54:57], v[156:159], v[172:175], v[54:57]
	v_mfma_f32_16x16x32_bf16 v[50:53], v[164:167], v[172:175], v[50:53]
	v_mfma_f32_16x16x32_bf16 v[38:41], v[156:159], v[200:203], v[38:41]
	v_mfma_f32_16x16x32_bf16 v[34:37], v[164:167], v[200:203], v[34:37]
	v_mfma_f32_16x16x32_bf16 v[22:25], v[156:159], v[208:211], v[22:25]
	v_mfma_f32_16x16x32_bf16 v[18:21], v[164:167], v[208:211], v[18:21]
	v_mfma_f32_16x16x32_bf16 v[6:9], v[156:159], v[234:237], v[6:9]
	v_mfma_f32_16x16x32_bf16 v[2:5], v[164:167], v[234:237], v[2:5]
	s_barrier
	s_setprio 0
	s_add_i32 s74, s74, 2
	s_add_u32 s72, s72, 0x100
	s_addc_u32 s73, s73, 0
	s_cmpk_gt_u32 s74, 0x55
	s_mov_b64 s[16:17], s[18:19]
	s_cbranch_scc0 .LBB0_991
	s_and_b64 vcc, exec, s[12:13]
	s_cbranch_vccz .LBB0_994
	s_barrier
